# sample-step dilated attention re-written by hand: one task per (batch, dilation group) covering both heads and all 8 queries, keys read as 8 KB blocks of consecutive rows with nt loads, per-wave onlin
# speedup vs baseline: 1.0297x; 1.0297x over previous
.LBB0_419:
	s_and_b64 vcc, exec, s[0:1]
	s_cbranch_vccz .LBB0_1020
	s_add_i32 s0, s56, 0xf800
	s_and_b32 s1, s0, 0xffff
	s_mul_i32 s1, s1, 0xcccd
	s_lshr_b32 s44, s1, 19
	s_mul_i32 s1, s44, 10
	s_sub_i32 s0, s0, s1
	s_and_b32 s57, s0, 0xffff
	s_cmp_gt_u32 s57, 1
	s_mov_b64 s[0:1], -1
	s_cbranch_scc0 .LBB0_920
	s_cmp_lt_u32 s57, 6
	s_cbranch_scc0 .LBB0_768
	s_cmp_ge_u32 s57, 4
	s_cbranch_scc1 .Lst4_done
	v_readfirstlane_b32 s4, v192
	s_sub_u32 s0, s57, 1
	s_lshl_b32 s0, s0, 1
	s_lshr_b32 s4, s4, 6
	s_movk_i32 s1, 0x80
	s_lshl_b32 s1, s1, s0
	s_cmp_eq_u32 s0, 2
	s_cselect_b32 s6, s82, s84
	s_cselect_b32 s7, s83, s85
	s_mov_b32 s29, 0x9a40000
	s_cselect_b32 s29, 0x5a40000, s29
	s_add_u32 s30, s0, 17
	s_lshl_b32 s31, s44, s30
	s_add_u32 s6, s6, s31
	s_addc_u32 s7, s7, 0
	s_add_u32 s10, s36, s29
	s_addc_u32 s11, s37, 0
	s_add_u32 s10, s10, s31
	s_addc_u32 s11, s11, 0
	s_sub_u32 s10, s10, 0x2000
	s_subb_u32 s11, s11, 0
	s_lshl_b32 s18, 0x400, s0
	s_lshl_b32 s64, s18, 3
	s_lshl_b32 s28, s44, 3
	s_mul_i32 s30, s28, 0x600
	s_lshl_b32 s31, s0, 8
	s_add_u32 s30, s30, s31
	s_add_u32 s12, s38, 0x784da00
	s_addc_u32 s13, s39, 0
	s_add_u32 s12, s12, s30
	s_addc_u32 s13, s13, 0
	s_add_u32 s29, s28, 0x4000
	s_add_u32 s29, s29, s4
	s_mul_i32 s30, s29, 0x300
	s_lshl_b32 s31, s0, 7
	s_add_u32 s30, s30, s31
	s_add_u32 s14, s38, 0x988da00
	s_addc_u32 s15, s39, 0
	s_add_u32 s14, s14, s30
	s_addc_u32 s15, s15, 0
	s_mul_i32 s30, s29, 24
	s_lshl_b32 s31, s0, 2
	s_add_u32 s30, s30, s31
	s_add_u32 s22, s38, 0xa54da00
	s_addc_u32 s23, s39, 0
	s_add_u32 s22, s22, s30
	s_addc_u32 s23, s23, 0
	v_and_b32_e32 v228, 63, v192
	v_lshlrev_b32_e32 v136, 4, v228
	v_and_b32_e32 v232, 0x1f0, v136
	global_load_dwordx4 v[138:141], v232, s[12:13] offset:0
	s_add_u32 s12, s12, 0x600
	s_addc_u32 s13, s13, 0
	global_load_dwordx4 v[142:145], v232, s[12:13]
	s_add_u32 s12, s12, 0x600
	s_addc_u32 s13, s13, 0
	global_load_dwordx4 v[146:149], v232, s[12:13]
	s_add_u32 s12, s12, 0x600
	s_addc_u32 s13, s13, 0
	global_load_dwordx4 v[150:153], v232, s[12:13]
	s_add_u32 s12, s12, 0x600
	s_addc_u32 s13, s13, 0
	global_load_dwordx4 v[154:157], v232, s[12:13]
	s_add_u32 s12, s12, 0x600
	s_addc_u32 s13, s13, 0
	global_load_dwordx4 v[158:161], v232, s[12:13]
	s_add_u32 s12, s12, 0x600
	s_addc_u32 s13, s13, 0
	global_load_dwordx4 v[162:165], v232, s[12:13]
	s_add_u32 s12, s12, 0x600
	s_addc_u32 s13, s13, 0
	global_load_dwordx4 v[166:169], v232, s[12:13]
	s_mul_i32 s28, s4, s18
	s_lshl_b32 s30, s1, 10
	s_sub_u32 s28, s30, s28
	s_add_u32 s31, s28, 0x0
	s_cmp_ge_u32 s31, s30
	s_cselect_b32 s42, s10, s6
	s_cselect_b32 s43, s11, s7
	s_add_u32 s42, s42, s31
	s_addc_u32 s43, s43, 0
	global_load_dwordx4 v[0:3], v136, s[42:43] nt
	s_add_u32 s31, s28, 0x400
	s_cmp_ge_u32 s31, s30
	s_cselect_b32 s42, s10, s6
	s_cselect_b32 s43, s11, s7
	s_add_u32 s42, s42, s31
	s_addc_u32 s43, s43, 0
	global_load_dwordx4 v[4:7], v136, s[42:43] nt
	s_add_u32 s31, s28, 0x800
	s_cmp_ge_u32 s31, s30
	s_cselect_b32 s42, s10, s6
	s_cselect_b32 s43, s11, s7
	s_add_u32 s42, s42, s31
	s_addc_u32 s43, s43, 0
	global_load_dwordx4 v[8:11], v136, s[42:43] nt
	s_add_u32 s31, s28, 0xc00
	s_cmp_ge_u32 s31, s30
	s_cselect_b32 s42, s10, s6
	s_cselect_b32 s43, s11, s7
	s_add_u32 s42, s42, s31
	s_addc_u32 s43, s43, 0
	global_load_dwordx4 v[12:15], v136, s[42:43] nt
	s_add_u32 s31, s28, 0x1000
	s_cmp_ge_u32 s31, s30
	s_cselect_b32 s42, s10, s6
	s_cselect_b32 s43, s11, s7
	s_add_u32 s42, s42, s31
	s_addc_u32 s43, s43, 0
	global_load_dwordx4 v[16:19], v136, s[42:43] nt
	s_add_u32 s31, s28, 0x1400
	s_cmp_ge_u32 s31, s30
	s_cselect_b32 s42, s10, s6
	s_cselect_b32 s43, s11, s7
	s_add_u32 s42, s42, s31
	s_addc_u32 s43, s43, 0
	global_load_dwordx4 v[20:23], v136, s[42:43] nt
	s_add_u32 s31, s28, 0x1800
	s_cmp_ge_u32 s31, s30
	s_cselect_b32 s42, s10, s6
	s_cselect_b32 s43, s11, s7
	s_add_u32 s42, s42, s31
	s_addc_u32 s43, s43, 0
	global_load_dwordx4 v[24:27], v136, s[42:43] nt
	s_add_u32 s31, s28, 0x1c00
	s_cmp_ge_u32 s31, s30
	s_cselect_b32 s42, s10, s6
	s_cselect_b32 s43, s11, s7
	s_add_u32 s42, s42, s31
	s_addc_u32 s43, s43, 0
	global_load_dwordx4 v[28:31], v136, s[42:43] nt
	s_add_u32 s62, s6, s28
	s_addc_u32 s63, s7, 0
	s_sub_u32 s62, s62, s64
	s_subb_u32 s63, s63, 0
	s_add_u32 s42, s62, 0x1000
	s_addc_u32 s43, s63, 0
	global_load_dwordx4 v[32:35], v136, s[62:63] nt
	global_load_dwordx4 v[36:39], v136, s[62:63] offset:1024 nt
	global_load_dwordx4 v[40:43], v136, s[62:63] offset:2048 nt
	global_load_dwordx4 v[44:47], v136, s[62:63] offset:3072 nt
	global_load_dwordx4 v[48:51], v136, s[42:43] nt
	global_load_dwordx4 v[52:55], v136, s[42:43] offset:1024 nt
	global_load_dwordx4 v[56:59], v136, s[42:43] offset:2048 nt
	global_load_dwordx4 v[60:63], v136, s[42:43] offset:3072 nt
	s_sub_u32 s62, s62, s64
	s_subb_u32 s63, s63, 0
	s_add_u32 s42, s62, 0x1000
	s_addc_u32 s43, s63, 0
	global_load_dwordx4 v[64:67], v136, s[62:63] nt
	global_load_dwordx4 v[68:71], v136, s[62:63] offset:1024 nt
	global_load_dwordx4 v[72:75], v136, s[62:63] offset:2048 nt
	global_load_dwordx4 v[76:79], v136, s[62:63] offset:3072 nt
	global_load_dwordx4 v[80:83], v136, s[42:43] nt
	global_load_dwordx4 v[84:87], v136, s[42:43] offset:1024 nt
	global_load_dwordx4 v[88:91], v136, s[42:43] offset:2048 nt
	global_load_dwordx4 v[92:95], v136, s[42:43] offset:3072 nt
	s_sub_u32 s62, s62, s64
	s_subb_u32 s63, s63, 0
	s_add_u32 s42, s62, 0x1000
	s_addc_u32 s43, s63, 0
	global_load_dwordx4 v[96:99], v136, s[62:63] nt
	global_load_dwordx4 v[100:103], v136, s[62:63] offset:1024 nt
	global_load_dwordx4 v[104:107], v136, s[62:63] offset:2048 nt
	global_load_dwordx4 v[108:111], v136, s[62:63] offset:3072 nt
	global_load_dwordx4 v[112:115], v136, s[42:43] nt
	global_load_dwordx4 v[116:119], v136, s[42:43] offset:1024 nt
	global_load_dwordx4 v[120:123], v136, s[42:43] offset:2048 nt
	global_load_dwordx4 v[124:127], v136, s[42:43] offset:3072 nt
	v_mov_b32_e32 v208, 0xff7fffff
	v_mov_b32_e32 v219, 0
	v_mov_b32_e32 v172, 0
	v_mov_b32_e32 v173, 0
	v_mov_b32_e32 v174, 0
	v_mov_b32_e32 v175, 0
	v_mov_b32_e32 v209, 0xff7fffff
	v_mov_b32_e32 v220, 0
	v_mov_b32_e32 v176, 0
	v_mov_b32_e32 v177, 0
	v_mov_b32_e32 v178, 0
	v_mov_b32_e32 v179, 0
	v_mov_b32_e32 v210, 0xff7fffff
	v_mov_b32_e32 v221, 0
	v_mov_b32_e32 v180, 0
	v_mov_b32_e32 v181, 0
	v_mov_b32_e32 v182, 0
	v_mov_b32_e32 v183, 0
	v_mov_b32_e32 v212, 0xff7fffff
	v_mov_b32_e32 v222, 0
	v_mov_b32_e32 v184, 0
	v_mov_b32_e32 v185, 0
	v_mov_b32_e32 v186, 0
	v_mov_b32_e32 v187, 0
	v_mov_b32_e32 v214, 0xff7fffff
	v_mov_b32_e32 v223, 0
	v_mov_b32_e32 v188, 0
	v_mov_b32_e32 v189, 0
	v_mov_b32_e32 v190, 0
	v_mov_b32_e32 v191, 0
	v_mov_b32_e32 v216, 0xff7fffff
	v_mov_b32_e32 v224, 0
	v_mov_b32_e32 v196, 0
	v_mov_b32_e32 v197, 0
	v_mov_b32_e32 v198, 0
	v_mov_b32_e32 v199, 0
	v_mov_b32_e32 v217, 0xff7fffff
	v_mov_b32_e32 v225, 0
	v_mov_b32_e32 v200, 0
	v_mov_b32_e32 v201, 0
	v_mov_b32_e32 v202, 0
	v_mov_b32_e32 v203, 0
	v_mov_b32_e32 v218, 0xff7fffff
	v_mov_b32_e32 v226, 0
	v_mov_b32_e32 v204, 0
	v_mov_b32_e32 v205, 0
	v_mov_b32_e32 v206, 0
	v_mov_b32_e32 v207, 0
	s_waitcnt vmcnt(31)
	v_mul_f32_e32 v244, v138, v0
	v_fmac_f32_e32 v244, v139, v1
	v_fmac_f32_e32 v244, v140, v2
	v_fmac_f32_e32 v244, v141, v3
	s_waitcnt vmcnt(30)
	v_mul_f32_e32 v245, v142, v4
	v_fmac_f32_e32 v245, v143, v5
	v_fmac_f32_e32 v245, v144, v6
	v_fmac_f32_e32 v245, v145, v7
	s_waitcnt vmcnt(29)
	v_mul_f32_e32 v246, v146, v8
	v_fmac_f32_e32 v246, v147, v9
	v_fmac_f32_e32 v246, v148, v10
	v_fmac_f32_e32 v246, v149, v11
	v_add_f32_dpp v244, v244, v244 quad_perm:[1,0,3,2] row_mask:0xf bank_mask:0xf bound_ctrl:1
	v_add_f32_dpp v245, v245, v245 quad_perm:[1,0,3,2] row_mask:0xf bank_mask:0xf bound_ctrl:1
	v_add_f32_dpp v246, v246, v246 quad_perm:[1,0,3,2] row_mask:0xf bank_mask:0xf bound_ctrl:1
	v_add_f32_dpp v244, v244, v244 quad_perm:[2,3,0,1] row_mask:0xf bank_mask:0xf bound_ctrl:1
	v_add_f32_dpp v245, v245, v245 quad_perm:[2,3,0,1] row_mask:0xf bank_mask:0xf bound_ctrl:1
	v_add_f32_dpp v246, v246, v246 quad_perm:[2,3,0,1] row_mask:0xf bank_mask:0xf bound_ctrl:1
	v_add_f32_dpp v244, v244, v244 row_ror:4 row_mask:0xf bank_mask:0xf bound_ctrl:1
	v_add_f32_dpp v245, v245, v245 row_ror:4 row_mask:0xf bank_mask:0xf bound_ctrl:1
	v_add_f32_dpp v246, v246, v246 row_ror:4 row_mask:0xf bank_mask:0xf bound_ctrl:1
	v_add_f32_dpp v244, v244, v244 row_ror:8 row_mask:0xf bank_mask:0xf bound_ctrl:1
	v_add_f32_dpp v245, v245, v245 row_ror:8 row_mask:0xf bank_mask:0xf bound_ctrl:1
	v_add_f32_dpp v246, v246, v246 row_ror:8 row_mask:0xf bank_mask:0xf bound_ctrl:1
	v_mov_b32_e32 v133, v244
	v_mov_b32_e32 v134, v245
	v_mov_b32_e32 v135, v246
	v_permlane32_swap_b32_e32 v244, v133
	v_permlane32_swap_b32_e32 v245, v134
	v_permlane32_swap_b32_e32 v246, v135
	s_waitcnt vmcnt(28)
	v_mul_f32_e32 v247, v150, v12
	v_fmac_f32_e32 v247, v151, v13
	v_fmac_f32_e32 v247, v152, v14
	v_fmac_f32_e32 v247, v153, v15
	s_waitcnt vmcnt(27)
	v_mul_f32_e32 v248, v154, v16
	v_fmac_f32_e32 v248, v155, v17
	v_fmac_f32_e32 v248, v156, v18
	v_fmac_f32_e32 v248, v157, v19
	s_waitcnt vmcnt(26)
	v_mul_f32_e32 v249, v158, v20
	v_fmac_f32_e32 v249, v159, v21
	v_fmac_f32_e32 v249, v160, v22
	v_fmac_f32_e32 v249, v161, v23
	v_add_f32_dpp v247, v247, v247 quad_perm:[1,0,3,2] row_mask:0xf bank_mask:0xf bound_ctrl:1
	v_add_f32_dpp v248, v248, v248 quad_perm:[1,0,3,2] row_mask:0xf bank_mask:0xf bound_ctrl:1
	v_add_f32_dpp v249, v249, v249 quad_perm:[1,0,3,2] row_mask:0xf bank_mask:0xf bound_ctrl:1
	v_add_f32_dpp v247, v247, v247 quad_perm:[2,3,0,1] row_mask:0xf bank_mask:0xf bound_ctrl:1
	v_add_f32_dpp v248, v248, v248 quad_perm:[2,3,0,1] row_mask:0xf bank_mask:0xf bound_ctrl:1
	v_add_f32_dpp v249, v249, v249 quad_perm:[2,3,0,1] row_mask:0xf bank_mask:0xf bound_ctrl:1
	v_add_f32_dpp v247, v247, v247 row_ror:4 row_mask:0xf bank_mask:0xf bound_ctrl:1
	v_add_f32_dpp v248, v248, v248 row_ror:4 row_mask:0xf bank_mask:0xf bound_ctrl:1
	v_add_f32_dpp v249, v249, v249 row_ror:4 row_mask:0xf bank_mask:0xf bound_ctrl:1
	v_add_f32_dpp v247, v247, v247 row_ror:8 row_mask:0xf bank_mask:0xf bound_ctrl:1
	v_add_f32_dpp v248, v248, v248 row_ror:8 row_mask:0xf bank_mask:0xf bound_ctrl:1
	v_add_f32_dpp v249, v249, v249 row_ror:8 row_mask:0xf bank_mask:0xf bound_ctrl:1
	v_mov_b32_e32 v133, v247
	v_mov_b32_e32 v134, v248
	v_mov_b32_e32 v135, v249
	v_permlane32_swap_b32_e32 v247, v133
	v_permlane32_swap_b32_e32 v248, v134
	v_permlane32_swap_b32_e32 v249, v135
	s_waitcnt vmcnt(25)
	v_mul_f32_e32 v250, v162, v24
	v_fmac_f32_e32 v250, v163, v25
	v_fmac_f32_e32 v250, v164, v26
	v_fmac_f32_e32 v250, v165, v27
	s_waitcnt vmcnt(24)
	v_mul_f32_e32 v251, v166, v28
	v_fmac_f32_e32 v251, v167, v29
	v_fmac_f32_e32 v251, v168, v30
	v_fmac_f32_e32 v251, v169, v31
	s_waitcnt vmcnt(23)
	v_mul_f32_e32 v252, v138, v32
	v_fmac_f32_e32 v252, v139, v33
	v_fmac_f32_e32 v252, v140, v34
	v_fmac_f32_e32 v252, v141, v35
	v_add_f32_dpp v250, v250, v250 quad_perm:[1,0,3,2] row_mask:0xf bank_mask:0xf bound_ctrl:1
	v_add_f32_dpp v251, v251, v251 quad_perm:[1,0,3,2] row_mask:0xf bank_mask:0xf bound_ctrl:1
	v_add_f32_dpp v252, v252, v252 quad_perm:[1,0,3,2] row_mask:0xf bank_mask:0xf bound_ctrl:1
	v_add_f32_dpp v250, v250, v250 quad_perm:[2,3,0,1] row_mask:0xf bank_mask:0xf bound_ctrl:1
	v_add_f32_dpp v251, v251, v251 quad_perm:[2,3,0,1] row_mask:0xf bank_mask:0xf bound_ctrl:1
	v_add_f32_dpp v252, v252, v252 quad_perm:[2,3,0,1] row_mask:0xf bank_mask:0xf bound_ctrl:1
	v_add_f32_dpp v250, v250, v250 row_ror:4 row_mask:0xf bank_mask:0xf bound_ctrl:1
	v_add_f32_dpp v251, v251, v251 row_ror:4 row_mask:0xf bank_mask:0xf bound_ctrl:1
	v_add_f32_dpp v252, v252, v252 row_ror:4 row_mask:0xf bank_mask:0xf bound_ctrl:1
	v_add_f32_dpp v250, v250, v250 row_ror:8 row_mask:0xf bank_mask:0xf bound_ctrl:1
	v_add_f32_dpp v251, v251, v251 row_ror:8 row_mask:0xf bank_mask:0xf bound_ctrl:1
	v_add_f32_dpp v252, v252, v252 row_ror:8 row_mask:0xf bank_mask:0xf bound_ctrl:1
	v_mov_b32_e32 v133, v250
	v_mov_b32_e32 v134, v251
	v_mov_b32_e32 v135, v252
	v_permlane32_swap_b32_e32 v250, v133
	v_permlane32_swap_b32_e32 v251, v134
	v_permlane32_swap_b32_e32 v252, v135
	s_waitcnt vmcnt(22)
	v_mul_f32_e32 v253, v142, v36
	v_fmac_f32_e32 v253, v143, v37
	v_fmac_f32_e32 v253, v144, v38
	v_fmac_f32_e32 v253, v145, v39
	s_waitcnt vmcnt(21)
	v_mul_f32_e32 v254, v146, v40
	v_fmac_f32_e32 v254, v147, v41
	v_fmac_f32_e32 v254, v148, v42
	v_fmac_f32_e32 v254, v149, v43
	s_waitcnt vmcnt(20)
	v_mul_f32_e32 v128, v150, v44
	v_fmac_f32_e32 v128, v151, v45
	v_fmac_f32_e32 v128, v152, v46
	v_fmac_f32_e32 v128, v153, v47
	v_add_f32_dpp v253, v253, v253 quad_perm:[1,0,3,2] row_mask:0xf bank_mask:0xf bound_ctrl:1
	v_add_f32_dpp v254, v254, v254 quad_perm:[1,0,3,2] row_mask:0xf bank_mask:0xf bound_ctrl:1
	v_add_f32_dpp v128, v128, v128 quad_perm:[1,0,3,2] row_mask:0xf bank_mask:0xf bound_ctrl:1
	v_add_f32_dpp v253, v253, v253 quad_perm:[2,3,0,1] row_mask:0xf bank_mask:0xf bound_ctrl:1
	v_add_f32_dpp v254, v254, v254 quad_perm:[2,3,0,1] row_mask:0xf bank_mask:0xf bound_ctrl:1
	v_add_f32_dpp v128, v128, v128 quad_perm:[2,3,0,1] row_mask:0xf bank_mask:0xf bound_ctrl:1
	v_add_f32_dpp v253, v253, v253 row_ror:4 row_mask:0xf bank_mask:0xf bound_ctrl:1
	v_add_f32_dpp v254, v254, v254 row_ror:4 row_mask:0xf bank_mask:0xf bound_ctrl:1
	v_add_f32_dpp v128, v128, v128 row_ror:4 row_mask:0xf bank_mask:0xf bound_ctrl:1
	v_add_f32_dpp v253, v253, v253 row_ror:8 row_mask:0xf bank_mask:0xf bound_ctrl:1
	v_add_f32_dpp v254, v254, v254 row_ror:8 row_mask:0xf bank_mask:0xf bound_ctrl:1
	v_add_f32_dpp v128, v128, v128 row_ror:8 row_mask:0xf bank_mask:0xf bound_ctrl:1
	v_mov_b32_e32 v133, v253
	v_mov_b32_e32 v134, v254
	v_mov_b32_e32 v135, v128
	v_permlane32_swap_b32_e32 v253, v133
	v_permlane32_swap_b32_e32 v254, v134
	v_permlane32_swap_b32_e32 v128, v135
	s_waitcnt vmcnt(19)
	v_mul_f32_e32 v129, v154, v48
	v_fmac_f32_e32 v129, v155, v49
	v_fmac_f32_e32 v129, v156, v50
	v_fmac_f32_e32 v129, v157, v51
	s_waitcnt vmcnt(18)
	v_mul_f32_e32 v130, v158, v52
	v_fmac_f32_e32 v130, v159, v53
	v_fmac_f32_e32 v130, v160, v54
	v_fmac_f32_e32 v130, v161, v55
	s_waitcnt vmcnt(17)
	v_mul_f32_e32 v131, v162, v56
	v_fmac_f32_e32 v131, v163, v57
	v_fmac_f32_e32 v131, v164, v58
	v_fmac_f32_e32 v131, v165, v59
	v_add_f32_dpp v129, v129, v129 quad_perm:[1,0,3,2] row_mask:0xf bank_mask:0xf bound_ctrl:1
	v_add_f32_dpp v130, v130, v130 quad_perm:[1,0,3,2] row_mask:0xf bank_mask:0xf bound_ctrl:1
	v_add_f32_dpp v131, v131, v131 quad_perm:[1,0,3,2] row_mask:0xf bank_mask:0xf bound_ctrl:1
	v_add_f32_dpp v129, v129, v129 quad_perm:[2,3,0,1] row_mask:0xf bank_mask:0xf bound_ctrl:1
	v_add_f32_dpp v130, v130, v130 quad_perm:[2,3,0,1] row_mask:0xf bank_mask:0xf bound_ctrl:1
	v_add_f32_dpp v131, v131, v131 quad_perm:[2,3,0,1] row_mask:0xf bank_mask:0xf bound_ctrl:1
	v_add_f32_dpp v129, v129, v129 row_ror:4 row_mask:0xf bank_mask:0xf bound_ctrl:1
	v_add_f32_dpp v130, v130, v130 row_ror:4 row_mask:0xf bank_mask:0xf bound_ctrl:1
	v_add_f32_dpp v131, v131, v131 row_ror:4 row_mask:0xf bank_mask:0xf bound_ctrl:1
	v_add_f32_dpp v129, v129, v129 row_ror:8 row_mask:0xf bank_mask:0xf bound_ctrl:1
	v_add_f32_dpp v130, v130, v130 row_ror:8 row_mask:0xf bank_mask:0xf bound_ctrl:1
	v_add_f32_dpp v131, v131, v131 row_ror:8 row_mask:0xf bank_mask:0xf bound_ctrl:1
	v_mov_b32_e32 v133, v129
	v_mov_b32_e32 v134, v130
	v_mov_b32_e32 v135, v131
	v_permlane32_swap_b32_e32 v129, v133
	v_permlane32_swap_b32_e32 v130, v134
	v_permlane32_swap_b32_e32 v131, v135
	s_waitcnt vmcnt(16)
	v_mul_f32_e32 v132, v166, v60
	v_fmac_f32_e32 v132, v167, v61
	v_fmac_f32_e32 v132, v168, v62
	v_fmac_f32_e32 v132, v169, v63
	s_nop 1
	v_add_f32_dpp v132, v132, v132 quad_perm:[1,0,3,2] row_mask:0xf bank_mask:0xf bound_ctrl:1
	s_nop 1
	v_add_f32_dpp v132, v132, v132 quad_perm:[2,3,0,1] row_mask:0xf bank_mask:0xf bound_ctrl:1
	s_nop 1
	v_add_f32_dpp v132, v132, v132 row_ror:4 row_mask:0xf bank_mask:0xf bound_ctrl:1
	s_nop 1
	v_add_f32_dpp v132, v132, v132 row_ror:8 row_mask:0xf bank_mask:0xf bound_ctrl:1
	s_nop 1
	v_mov_b32_e32 v133, v132
	s_nop 1
	v_permlane32_swap_b32_e32 v132, v133
	v_max3_f32 v228, v244, v252, v208
	v_sub_f32_e32 v227, v208, v228
	v_sub_f32_e32 v244, v244, v228
	v_sub_f32_e32 v252, v252, v228
	v_mul_f32_e32 v227, 0x3fb8aa3b, v227
	v_mul_f32_e32 v244, 0x3fb8aa3b, v244
	v_mul_f32_e32 v252, 0x3fb8aa3b, v252
	v_exp_f32_e32 v227, v227
	v_exp_f32_e32 v244, v244
	v_exp_f32_e32 v252, v252
	v_mov_b32_e32 v208, v228
	v_fma_f32 v219, v219, v227, v244
	v_add_f32_e32 v219, v219, v252
	v_mul_f32_e32 v172, v172, v227
	v_mul_f32_e32 v173, v173, v227
	v_mul_f32_e32 v174, v174, v227
	v_mul_f32_e32 v175, v175, v227
	v_fmac_f32_e32 v172, v244, v0
	v_fmac_f32_e32 v173, v244, v1
	v_fmac_f32_e32 v174, v244, v2
	v_fmac_f32_e32 v175, v244, v3
	v_fmac_f32_e32 v172, v252, v32
	v_fmac_f32_e32 v173, v252, v33
	v_fmac_f32_e32 v174, v252, v34
	v_fmac_f32_e32 v175, v252, v35
	v_max3_f32 v228, v245, v253, v209
	v_sub_f32_e32 v227, v209, v228
	v_sub_f32_e32 v245, v245, v228
	v_sub_f32_e32 v253, v253, v228
	v_mul_f32_e32 v227, 0x3fb8aa3b, v227
	v_mul_f32_e32 v245, 0x3fb8aa3b, v245
	v_mul_f32_e32 v253, 0x3fb8aa3b, v253
	v_exp_f32_e32 v227, v227
	v_exp_f32_e32 v245, v245
	v_exp_f32_e32 v253, v253
	v_mov_b32_e32 v209, v228
	v_fma_f32 v220, v220, v227, v245
	v_add_f32_e32 v220, v220, v253
	v_mul_f32_e32 v176, v176, v227
	v_mul_f32_e32 v177, v177, v227
	v_mul_f32_e32 v178, v178, v227
	v_mul_f32_e32 v179, v179, v227
	v_fmac_f32_e32 v176, v245, v4
	v_fmac_f32_e32 v177, v245, v5
	v_fmac_f32_e32 v178, v245, v6
	v_fmac_f32_e32 v179, v245, v7
	v_fmac_f32_e32 v176, v253, v36
	v_fmac_f32_e32 v177, v253, v37
	v_fmac_f32_e32 v178, v253, v38
	v_fmac_f32_e32 v179, v253, v39
	v_max3_f32 v228, v246, v254, v210
	v_sub_f32_e32 v227, v210, v228
	v_sub_f32_e32 v246, v246, v228
	v_sub_f32_e32 v254, v254, v228
	v_mul_f32_e32 v227, 0x3fb8aa3b, v227
	v_mul_f32_e32 v246, 0x3fb8aa3b, v246
	v_mul_f32_e32 v254, 0x3fb8aa3b, v254
	v_exp_f32_e32 v227, v227
	v_exp_f32_e32 v246, v246
	v_exp_f32_e32 v254, v254
	v_mov_b32_e32 v210, v228
	v_fma_f32 v221, v221, v227, v246
	v_add_f32_e32 v221, v221, v254
	v_mul_f32_e32 v180, v180, v227
	v_mul_f32_e32 v181, v181, v227
	v_mul_f32_e32 v182, v182, v227
	v_mul_f32_e32 v183, v183, v227
	v_fmac_f32_e32 v180, v246, v8
	v_fmac_f32_e32 v181, v246, v9
	v_fmac_f32_e32 v182, v246, v10
	v_fmac_f32_e32 v183, v246, v11
	v_fmac_f32_e32 v180, v254, v40
	v_fmac_f32_e32 v181, v254, v41
	v_fmac_f32_e32 v182, v254, v42
	v_fmac_f32_e32 v183, v254, v43
	v_max3_f32 v228, v247, v128, v212
	v_sub_f32_e32 v227, v212, v228
	v_sub_f32_e32 v247, v247, v228
	v_sub_f32_e32 v128, v128, v228
	v_mul_f32_e32 v227, 0x3fb8aa3b, v227
	v_mul_f32_e32 v247, 0x3fb8aa3b, v247
	v_mul_f32_e32 v128, 0x3fb8aa3b, v128
	v_exp_f32_e32 v227, v227
	v_exp_f32_e32 v247, v247
	v_exp_f32_e32 v128, v128
	v_mov_b32_e32 v212, v228
	v_fma_f32 v222, v222, v227, v247
	v_add_f32_e32 v222, v222, v128
	v_mul_f32_e32 v184, v184, v227
	v_mul_f32_e32 v185, v185, v227
	v_mul_f32_e32 v186, v186, v227
	v_mul_f32_e32 v187, v187, v227
	v_fmac_f32_e32 v184, v247, v12
	v_fmac_f32_e32 v185, v247, v13
	v_fmac_f32_e32 v186, v247, v14
	v_fmac_f32_e32 v187, v247, v15
	v_fmac_f32_e32 v184, v128, v44
	v_fmac_f32_e32 v185, v128, v45
	v_fmac_f32_e32 v186, v128, v46
	v_fmac_f32_e32 v187, v128, v47
	v_max3_f32 v228, v248, v129, v214
	v_sub_f32_e32 v227, v214, v228
	v_sub_f32_e32 v248, v248, v228
	v_sub_f32_e32 v129, v129, v228
	v_mul_f32_e32 v227, 0x3fb8aa3b, v227
	v_mul_f32_e32 v248, 0x3fb8aa3b, v248
	v_mul_f32_e32 v129, 0x3fb8aa3b, v129
	v_exp_f32_e32 v227, v227
	v_exp_f32_e32 v248, v248
	v_exp_f32_e32 v129, v129
	v_mov_b32_e32 v214, v228
	v_fma_f32 v223, v223, v227, v248
	v_add_f32_e32 v223, v223, v129
	v_mul_f32_e32 v188, v188, v227
	v_mul_f32_e32 v189, v189, v227
	v_mul_f32_e32 v190, v190, v227
	v_mul_f32_e32 v191, v191, v227
	v_fmac_f32_e32 v188, v248, v16
	v_fmac_f32_e32 v189, v248, v17
	v_fmac_f32_e32 v190, v248, v18
	v_fmac_f32_e32 v191, v248, v19
	v_fmac_f32_e32 v188, v129, v48
	v_fmac_f32_e32 v189, v129, v49
	v_fmac_f32_e32 v190, v129, v50
	v_fmac_f32_e32 v191, v129, v51
	v_max3_f32 v228, v249, v130, v216
	v_sub_f32_e32 v227, v216, v228
	v_sub_f32_e32 v249, v249, v228
	v_sub_f32_e32 v130, v130, v228
	v_mul_f32_e32 v227, 0x3fb8aa3b, v227
	v_mul_f32_e32 v249, 0x3fb8aa3b, v249
	v_mul_f32_e32 v130, 0x3fb8aa3b, v130
	v_exp_f32_e32 v227, v227
	v_exp_f32_e32 v249, v249
	v_exp_f32_e32 v130, v130
	v_mov_b32_e32 v216, v228
	v_fma_f32 v224, v224, v227, v249
	v_add_f32_e32 v224, v224, v130
	v_mul_f32_e32 v196, v196, v227
	v_mul_f32_e32 v197, v197, v227
	v_mul_f32_e32 v198, v198, v227
	v_mul_f32_e32 v199, v199, v227
	v_fmac_f32_e32 v196, v249, v20
	v_fmac_f32_e32 v197, v249, v21
	v_fmac_f32_e32 v198, v249, v22
	v_fmac_f32_e32 v199, v249, v23
	v_fmac_f32_e32 v196, v130, v52
	v_fmac_f32_e32 v197, v130, v53
	v_fmac_f32_e32 v198, v130, v54
	v_fmac_f32_e32 v199, v130, v55
	v_max3_f32 v228, v250, v131, v217
	v_sub_f32_e32 v227, v217, v228
	v_sub_f32_e32 v250, v250, v228
	v_sub_f32_e32 v131, v131, v228
	v_mul_f32_e32 v227, 0x3fb8aa3b, v227
	v_mul_f32_e32 v250, 0x3fb8aa3b, v250
	v_mul_f32_e32 v131, 0x3fb8aa3b, v131
	v_exp_f32_e32 v227, v227
	v_exp_f32_e32 v250, v250
	v_exp_f32_e32 v131, v131
	v_mov_b32_e32 v217, v228
	v_fma_f32 v225, v225, v227, v250
	v_add_f32_e32 v225, v225, v131
	v_mul_f32_e32 v200, v200, v227
	v_mul_f32_e32 v201, v201, v227
	v_mul_f32_e32 v202, v202, v227
	v_mul_f32_e32 v203, v203, v227
	v_fmac_f32_e32 v200, v250, v24
	v_fmac_f32_e32 v201, v250, v25
	v_fmac_f32_e32 v202, v250, v26
	v_fmac_f32_e32 v203, v250, v27
	v_fmac_f32_e32 v200, v131, v56
	v_fmac_f32_e32 v201, v131, v57
	v_fmac_f32_e32 v202, v131, v58
	v_fmac_f32_e32 v203, v131, v59
	v_max3_f32 v228, v251, v132, v218
	v_sub_f32_e32 v227, v218, v228
	v_sub_f32_e32 v251, v251, v228
	v_sub_f32_e32 v132, v132, v228
	v_mul_f32_e32 v227, 0x3fb8aa3b, v227
	v_mul_f32_e32 v251, 0x3fb8aa3b, v251
	v_mul_f32_e32 v132, 0x3fb8aa3b, v132
	v_exp_f32_e32 v227, v227
	v_exp_f32_e32 v251, v251
	v_exp_f32_e32 v132, v132
	v_mov_b32_e32 v218, v228
	v_fma_f32 v226, v226, v227, v251
	v_add_f32_e32 v226, v226, v132
	v_mul_f32_e32 v204, v204, v227
	v_mul_f32_e32 v205, v205, v227
	v_mul_f32_e32 v206, v206, v227
	v_mul_f32_e32 v207, v207, v227
	v_fmac_f32_e32 v204, v251, v28
	v_fmac_f32_e32 v205, v251, v29
	v_fmac_f32_e32 v206, v251, v30
	v_fmac_f32_e32 v207, v251, v31
	v_fmac_f32_e32 v204, v132, v60
	v_fmac_f32_e32 v205, v132, v61
	v_fmac_f32_e32 v206, v132, v62
	v_fmac_f32_e32 v207, v132, v63
	s_sub_u32 s62, s62, s64
	s_subb_u32 s63, s63, 0
	s_add_u32 s42, s62, 0x1000
	s_addc_u32 s43, s63, 0
	global_load_dwordx4 v[0:3], v136, s[62:63] nt
	global_load_dwordx4 v[4:7], v136, s[62:63] offset:1024 nt
	global_load_dwordx4 v[8:11], v136, s[62:63] offset:2048 nt
	global_load_dwordx4 v[12:15], v136, s[62:63] offset:3072 nt
	global_load_dwordx4 v[16:19], v136, s[42:43] nt
	global_load_dwordx4 v[20:23], v136, s[42:43] offset:1024 nt
	global_load_dwordx4 v[24:27], v136, s[42:43] offset:2048 nt
	global_load_dwordx4 v[28:31], v136, s[42:43] offset:3072 nt
	s_sub_u32 s62, s62, s64
	s_subb_u32 s63, s63, 0
	s_add_u32 s42, s62, 0x1000
	s_addc_u32 s43, s63, 0
	global_load_dwordx4 v[32:35], v136, s[62:63] nt
	global_load_dwordx4 v[36:39], v136, s[62:63] offset:1024 nt
	global_load_dwordx4 v[40:43], v136, s[62:63] offset:2048 nt
	global_load_dwordx4 v[44:47], v136, s[62:63] offset:3072 nt
	global_load_dwordx4 v[48:51], v136, s[42:43] nt
	global_load_dwordx4 v[52:55], v136, s[42:43] offset:1024 nt
	global_load_dwordx4 v[56:59], v136, s[42:43] offset:2048 nt
	global_load_dwordx4 v[60:63], v136, s[42:43] offset:3072 nt
	s_waitcnt vmcnt(31)
	v_mul_f32_e32 v244, v138, v64
	v_fmac_f32_e32 v244, v139, v65
	v_fmac_f32_e32 v244, v140, v66
	v_fmac_f32_e32 v244, v141, v67
	s_waitcnt vmcnt(30)
	v_mul_f32_e32 v245, v142, v68
	v_fmac_f32_e32 v245, v143, v69
	v_fmac_f32_e32 v245, v144, v70
	v_fmac_f32_e32 v245, v145, v71
	s_waitcnt vmcnt(29)
	v_mul_f32_e32 v246, v146, v72
	v_fmac_f32_e32 v246, v147, v73
	v_fmac_f32_e32 v246, v148, v74
	v_fmac_f32_e32 v246, v149, v75
	v_add_f32_dpp v244, v244, v244 quad_perm:[1,0,3,2] row_mask:0xf bank_mask:0xf bound_ctrl:1
	v_add_f32_dpp v245, v245, v245 quad_perm:[1,0,3,2] row_mask:0xf bank_mask:0xf bound_ctrl:1
	v_add_f32_dpp v246, v246, v246 quad_perm:[1,0,3,2] row_mask:0xf bank_mask:0xf bound_ctrl:1
	v_add_f32_dpp v244, v244, v244 quad_perm:[2,3,0,1] row_mask:0xf bank_mask:0xf bound_ctrl:1
	v_add_f32_dpp v245, v245, v245 quad_perm:[2,3,0,1] row_mask:0xf bank_mask:0xf bound_ctrl:1
	v_add_f32_dpp v246, v246, v246 quad_perm:[2,3,0,1] row_mask:0xf bank_mask:0xf bound_ctrl:1
	v_add_f32_dpp v244, v244, v244 row_ror:4 row_mask:0xf bank_mask:0xf bound_ctrl:1
	v_add_f32_dpp v245, v245, v245 row_ror:4 row_mask:0xf bank_mask:0xf bound_ctrl:1
	v_add_f32_dpp v246, v246, v246 row_ror:4 row_mask:0xf bank_mask:0xf bound_ctrl:1
	v_add_f32_dpp v244, v244, v244 row_ror:8 row_mask:0xf bank_mask:0xf bound_ctrl:1
	v_add_f32_dpp v245, v245, v245 row_ror:8 row_mask:0xf bank_mask:0xf bound_ctrl:1
	v_add_f32_dpp v246, v246, v246 row_ror:8 row_mask:0xf bank_mask:0xf bound_ctrl:1
	v_mov_b32_e32 v133, v244
	v_mov_b32_e32 v134, v245
	v_mov_b32_e32 v135, v246
	v_permlane32_swap_b32_e32 v244, v133
	v_permlane32_swap_b32_e32 v245, v134
	v_permlane32_swap_b32_e32 v246, v135
	s_waitcnt vmcnt(28)
	v_mul_f32_e32 v247, v150, v76
	v_fmac_f32_e32 v247, v151, v77
	v_fmac_f32_e32 v247, v152, v78
	v_fmac_f32_e32 v247, v153, v79
	s_waitcnt vmcnt(27)
	v_mul_f32_e32 v248, v154, v80
	v_fmac_f32_e32 v248, v155, v81
	v_fmac_f32_e32 v248, v156, v82
	v_fmac_f32_e32 v248, v157, v83
	s_waitcnt vmcnt(26)
	v_mul_f32_e32 v249, v158, v84
	v_fmac_f32_e32 v249, v159, v85
	v_fmac_f32_e32 v249, v160, v86
	v_fmac_f32_e32 v249, v161, v87
	v_add_f32_dpp v247, v247, v247 quad_perm:[1,0,3,2] row_mask:0xf bank_mask:0xf bound_ctrl:1
	v_add_f32_dpp v248, v248, v248 quad_perm:[1,0,3,2] row_mask:0xf bank_mask:0xf bound_ctrl:1
	v_add_f32_dpp v249, v249, v249 quad_perm:[1,0,3,2] row_mask:0xf bank_mask:0xf bound_ctrl:1
	v_add_f32_dpp v247, v247, v247 quad_perm:[2,3,0,1] row_mask:0xf bank_mask:0xf bound_ctrl:1
	v_add_f32_dpp v248, v248, v248 quad_perm:[2,3,0,1] row_mask:0xf bank_mask:0xf bound_ctrl:1
	v_add_f32_dpp v249, v249, v249 quad_perm:[2,3,0,1] row_mask:0xf bank_mask:0xf bound_ctrl:1
	v_add_f32_dpp v247, v247, v247 row_ror:4 row_mask:0xf bank_mask:0xf bound_ctrl:1
	v_add_f32_dpp v248, v248, v248 row_ror:4 row_mask:0xf bank_mask:0xf bound_ctrl:1
	v_add_f32_dpp v249, v249, v249 row_ror:4 row_mask:0xf bank_mask:0xf bound_ctrl:1
	v_add_f32_dpp v247, v247, v247 row_ror:8 row_mask:0xf bank_mask:0xf bound_ctrl:1
	v_add_f32_dpp v248, v248, v248 row_ror:8 row_mask:0xf bank_mask:0xf bound_ctrl:1
	v_add_f32_dpp v249, v249, v249 row_ror:8 row_mask:0xf bank_mask:0xf bound_ctrl:1
	v_mov_b32_e32 v133, v247
	v_mov_b32_e32 v134, v248
	v_mov_b32_e32 v135, v249
	v_permlane32_swap_b32_e32 v247, v133
	v_permlane32_swap_b32_e32 v248, v134
	v_permlane32_swap_b32_e32 v249, v135
	s_waitcnt vmcnt(25)
	v_mul_f32_e32 v250, v162, v88
	v_fmac_f32_e32 v250, v163, v89
	v_fmac_f32_e32 v250, v164, v90
	v_fmac_f32_e32 v250, v165, v91
	s_waitcnt vmcnt(24)
	v_mul_f32_e32 v251, v166, v92
	v_fmac_f32_e32 v251, v167, v93
	v_fmac_f32_e32 v251, v168, v94
	v_fmac_f32_e32 v251, v169, v95
	s_waitcnt vmcnt(23)
	v_mul_f32_e32 v252, v138, v96
	v_fmac_f32_e32 v252, v139, v97
	v_fmac_f32_e32 v252, v140, v98
	v_fmac_f32_e32 v252, v141, v99
	v_add_f32_dpp v250, v250, v250 quad_perm:[1,0,3,2] row_mask:0xf bank_mask:0xf bound_ctrl:1
	v_add_f32_dpp v251, v251, v251 quad_perm:[1,0,3,2] row_mask:0xf bank_mask:0xf bound_ctrl:1
	v_add_f32_dpp v252, v252, v252 quad_perm:[1,0,3,2] row_mask:0xf bank_mask:0xf bound_ctrl:1
	v_add_f32_dpp v250, v250, v250 quad_perm:[2,3,0,1] row_mask:0xf bank_mask:0xf bound_ctrl:1
	v_add_f32_dpp v251, v251, v251 quad_perm:[2,3,0,1] row_mask:0xf bank_mask:0xf bound_ctrl:1
	v_add_f32_dpp v252, v252, v252 quad_perm:[2,3,0,1] row_mask:0xf bank_mask:0xf bound_ctrl:1
	v_add_f32_dpp v250, v250, v250 row_ror:4 row_mask:0xf bank_mask:0xf bound_ctrl:1
	v_add_f32_dpp v251, v251, v251 row_ror:4 row_mask:0xf bank_mask:0xf bound_ctrl:1
	v_add_f32_dpp v252, v252, v252 row_ror:4 row_mask:0xf bank_mask:0xf bound_ctrl:1
	v_add_f32_dpp v250, v250, v250 row_ror:8 row_mask:0xf bank_mask:0xf bound_ctrl:1
	v_add_f32_dpp v251, v251, v251 row_ror:8 row_mask:0xf bank_mask:0xf bound_ctrl:1
	v_add_f32_dpp v252, v252, v252 row_ror:8 row_mask:0xf bank_mask:0xf bound_ctrl:1
	v_mov_b32_e32 v133, v250
	v_mov_b32_e32 v134, v251
	v_mov_b32_e32 v135, v252
	v_permlane32_swap_b32_e32 v250, v133
	v_permlane32_swap_b32_e32 v251, v134
	v_permlane32_swap_b32_e32 v252, v135
	s_waitcnt vmcnt(22)
	v_mul_f32_e32 v253, v142, v100
	v_fmac_f32_e32 v253, v143, v101
	v_fmac_f32_e32 v253, v144, v102
	v_fmac_f32_e32 v253, v145, v103
	s_waitcnt vmcnt(21)
	v_mul_f32_e32 v254, v146, v104
	v_fmac_f32_e32 v254, v147, v105
	v_fmac_f32_e32 v254, v148, v106
	v_fmac_f32_e32 v254, v149, v107
	s_waitcnt vmcnt(20)
	v_mul_f32_e32 v128, v150, v108
	v_fmac_f32_e32 v128, v151, v109
	v_fmac_f32_e32 v128, v152, v110
	v_fmac_f32_e32 v128, v153, v111
	v_add_f32_dpp v253, v253, v253 quad_perm:[1,0,3,2] row_mask:0xf bank_mask:0xf bound_ctrl:1
	v_add_f32_dpp v254, v254, v254 quad_perm:[1,0,3,2] row_mask:0xf bank_mask:0xf bound_ctrl:1
	v_add_f32_dpp v128, v128, v128 quad_perm:[1,0,3,2] row_mask:0xf bank_mask:0xf bound_ctrl:1
	v_add_f32_dpp v253, v253, v253 quad_perm:[2,3,0,1] row_mask:0xf bank_mask:0xf bound_ctrl:1
	v_add_f32_dpp v254, v254, v254 quad_perm:[2,3,0,1] row_mask:0xf bank_mask:0xf bound_ctrl:1
	v_add_f32_dpp v128, v128, v128 quad_perm:[2,3,0,1] row_mask:0xf bank_mask:0xf bound_ctrl:1
	v_add_f32_dpp v253, v253, v253 row_ror:4 row_mask:0xf bank_mask:0xf bound_ctrl:1
	v_add_f32_dpp v254, v254, v254 row_ror:4 row_mask:0xf bank_mask:0xf bound_ctrl:1
	v_add_f32_dpp v128, v128, v128 row_ror:4 row_mask:0xf bank_mask:0xf bound_ctrl:1
	v_add_f32_dpp v253, v253, v253 row_ror:8 row_mask:0xf bank_mask:0xf bound_ctrl:1
	v_add_f32_dpp v254, v254, v254 row_ror:8 row_mask:0xf bank_mask:0xf bound_ctrl:1
	v_add_f32_dpp v128, v128, v128 row_ror:8 row_mask:0xf bank_mask:0xf bound_ctrl:1
	v_mov_b32_e32 v133, v253
	v_mov_b32_e32 v134, v254
	v_mov_b32_e32 v135, v128
	v_permlane32_swap_b32_e32 v253, v133
	v_permlane32_swap_b32_e32 v254, v134
	v_permlane32_swap_b32_e32 v128, v135
	s_waitcnt vmcnt(19)
	v_mul_f32_e32 v129, v154, v112
	v_fmac_f32_e32 v129, v155, v113
	v_fmac_f32_e32 v129, v156, v114
	v_fmac_f32_e32 v129, v157, v115
	s_waitcnt vmcnt(18)
	v_mul_f32_e32 v130, v158, v116
	v_fmac_f32_e32 v130, v159, v117
	v_fmac_f32_e32 v130, v160, v118
	v_fmac_f32_e32 v130, v161, v119
	s_waitcnt vmcnt(17)
	v_mul_f32_e32 v131, v162, v120
	v_fmac_f32_e32 v131, v163, v121
	v_fmac_f32_e32 v131, v164, v122
	v_fmac_f32_e32 v131, v165, v123
	v_add_f32_dpp v129, v129, v129 quad_perm:[1,0,3,2] row_mask:0xf bank_mask:0xf bound_ctrl:1
	v_add_f32_dpp v130, v130, v130 quad_perm:[1,0,3,2] row_mask:0xf bank_mask:0xf bound_ctrl:1
	v_add_f32_dpp v131, v131, v131 quad_perm:[1,0,3,2] row_mask:0xf bank_mask:0xf bound_ctrl:1
	v_add_f32_dpp v129, v129, v129 quad_perm:[2,3,0,1] row_mask:0xf bank_mask:0xf bound_ctrl:1
	v_add_f32_dpp v130, v130, v130 quad_perm:[2,3,0,1] row_mask:0xf bank_mask:0xf bound_ctrl:1
	v_add_f32_dpp v131, v131, v131 quad_perm:[2,3,0,1] row_mask:0xf bank_mask:0xf bound_ctrl:1
	v_add_f32_dpp v129, v129, v129 row_ror:4 row_mask:0xf bank_mask:0xf bound_ctrl:1
	v_add_f32_dpp v130, v130, v130 row_ror:4 row_mask:0xf bank_mask:0xf bound_ctrl:1
	v_add_f32_dpp v131, v131, v131 row_ror:4 row_mask:0xf bank_mask:0xf bound_ctrl:1
	v_add_f32_dpp v129, v129, v129 row_ror:8 row_mask:0xf bank_mask:0xf bound_ctrl:1
	v_add_f32_dpp v130, v130, v130 row_ror:8 row_mask:0xf bank_mask:0xf bound_ctrl:1
	v_add_f32_dpp v131, v131, v131 row_ror:8 row_mask:0xf bank_mask:0xf bound_ctrl:1
	v_mov_b32_e32 v133, v129
	v_mov_b32_e32 v134, v130
	v_mov_b32_e32 v135, v131
	v_permlane32_swap_b32_e32 v129, v133
	v_permlane32_swap_b32_e32 v130, v134
	v_permlane32_swap_b32_e32 v131, v135
	s_waitcnt vmcnt(16)
	v_mul_f32_e32 v132, v166, v124
	v_fmac_f32_e32 v132, v167, v125
	v_fmac_f32_e32 v132, v168, v126
	v_fmac_f32_e32 v132, v169, v127
	s_nop 1
	v_add_f32_dpp v132, v132, v132 quad_perm:[1,0,3,2] row_mask:0xf bank_mask:0xf bound_ctrl:1
	s_nop 1
	v_add_f32_dpp v132, v132, v132 quad_perm:[2,3,0,1] row_mask:0xf bank_mask:0xf bound_ctrl:1
	s_nop 1
	v_add_f32_dpp v132, v132, v132 row_ror:4 row_mask:0xf bank_mask:0xf bound_ctrl:1
	s_nop 1
	v_add_f32_dpp v132, v132, v132 row_ror:8 row_mask:0xf bank_mask:0xf bound_ctrl:1
	s_nop 1
	v_mov_b32_e32 v133, v132
	s_nop 1
	v_permlane32_swap_b32_e32 v132, v133
	v_max3_f32 v228, v244, v252, v208
	v_sub_f32_e32 v227, v208, v228
	v_sub_f32_e32 v244, v244, v228
	v_sub_f32_e32 v252, v252, v228
	v_mul_f32_e32 v227, 0x3fb8aa3b, v227
	v_mul_f32_e32 v244, 0x3fb8aa3b, v244
	v_mul_f32_e32 v252, 0x3fb8aa3b, v252
	v_exp_f32_e32 v227, v227
	v_exp_f32_e32 v244, v244
	v_exp_f32_e32 v252, v252
	v_mov_b32_e32 v208, v228
	v_fma_f32 v219, v219, v227, v244
	v_add_f32_e32 v219, v219, v252
	v_mul_f32_e32 v172, v172, v227
	v_mul_f32_e32 v173, v173, v227
	v_mul_f32_e32 v174, v174, v227
	v_mul_f32_e32 v175, v175, v227
	v_fmac_f32_e32 v172, v244, v64
	v_fmac_f32_e32 v173, v244, v65
	v_fmac_f32_e32 v174, v244, v66
	v_fmac_f32_e32 v175, v244, v67
	v_fmac_f32_e32 v172, v252, v96
	v_fmac_f32_e32 v173, v252, v97
	v_fmac_f32_e32 v174, v252, v98
	v_fmac_f32_e32 v175, v252, v99
	v_max3_f32 v228, v245, v253, v209
	v_sub_f32_e32 v227, v209, v228
	v_sub_f32_e32 v245, v245, v228
	v_sub_f32_e32 v253, v253, v228
	v_mul_f32_e32 v227, 0x3fb8aa3b, v227
	v_mul_f32_e32 v245, 0x3fb8aa3b, v245
	v_mul_f32_e32 v253, 0x3fb8aa3b, v253
	v_exp_f32_e32 v227, v227
	v_exp_f32_e32 v245, v245
	v_exp_f32_e32 v253, v253
	v_mov_b32_e32 v209, v228
	v_fma_f32 v220, v220, v227, v245
	v_add_f32_e32 v220, v220, v253
	v_mul_f32_e32 v176, v176, v227
	v_mul_f32_e32 v177, v177, v227
	v_mul_f32_e32 v178, v178, v227
	v_mul_f32_e32 v179, v179, v227
	v_fmac_f32_e32 v176, v245, v68
	v_fmac_f32_e32 v177, v245, v69
	v_fmac_f32_e32 v178, v245, v70
	v_fmac_f32_e32 v179, v245, v71
	v_fmac_f32_e32 v176, v253, v100
	v_fmac_f32_e32 v177, v253, v101
	v_fmac_f32_e32 v178, v253, v102
	v_fmac_f32_e32 v179, v253, v103
	v_max3_f32 v228, v246, v254, v210
	v_sub_f32_e32 v227, v210, v228
	v_sub_f32_e32 v246, v246, v228
	v_sub_f32_e32 v254, v254, v228
	v_mul_f32_e32 v227, 0x3fb8aa3b, v227
	v_mul_f32_e32 v246, 0x3fb8aa3b, v246
	v_mul_f32_e32 v254, 0x3fb8aa3b, v254
	v_exp_f32_e32 v227, v227
	v_exp_f32_e32 v246, v246
	v_exp_f32_e32 v254, v254
	v_mov_b32_e32 v210, v228
	v_fma_f32 v221, v221, v227, v246
	v_add_f32_e32 v221, v221, v254
	v_mul_f32_e32 v180, v180, v227
	v_mul_f32_e32 v181, v181, v227
	v_mul_f32_e32 v182, v182, v227
	v_mul_f32_e32 v183, v183, v227
	v_fmac_f32_e32 v180, v246, v72
	v_fmac_f32_e32 v181, v246, v73
	v_fmac_f32_e32 v182, v246, v74
	v_fmac_f32_e32 v183, v246, v75
	v_fmac_f32_e32 v180, v254, v104
	v_fmac_f32_e32 v181, v254, v105
	v_fmac_f32_e32 v182, v254, v106
	v_fmac_f32_e32 v183, v254, v107
	v_max3_f32 v228, v247, v128, v212
	v_sub_f32_e32 v227, v212, v228
	v_sub_f32_e32 v247, v247, v228
	v_sub_f32_e32 v128, v128, v228
	v_mul_f32_e32 v227, 0x3fb8aa3b, v227
	v_mul_f32_e32 v247, 0x3fb8aa3b, v247
	v_mul_f32_e32 v128, 0x3fb8aa3b, v128
	v_exp_f32_e32 v227, v227
	v_exp_f32_e32 v247, v247
	v_exp_f32_e32 v128, v128
	v_mov_b32_e32 v212, v228
	v_fma_f32 v222, v222, v227, v247
	v_add_f32_e32 v222, v222, v128
	v_mul_f32_e32 v184, v184, v227
	v_mul_f32_e32 v185, v185, v227
	v_mul_f32_e32 v186, v186, v227
	v_mul_f32_e32 v187, v187, v227
	v_fmac_f32_e32 v184, v247, v76
	v_fmac_f32_e32 v185, v247, v77
	v_fmac_f32_e32 v186, v247, v78
	v_fmac_f32_e32 v187, v247, v79
	v_fmac_f32_e32 v184, v128, v108
	v_fmac_f32_e32 v185, v128, v109
	v_fmac_f32_e32 v186, v128, v110
	v_fmac_f32_e32 v187, v128, v111
	v_max3_f32 v228, v248, v129, v214
	v_sub_f32_e32 v227, v214, v228
	v_sub_f32_e32 v248, v248, v228
	v_sub_f32_e32 v129, v129, v228
	v_mul_f32_e32 v227, 0x3fb8aa3b, v227
	v_mul_f32_e32 v248, 0x3fb8aa3b, v248
	v_mul_f32_e32 v129, 0x3fb8aa3b, v129
	v_exp_f32_e32 v227, v227
	v_exp_f32_e32 v248, v248
	v_exp_f32_e32 v129, v129
	v_mov_b32_e32 v214, v228
	v_fma_f32 v223, v223, v227, v248
	v_add_f32_e32 v223, v223, v129
	v_mul_f32_e32 v188, v188, v227
	v_mul_f32_e32 v189, v189, v227
	v_mul_f32_e32 v190, v190, v227
	v_mul_f32_e32 v191, v191, v227
	v_fmac_f32_e32 v188, v248, v80
	v_fmac_f32_e32 v189, v248, v81
	v_fmac_f32_e32 v190, v248, v82
	v_fmac_f32_e32 v191, v248, v83
	v_fmac_f32_e32 v188, v129, v112
	v_fmac_f32_e32 v189, v129, v113
	v_fmac_f32_e32 v190, v129, v114
	v_fmac_f32_e32 v191, v129, v115
	v_max3_f32 v228, v249, v130, v216
	v_sub_f32_e32 v227, v216, v228
	v_sub_f32_e32 v249, v249, v228
	v_sub_f32_e32 v130, v130, v228
	v_mul_f32_e32 v227, 0x3fb8aa3b, v227
	v_mul_f32_e32 v249, 0x3fb8aa3b, v249
	v_mul_f32_e32 v130, 0x3fb8aa3b, v130
	v_exp_f32_e32 v227, v227
	v_exp_f32_e32 v249, v249
	v_exp_f32_e32 v130, v130
	v_mov_b32_e32 v216, v228
	v_fma_f32 v224, v224, v227, v249
	v_add_f32_e32 v224, v224, v130
	v_mul_f32_e32 v196, v196, v227
	v_mul_f32_e32 v197, v197, v227
	v_mul_f32_e32 v198, v198, v227
	v_mul_f32_e32 v199, v199, v227
	v_fmac_f32_e32 v196, v249, v84
	v_fmac_f32_e32 v197, v249, v85
	v_fmac_f32_e32 v198, v249, v86
	v_fmac_f32_e32 v199, v249, v87
	v_fmac_f32_e32 v196, v130, v116
	v_fmac_f32_e32 v197, v130, v117
	v_fmac_f32_e32 v198, v130, v118
	v_fmac_f32_e32 v199, v130, v119
	v_max3_f32 v228, v250, v131, v217
	v_sub_f32_e32 v227, v217, v228
	v_sub_f32_e32 v250, v250, v228
	v_sub_f32_e32 v131, v131, v228
	v_mul_f32_e32 v227, 0x3fb8aa3b, v227
	v_mul_f32_e32 v250, 0x3fb8aa3b, v250
	v_mul_f32_e32 v131, 0x3fb8aa3b, v131
	v_exp_f32_e32 v227, v227
	v_exp_f32_e32 v250, v250
	v_exp_f32_e32 v131, v131
	v_mov_b32_e32 v217, v228
	v_fma_f32 v225, v225, v227, v250
	v_add_f32_e32 v225, v225, v131
	v_mul_f32_e32 v200, v200, v227
	v_mul_f32_e32 v201, v201, v227
	v_mul_f32_e32 v202, v202, v227
	v_mul_f32_e32 v203, v203, v227
	v_fmac_f32_e32 v200, v250, v88
	v_fmac_f32_e32 v201, v250, v89
	v_fmac_f32_e32 v202, v250, v90
	v_fmac_f32_e32 v203, v250, v91
	v_fmac_f32_e32 v200, v131, v120
	v_fmac_f32_e32 v201, v131, v121
	v_fmac_f32_e32 v202, v131, v122
	v_fmac_f32_e32 v203, v131, v123
	v_max3_f32 v228, v251, v132, v218
	v_sub_f32_e32 v227, v218, v228
	v_sub_f32_e32 v251, v251, v228
	v_sub_f32_e32 v132, v132, v228
	v_mul_f32_e32 v227, 0x3fb8aa3b, v227
	v_mul_f32_e32 v251, 0x3fb8aa3b, v251
	v_mul_f32_e32 v132, 0x3fb8aa3b, v132
	v_exp_f32_e32 v227, v227
	v_exp_f32_e32 v251, v251
	v_exp_f32_e32 v132, v132
	v_mov_b32_e32 v218, v228
	v_fma_f32 v226, v226, v227, v251
	v_add_f32_e32 v226, v226, v132
	v_mul_f32_e32 v204, v204, v227
	v_mul_f32_e32 v205, v205, v227
	v_mul_f32_e32 v206, v206, v227
	v_mul_f32_e32 v207, v207, v227
	v_fmac_f32_e32 v204, v251, v92
	v_fmac_f32_e32 v205, v251, v93
	v_fmac_f32_e32 v206, v251, v94
	v_fmac_f32_e32 v207, v251, v95
	v_fmac_f32_e32 v204, v132, v124
	v_fmac_f32_e32 v205, v132, v125
	v_fmac_f32_e32 v206, v132, v126
	v_fmac_f32_e32 v207, v132, v127
	s_sub_u32 s62, s62, s64
	s_subb_u32 s63, s63, 0
	s_add_u32 s42, s62, 0x1000
	s_addc_u32 s43, s63, 0
	global_load_dwordx4 v[64:67], v136, s[62:63] nt
	global_load_dwordx4 v[68:71], v136, s[62:63] offset:1024 nt
	global_load_dwordx4 v[72:75], v136, s[62:63] offset:2048 nt
	global_load_dwordx4 v[76:79], v136, s[62:63] offset:3072 nt
	global_load_dwordx4 v[80:83], v136, s[42:43] nt
	global_load_dwordx4 v[84:87], v136, s[42:43] offset:1024 nt
	global_load_dwordx4 v[88:91], v136, s[42:43] offset:2048 nt
	global_load_dwordx4 v[92:95], v136, s[42:43] offset:3072 nt
	s_sub_u32 s62, s62, s64
	s_subb_u32 s63, s63, 0
	s_add_u32 s42, s62, 0x1000
	s_addc_u32 s43, s63, 0
	global_load_dwordx4 v[96:99], v136, s[62:63] nt
	global_load_dwordx4 v[100:103], v136, s[62:63] offset:1024 nt
	global_load_dwordx4 v[104:107], v136, s[62:63] offset:2048 nt
	global_load_dwordx4 v[108:111], v136, s[62:63] offset:3072 nt
	global_load_dwordx4 v[112:115], v136, s[42:43] nt
	global_load_dwordx4 v[116:119], v136, s[42:43] offset:1024 nt
	global_load_dwordx4 v[120:123], v136, s[42:43] offset:2048 nt
	global_load_dwordx4 v[124:127], v136, s[42:43] offset:3072 nt
	s_waitcnt vmcnt(31)
	v_mul_f32_e32 v244, v138, v0
	v_fmac_f32_e32 v244, v139, v1
	v_fmac_f32_e32 v244, v140, v2
	v_fmac_f32_e32 v244, v141, v3
	s_waitcnt vmcnt(30)
	v_mul_f32_e32 v245, v142, v4
	v_fmac_f32_e32 v245, v143, v5
	v_fmac_f32_e32 v245, v144, v6
	v_fmac_f32_e32 v245, v145, v7
	s_waitcnt vmcnt(29)
	v_mul_f32_e32 v246, v146, v8
	v_fmac_f32_e32 v246, v147, v9
	v_fmac_f32_e32 v246, v148, v10
	v_fmac_f32_e32 v246, v149, v11
	v_add_f32_dpp v244, v244, v244 quad_perm:[1,0,3,2] row_mask:0xf bank_mask:0xf bound_ctrl:1
	v_add_f32_dpp v245, v245, v245 quad_perm:[1,0,3,2] row_mask:0xf bank_mask:0xf bound_ctrl:1
	v_add_f32_dpp v246, v246, v246 quad_perm:[1,0,3,2] row_mask:0xf bank_mask:0xf bound_ctrl:1
	v_add_f32_dpp v244, v244, v244 quad_perm:[2,3,0,1] row_mask:0xf bank_mask:0xf bound_ctrl:1
	v_add_f32_dpp v245, v245, v245 quad_perm:[2,3,0,1] row_mask:0xf bank_mask:0xf bound_ctrl:1
	v_add_f32_dpp v246, v246, v246 quad_perm:[2,3,0,1] row_mask:0xf bank_mask:0xf bound_ctrl:1
	v_add_f32_dpp v244, v244, v244 row_ror:4 row_mask:0xf bank_mask:0xf bound_ctrl:1
	v_add_f32_dpp v245, v245, v245 row_ror:4 row_mask:0xf bank_mask:0xf bound_ctrl:1
	v_add_f32_dpp v246, v246, v246 row_ror:4 row_mask:0xf bank_mask:0xf bound_ctrl:1
	v_add_f32_dpp v244, v244, v244 row_ror:8 row_mask:0xf bank_mask:0xf bound_ctrl:1
	v_add_f32_dpp v245, v245, v245 row_ror:8 row_mask:0xf bank_mask:0xf bound_ctrl:1
	v_add_f32_dpp v246, v246, v246 row_ror:8 row_mask:0xf bank_mask:0xf bound_ctrl:1
	v_mov_b32_e32 v133, v244
	v_mov_b32_e32 v134, v245
	v_mov_b32_e32 v135, v246
	v_permlane32_swap_b32_e32 v244, v133
	v_permlane32_swap_b32_e32 v245, v134
	v_permlane32_swap_b32_e32 v246, v135
	s_waitcnt vmcnt(28)
	v_mul_f32_e32 v247, v150, v12
	v_fmac_f32_e32 v247, v151, v13
	v_fmac_f32_e32 v247, v152, v14
	v_fmac_f32_e32 v247, v153, v15
	s_waitcnt vmcnt(27)
	v_mul_f32_e32 v248, v154, v16
	v_fmac_f32_e32 v248, v155, v17
	v_fmac_f32_e32 v248, v156, v18
	v_fmac_f32_e32 v248, v157, v19
	s_waitcnt vmcnt(26)
	v_mul_f32_e32 v249, v158, v20
	v_fmac_f32_e32 v249, v159, v21
	v_fmac_f32_e32 v249, v160, v22
	v_fmac_f32_e32 v249, v161, v23
	v_add_f32_dpp v247, v247, v247 quad_perm:[1,0,3,2] row_mask:0xf bank_mask:0xf bound_ctrl:1
	v_add_f32_dpp v248, v248, v248 quad_perm:[1,0,3,2] row_mask:0xf bank_mask:0xf bound_ctrl:1
	v_add_f32_dpp v249, v249, v249 quad_perm:[1,0,3,2] row_mask:0xf bank_mask:0xf bound_ctrl:1
	v_add_f32_dpp v247, v247, v247 quad_perm:[2,3,0,1] row_mask:0xf bank_mask:0xf bound_ctrl:1
	v_add_f32_dpp v248, v248, v248 quad_perm:[2,3,0,1] row_mask:0xf bank_mask:0xf bound_ctrl:1
	v_add_f32_dpp v249, v249, v249 quad_perm:[2,3,0,1] row_mask:0xf bank_mask:0xf bound_ctrl:1
	v_add_f32_dpp v247, v247, v247 row_ror:4 row_mask:0xf bank_mask:0xf bound_ctrl:1
	v_add_f32_dpp v248, v248, v248 row_ror:4 row_mask:0xf bank_mask:0xf bound_ctrl:1
	v_add_f32_dpp v249, v249, v249 row_ror:4 row_mask:0xf bank_mask:0xf bound_ctrl:1
	v_add_f32_dpp v247, v247, v247 row_ror:8 row_mask:0xf bank_mask:0xf bound_ctrl:1
	v_add_f32_dpp v248, v248, v248 row_ror:8 row_mask:0xf bank_mask:0xf bound_ctrl:1
	v_add_f32_dpp v249, v249, v249 row_ror:8 row_mask:0xf bank_mask:0xf bound_ctrl:1
	v_mov_b32_e32 v133, v247
	v_mov_b32_e32 v134, v248
	v_mov_b32_e32 v135, v249
	v_permlane32_swap_b32_e32 v247, v133
	v_permlane32_swap_b32_e32 v248, v134
	v_permlane32_swap_b32_e32 v249, v135
	s_waitcnt vmcnt(25)
	v_mul_f32_e32 v250, v162, v24
	v_fmac_f32_e32 v250, v163, v25
	v_fmac_f32_e32 v250, v164, v26
	v_fmac_f32_e32 v250, v165, v27
	s_waitcnt vmcnt(24)
	v_mul_f32_e32 v251, v166, v28
	v_fmac_f32_e32 v251, v167, v29
	v_fmac_f32_e32 v251, v168, v30
	v_fmac_f32_e32 v251, v169, v31
	s_waitcnt vmcnt(23)
	v_mul_f32_e32 v252, v138, v32
	v_fmac_f32_e32 v252, v139, v33
	v_fmac_f32_e32 v252, v140, v34
	v_fmac_f32_e32 v252, v141, v35
	v_add_f32_dpp v250, v250, v250 quad_perm:[1,0,3,2] row_mask:0xf bank_mask:0xf bound_ctrl:1
	v_add_f32_dpp v251, v251, v251 quad_perm:[1,0,3,2] row_mask:0xf bank_mask:0xf bound_ctrl:1
	v_add_f32_dpp v252, v252, v252 quad_perm:[1,0,3,2] row_mask:0xf bank_mask:0xf bound_ctrl:1
	v_add_f32_dpp v250, v250, v250 quad_perm:[2,3,0,1] row_mask:0xf bank_mask:0xf bound_ctrl:1
	v_add_f32_dpp v251, v251, v251 quad_perm:[2,3,0,1] row_mask:0xf bank_mask:0xf bound_ctrl:1
	v_add_f32_dpp v252, v252, v252 quad_perm:[2,3,0,1] row_mask:0xf bank_mask:0xf bound_ctrl:1
	v_add_f32_dpp v250, v250, v250 row_ror:4 row_mask:0xf bank_mask:0xf bound_ctrl:1
	v_add_f32_dpp v251, v251, v251 row_ror:4 row_mask:0xf bank_mask:0xf bound_ctrl:1
	v_add_f32_dpp v252, v252, v252 row_ror:4 row_mask:0xf bank_mask:0xf bound_ctrl:1
	v_add_f32_dpp v250, v250, v250 row_ror:8 row_mask:0xf bank_mask:0xf bound_ctrl:1
	v_add_f32_dpp v251, v251, v251 row_ror:8 row_mask:0xf bank_mask:0xf bound_ctrl:1
	v_add_f32_dpp v252, v252, v252 row_ror:8 row_mask:0xf bank_mask:0xf bound_ctrl:1
	v_mov_b32_e32 v133, v250
	v_mov_b32_e32 v134, v251
	v_mov_b32_e32 v135, v252
	v_permlane32_swap_b32_e32 v250, v133
	v_permlane32_swap_b32_e32 v251, v134
	v_permlane32_swap_b32_e32 v252, v135
	s_waitcnt vmcnt(22)
	v_mul_f32_e32 v253, v142, v36
	v_fmac_f32_e32 v253, v143, v37
	v_fmac_f32_e32 v253, v144, v38
	v_fmac_f32_e32 v253, v145, v39
	s_waitcnt vmcnt(21)
	v_mul_f32_e32 v254, v146, v40
	v_fmac_f32_e32 v254, v147, v41
	v_fmac_f32_e32 v254, v148, v42
	v_fmac_f32_e32 v254, v149, v43
	s_waitcnt vmcnt(20)
	v_mul_f32_e32 v128, v150, v44
	v_fmac_f32_e32 v128, v151, v45
	v_fmac_f32_e32 v128, v152, v46
	v_fmac_f32_e32 v128, v153, v47
	v_add_f32_dpp v253, v253, v253 quad_perm:[1,0,3,2] row_mask:0xf bank_mask:0xf bound_ctrl:1
	v_add_f32_dpp v254, v254, v254 quad_perm:[1,0,3,2] row_mask:0xf bank_mask:0xf bound_ctrl:1
	v_add_f32_dpp v128, v128, v128 quad_perm:[1,0,3,2] row_mask:0xf bank_mask:0xf bound_ctrl:1
	v_add_f32_dpp v253, v253, v253 quad_perm:[2,3,0,1] row_mask:0xf bank_mask:0xf bound_ctrl:1
	v_add_f32_dpp v254, v254, v254 quad_perm:[2,3,0,1] row_mask:0xf bank_mask:0xf bound_ctrl:1
	v_add_f32_dpp v128, v128, v128 quad_perm:[2,3,0,1] row_mask:0xf bank_mask:0xf bound_ctrl:1
	v_add_f32_dpp v253, v253, v253 row_ror:4 row_mask:0xf bank_mask:0xf bound_ctrl:1
	v_add_f32_dpp v254, v254, v254 row_ror:4 row_mask:0xf bank_mask:0xf bound_ctrl:1
	v_add_f32_dpp v128, v128, v128 row_ror:4 row_mask:0xf bank_mask:0xf bound_ctrl:1
	v_add_f32_dpp v253, v253, v253 row_ror:8 row_mask:0xf bank_mask:0xf bound_ctrl:1
	v_add_f32_dpp v254, v254, v254 row_ror:8 row_mask:0xf bank_mask:0xf bound_ctrl:1
	v_add_f32_dpp v128, v128, v128 row_ror:8 row_mask:0xf bank_mask:0xf bound_ctrl:1
	v_mov_b32_e32 v133, v253
	v_mov_b32_e32 v134, v254
	v_mov_b32_e32 v135, v128
	v_permlane32_swap_b32_e32 v253, v133
	v_permlane32_swap_b32_e32 v254, v134
	v_permlane32_swap_b32_e32 v128, v135
	s_waitcnt vmcnt(19)
	v_mul_f32_e32 v129, v154, v48
	v_fmac_f32_e32 v129, v155, v49
	v_fmac_f32_e32 v129, v156, v50
	v_fmac_f32_e32 v129, v157, v51
	s_waitcnt vmcnt(18)
	v_mul_f32_e32 v130, v158, v52
	v_fmac_f32_e32 v130, v159, v53
	v_fmac_f32_e32 v130, v160, v54
	v_fmac_f32_e32 v130, v161, v55
	s_waitcnt vmcnt(17)
	v_mul_f32_e32 v131, v162, v56
	v_fmac_f32_e32 v131, v163, v57
	v_fmac_f32_e32 v131, v164, v58
	v_fmac_f32_e32 v131, v165, v59
	v_add_f32_dpp v129, v129, v129 quad_perm:[1,0,3,2] row_mask:0xf bank_mask:0xf bound_ctrl:1
	v_add_f32_dpp v130, v130, v130 quad_perm:[1,0,3,2] row_mask:0xf bank_mask:0xf bound_ctrl:1
	v_add_f32_dpp v131, v131, v131 quad_perm:[1,0,3,2] row_mask:0xf bank_mask:0xf bound_ctrl:1
	v_add_f32_dpp v129, v129, v129 quad_perm:[2,3,0,1] row_mask:0xf bank_mask:0xf bound_ctrl:1
	v_add_f32_dpp v130, v130, v130 quad_perm:[2,3,0,1] row_mask:0xf bank_mask:0xf bound_ctrl:1
	v_add_f32_dpp v131, v131, v131 quad_perm:[2,3,0,1] row_mask:0xf bank_mask:0xf bound_ctrl:1
	v_add_f32_dpp v129, v129, v129 row_ror:4 row_mask:0xf bank_mask:0xf bound_ctrl:1
	v_add_f32_dpp v130, v130, v130 row_ror:4 row_mask:0xf bank_mask:0xf bound_ctrl:1
	v_add_f32_dpp v131, v131, v131 row_ror:4 row_mask:0xf bank_mask:0xf bound_ctrl:1
	v_add_f32_dpp v129, v129, v129 row_ror:8 row_mask:0xf bank_mask:0xf bound_ctrl:1
	v_add_f32_dpp v130, v130, v130 row_ror:8 row_mask:0xf bank_mask:0xf bound_ctrl:1
	v_add_f32_dpp v131, v131, v131 row_ror:8 row_mask:0xf bank_mask:0xf bound_ctrl:1
	v_mov_b32_e32 v133, v129
	v_mov_b32_e32 v134, v130
	v_mov_b32_e32 v135, v131
	v_permlane32_swap_b32_e32 v129, v133
	v_permlane32_swap_b32_e32 v130, v134
	v_permlane32_swap_b32_e32 v131, v135
	s_waitcnt vmcnt(16)
	v_mul_f32_e32 v132, v166, v60
	v_fmac_f32_e32 v132, v167, v61
	v_fmac_f32_e32 v132, v168, v62
	v_fmac_f32_e32 v132, v169, v63
	s_nop 1
	v_add_f32_dpp v132, v132, v132 quad_perm:[1,0,3,2] row_mask:0xf bank_mask:0xf bound_ctrl:1
	s_nop 1
	v_add_f32_dpp v132, v132, v132 quad_perm:[2,3,0,1] row_mask:0xf bank_mask:0xf bound_ctrl:1
	s_nop 1
	v_add_f32_dpp v132, v132, v132 row_ror:4 row_mask:0xf bank_mask:0xf bound_ctrl:1
	s_nop 1
	v_add_f32_dpp v132, v132, v132 row_ror:8 row_mask:0xf bank_mask:0xf bound_ctrl:1
	s_nop 1
	v_mov_b32_e32 v133, v132
	s_nop 1
	v_permlane32_swap_b32_e32 v132, v133
	v_max3_f32 v228, v244, v252, v208
	v_sub_f32_e32 v227, v208, v228
	v_sub_f32_e32 v244, v244, v228
	v_sub_f32_e32 v252, v252, v228
	v_mul_f32_e32 v227, 0x3fb8aa3b, v227
	v_mul_f32_e32 v244, 0x3fb8aa3b, v244
	v_mul_f32_e32 v252, 0x3fb8aa3b, v252
	v_exp_f32_e32 v227, v227
	v_exp_f32_e32 v244, v244
	v_exp_f32_e32 v252, v252
	v_mov_b32_e32 v208, v228
	v_fma_f32 v219, v219, v227, v244
	v_add_f32_e32 v219, v219, v252
	v_mul_f32_e32 v172, v172, v227
	v_mul_f32_e32 v173, v173, v227
	v_mul_f32_e32 v174, v174, v227
	v_mul_f32_e32 v175, v175, v227
	v_fmac_f32_e32 v172, v244, v0
	v_fmac_f32_e32 v173, v244, v1
	v_fmac_f32_e32 v174, v244, v2
	v_fmac_f32_e32 v175, v244, v3
	v_fmac_f32_e32 v172, v252, v32
	v_fmac_f32_e32 v173, v252, v33
	v_fmac_f32_e32 v174, v252, v34
	v_fmac_f32_e32 v175, v252, v35
	v_max3_f32 v228, v245, v253, v209
	v_sub_f32_e32 v227, v209, v228
	v_sub_f32_e32 v245, v245, v228
	v_sub_f32_e32 v253, v253, v228
	v_mul_f32_e32 v227, 0x3fb8aa3b, v227
	v_mul_f32_e32 v245, 0x3fb8aa3b, v245
	v_mul_f32_e32 v253, 0x3fb8aa3b, v253
	v_exp_f32_e32 v227, v227
	v_exp_f32_e32 v245, v245
	v_exp_f32_e32 v253, v253
	v_mov_b32_e32 v209, v228
	v_fma_f32 v220, v220, v227, v245
	v_add_f32_e32 v220, v220, v253
	v_mul_f32_e32 v176, v176, v227
	v_mul_f32_e32 v177, v177, v227
	v_mul_f32_e32 v178, v178, v227
	v_mul_f32_e32 v179, v179, v227
	v_fmac_f32_e32 v176, v245, v4
	v_fmac_f32_e32 v177, v245, v5
	v_fmac_f32_e32 v178, v245, v6
	v_fmac_f32_e32 v179, v245, v7
	v_fmac_f32_e32 v176, v253, v36
	v_fmac_f32_e32 v177, v253, v37
	v_fmac_f32_e32 v178, v253, v38
	v_fmac_f32_e32 v179, v253, v39
	v_max3_f32 v228, v246, v254, v210
	v_sub_f32_e32 v227, v210, v228
	v_sub_f32_e32 v246, v246, v228
	v_sub_f32_e32 v254, v254, v228
	v_mul_f32_e32 v227, 0x3fb8aa3b, v227
	v_mul_f32_e32 v246, 0x3fb8aa3b, v246
	v_mul_f32_e32 v254, 0x3fb8aa3b, v254
	v_exp_f32_e32 v227, v227
	v_exp_f32_e32 v246, v246
	v_exp_f32_e32 v254, v254
	v_mov_b32_e32 v210, v228
	v_fma_f32 v221, v221, v227, v246
	v_add_f32_e32 v221, v221, v254
	v_mul_f32_e32 v180, v180, v227
	v_mul_f32_e32 v181, v181, v227
	v_mul_f32_e32 v182, v182, v227
	v_mul_f32_e32 v183, v183, v227
	v_fmac_f32_e32 v180, v246, v8
	v_fmac_f32_e32 v181, v246, v9
	v_fmac_f32_e32 v182, v246, v10
	v_fmac_f32_e32 v183, v246, v11
	v_fmac_f32_e32 v180, v254, v40
	v_fmac_f32_e32 v181, v254, v41
	v_fmac_f32_e32 v182, v254, v42
	v_fmac_f32_e32 v183, v254, v43
	v_max3_f32 v228, v247, v128, v212
	v_sub_f32_e32 v227, v212, v228
	v_sub_f32_e32 v247, v247, v228
	v_sub_f32_e32 v128, v128, v228
	v_mul_f32_e32 v227, 0x3fb8aa3b, v227
	v_mul_f32_e32 v247, 0x3fb8aa3b, v247
	v_mul_f32_e32 v128, 0x3fb8aa3b, v128
	v_exp_f32_e32 v227, v227
	v_exp_f32_e32 v247, v247
	v_exp_f32_e32 v128, v128
	v_mov_b32_e32 v212, v228
	v_fma_f32 v222, v222, v227, v247
	v_add_f32_e32 v222, v222, v128
	v_mul_f32_e32 v184, v184, v227
	v_mul_f32_e32 v185, v185, v227
	v_mul_f32_e32 v186, v186, v227
	v_mul_f32_e32 v187, v187, v227
	v_fmac_f32_e32 v184, v247, v12
	v_fmac_f32_e32 v185, v247, v13
	v_fmac_f32_e32 v186, v247, v14
	v_fmac_f32_e32 v187, v247, v15
	v_fmac_f32_e32 v184, v128, v44
	v_fmac_f32_e32 v185, v128, v45
	v_fmac_f32_e32 v186, v128, v46
	v_fmac_f32_e32 v187, v128, v47
	v_max3_f32 v228, v248, v129, v214
	v_sub_f32_e32 v227, v214, v228
	v_sub_f32_e32 v248, v248, v228
	v_sub_f32_e32 v129, v129, v228
	v_mul_f32_e32 v227, 0x3fb8aa3b, v227
	v_mul_f32_e32 v248, 0x3fb8aa3b, v248
	v_mul_f32_e32 v129, 0x3fb8aa3b, v129
	v_exp_f32_e32 v227, v227
	v_exp_f32_e32 v248, v248
	v_exp_f32_e32 v129, v129
	v_mov_b32_e32 v214, v228
	v_fma_f32 v223, v223, v227, v248
	v_add_f32_e32 v223, v223, v129
	v_mul_f32_e32 v188, v188, v227
	v_mul_f32_e32 v189, v189, v227
	v_mul_f32_e32 v190, v190, v227
	v_mul_f32_e32 v191, v191, v227
	v_fmac_f32_e32 v188, v248, v16
	v_fmac_f32_e32 v189, v248, v17
	v_fmac_f32_e32 v190, v248, v18
	v_fmac_f32_e32 v191, v248, v19
	v_fmac_f32_e32 v188, v129, v48
	v_fmac_f32_e32 v189, v129, v49
	v_fmac_f32_e32 v190, v129, v50
	v_fmac_f32_e32 v191, v129, v51
	v_max3_f32 v228, v249, v130, v216
	v_sub_f32_e32 v227, v216, v228
	v_sub_f32_e32 v249, v249, v228
	v_sub_f32_e32 v130, v130, v228
	v_mul_f32_e32 v227, 0x3fb8aa3b, v227
	v_mul_f32_e32 v249, 0x3fb8aa3b, v249
	v_mul_f32_e32 v130, 0x3fb8aa3b, v130
	v_exp_f32_e32 v227, v227
	v_exp_f32_e32 v249, v249
	v_exp_f32_e32 v130, v130
	v_mov_b32_e32 v216, v228
	v_fma_f32 v224, v224, v227, v249
	v_add_f32_e32 v224, v224, v130
	v_mul_f32_e32 v196, v196, v227
	v_mul_f32_e32 v197, v197, v227
	v_mul_f32_e32 v198, v198, v227
	v_mul_f32_e32 v199, v199, v227
	v_fmac_f32_e32 v196, v249, v20
	v_fmac_f32_e32 v197, v249, v21
	v_fmac_f32_e32 v198, v249, v22
	v_fmac_f32_e32 v199, v249, v23
	v_fmac_f32_e32 v196, v130, v52
	v_fmac_f32_e32 v197, v130, v53
	v_fmac_f32_e32 v198, v130, v54
	v_fmac_f32_e32 v199, v130, v55
	v_max3_f32 v228, v250, v131, v217
	v_sub_f32_e32 v227, v217, v228
	v_sub_f32_e32 v250, v250, v228
	v_sub_f32_e32 v131, v131, v228
	v_mul_f32_e32 v227, 0x3fb8aa3b, v227
	v_mul_f32_e32 v250, 0x3fb8aa3b, v250
	v_mul_f32_e32 v131, 0x3fb8aa3b, v131
	v_exp_f32_e32 v227, v227
	v_exp_f32_e32 v250, v250
	v_exp_f32_e32 v131, v131
	v_mov_b32_e32 v217, v228
	v_fma_f32 v225, v225, v227, v250
	v_add_f32_e32 v225, v225, v131
	v_mul_f32_e32 v200, v200, v227
	v_mul_f32_e32 v201, v201, v227
	v_mul_f32_e32 v202, v202, v227
	v_mul_f32_e32 v203, v203, v227
	v_fmac_f32_e32 v200, v250, v24
	v_fmac_f32_e32 v201, v250, v25
	v_fmac_f32_e32 v202, v250, v26
	v_fmac_f32_e32 v203, v250, v27
	v_fmac_f32_e32 v200, v131, v56
	v_fmac_f32_e32 v201, v131, v57
	v_fmac_f32_e32 v202, v131, v58
	v_fmac_f32_e32 v203, v131, v59
	v_max3_f32 v228, v251, v132, v218
	v_sub_f32_e32 v227, v218, v228
	v_sub_f32_e32 v251, v251, v228
	v_sub_f32_e32 v132, v132, v228
	v_mul_f32_e32 v227, 0x3fb8aa3b, v227
	v_mul_f32_e32 v251, 0x3fb8aa3b, v251
	v_mul_f32_e32 v132, 0x3fb8aa3b, v132
	v_exp_f32_e32 v227, v227
	v_exp_f32_e32 v251, v251
	v_exp_f32_e32 v132, v132
	v_mov_b32_e32 v218, v228
	v_fma_f32 v226, v226, v227, v251
	v_add_f32_e32 v226, v226, v132
	v_mul_f32_e32 v204, v204, v227
	v_mul_f32_e32 v205, v205, v227
	v_mul_f32_e32 v206, v206, v227
	v_mul_f32_e32 v207, v207, v227
	v_fmac_f32_e32 v204, v251, v28
	v_fmac_f32_e32 v205, v251, v29
	v_fmac_f32_e32 v206, v251, v30
	v_fmac_f32_e32 v207, v251, v31
	v_fmac_f32_e32 v204, v132, v60
	v_fmac_f32_e32 v205, v132, v61
	v_fmac_f32_e32 v206, v132, v62
	v_fmac_f32_e32 v207, v132, v63
	s_sub_u32 s62, s62, s64
	s_subb_u32 s63, s63, 0
	s_add_u32 s42, s62, 0x1000
	s_addc_u32 s43, s63, 0
	global_load_dwordx4 v[0:3], v136, s[62:63] nt
	global_load_dwordx4 v[4:7], v136, s[62:63] offset:1024 nt
	global_load_dwordx4 v[8:11], v136, s[62:63] offset:2048 nt
	global_load_dwordx4 v[12:15], v136, s[62:63] offset:3072 nt
	global_load_dwordx4 v[16:19], v136, s[42:43] nt
	global_load_dwordx4 v[20:23], v136, s[42:43] offset:1024 nt
	global_load_dwordx4 v[24:27], v136, s[42:43] offset:2048 nt
	global_load_dwordx4 v[28:31], v136, s[42:43] offset:3072 nt
	s_sub_u32 s62, s62, s64
	s_subb_u32 s63, s63, 0
	s_add_u32 s42, s62, 0x1000
	s_addc_u32 s43, s63, 0
	global_load_dwordx4 v[32:35], v136, s[62:63] nt
	global_load_dwordx4 v[36:39], v136, s[62:63] offset:1024 nt
	global_load_dwordx4 v[40:43], v136, s[62:63] offset:2048 nt
	global_load_dwordx4 v[44:47], v136, s[62:63] offset:3072 nt
	global_load_dwordx4 v[48:51], v136, s[42:43] nt
	global_load_dwordx4 v[52:55], v136, s[42:43] offset:1024 nt
	global_load_dwordx4 v[56:59], v136, s[42:43] offset:2048 nt
	global_load_dwordx4 v[60:63], v136, s[42:43] offset:3072 nt
	s_waitcnt vmcnt(31)
	v_mul_f32_e32 v244, v138, v64
	v_fmac_f32_e32 v244, v139, v65
	v_fmac_f32_e32 v244, v140, v66
	v_fmac_f32_e32 v244, v141, v67
	s_waitcnt vmcnt(30)
	v_mul_f32_e32 v245, v142, v68
	v_fmac_f32_e32 v245, v143, v69
	v_fmac_f32_e32 v245, v144, v70
	v_fmac_f32_e32 v245, v145, v71
	s_waitcnt vmcnt(29)
	v_mul_f32_e32 v246, v146, v72
	v_fmac_f32_e32 v246, v147, v73
	v_fmac_f32_e32 v246, v148, v74
	v_fmac_f32_e32 v246, v149, v75
	v_add_f32_dpp v244, v244, v244 quad_perm:[1,0,3,2] row_mask:0xf bank_mask:0xf bound_ctrl:1
	v_add_f32_dpp v245, v245, v245 quad_perm:[1,0,3,2] row_mask:0xf bank_mask:0xf bound_ctrl:1
	v_add_f32_dpp v246, v246, v246 quad_perm:[1,0,3,2] row_mask:0xf bank_mask:0xf bound_ctrl:1
	v_add_f32_dpp v244, v244, v244 quad_perm:[2,3,0,1] row_mask:0xf bank_mask:0xf bound_ctrl:1
	v_add_f32_dpp v245, v245, v245 quad_perm:[2,3,0,1] row_mask:0xf bank_mask:0xf bound_ctrl:1
	v_add_f32_dpp v246, v246, v246 quad_perm:[2,3,0,1] row_mask:0xf bank_mask:0xf bound_ctrl:1
	v_add_f32_dpp v244, v244, v244 row_ror:4 row_mask:0xf bank_mask:0xf bound_ctrl:1
	v_add_f32_dpp v245, v245, v245 row_ror:4 row_mask:0xf bank_mask:0xf bound_ctrl:1
	v_add_f32_dpp v246, v246, v246 row_ror:4 row_mask:0xf bank_mask:0xf bound_ctrl:1
	v_add_f32_dpp v244, v244, v244 row_ror:8 row_mask:0xf bank_mask:0xf bound_ctrl:1
	v_add_f32_dpp v245, v245, v245 row_ror:8 row_mask:0xf bank_mask:0xf bound_ctrl:1
	v_add_f32_dpp v246, v246, v246 row_ror:8 row_mask:0xf bank_mask:0xf bound_ctrl:1
	v_mov_b32_e32 v133, v244
	v_mov_b32_e32 v134, v245
	v_mov_b32_e32 v135, v246
	v_permlane32_swap_b32_e32 v244, v133
	v_permlane32_swap_b32_e32 v245, v134
	v_permlane32_swap_b32_e32 v246, v135
	s_waitcnt vmcnt(28)
	v_mul_f32_e32 v247, v150, v76
	v_fmac_f32_e32 v247, v151, v77
	v_fmac_f32_e32 v247, v152, v78
	v_fmac_f32_e32 v247, v153, v79
	s_waitcnt vmcnt(27)
	v_mul_f32_e32 v248, v154, v80
	v_fmac_f32_e32 v248, v155, v81
	v_fmac_f32_e32 v248, v156, v82
	v_fmac_f32_e32 v248, v157, v83
	s_waitcnt vmcnt(26)
	v_mul_f32_e32 v249, v158, v84
	v_fmac_f32_e32 v249, v159, v85
	v_fmac_f32_e32 v249, v160, v86
	v_fmac_f32_e32 v249, v161, v87
	v_add_f32_dpp v247, v247, v247 quad_perm:[1,0,3,2] row_mask:0xf bank_mask:0xf bound_ctrl:1
	v_add_f32_dpp v248, v248, v248 quad_perm:[1,0,3,2] row_mask:0xf bank_mask:0xf bound_ctrl:1
	v_add_f32_dpp v249, v249, v249 quad_perm:[1,0,3,2] row_mask:0xf bank_mask:0xf bound_ctrl:1
	v_add_f32_dpp v247, v247, v247 quad_perm:[2,3,0,1] row_mask:0xf bank_mask:0xf bound_ctrl:1
	v_add_f32_dpp v248, v248, v248 quad_perm:[2,3,0,1] row_mask:0xf bank_mask:0xf bound_ctrl:1
	v_add_f32_dpp v249, v249, v249 quad_perm:[2,3,0,1] row_mask:0xf bank_mask:0xf bound_ctrl:1
	v_add_f32_dpp v247, v247, v247 row_ror:4 row_mask:0xf bank_mask:0xf bound_ctrl:1
	v_add_f32_dpp v248, v248, v248 row_ror:4 row_mask:0xf bank_mask:0xf bound_ctrl:1
	v_add_f32_dpp v249, v249, v249 row_ror:4 row_mask:0xf bank_mask:0xf bound_ctrl:1
	v_add_f32_dpp v247, v247, v247 row_ror:8 row_mask:0xf bank_mask:0xf bound_ctrl:1
	v_add_f32_dpp v248, v248, v248 row_ror:8 row_mask:0xf bank_mask:0xf bound_ctrl:1
	v_add_f32_dpp v249, v249, v249 row_ror:8 row_mask:0xf bank_mask:0xf bound_ctrl:1
	v_mov_b32_e32 v133, v247
	v_mov_b32_e32 v134, v248
	v_mov_b32_e32 v135, v249
	v_permlane32_swap_b32_e32 v247, v133
	v_permlane32_swap_b32_e32 v248, v134
	v_permlane32_swap_b32_e32 v249, v135
	s_waitcnt vmcnt(25)
	v_mul_f32_e32 v250, v162, v88
	v_fmac_f32_e32 v250, v163, v89
	v_fmac_f32_e32 v250, v164, v90
	v_fmac_f32_e32 v250, v165, v91
	s_waitcnt vmcnt(24)
	v_mul_f32_e32 v251, v166, v92
	v_fmac_f32_e32 v251, v167, v93
	v_fmac_f32_e32 v251, v168, v94
	v_fmac_f32_e32 v251, v169, v95
	s_waitcnt vmcnt(23)
	v_mul_f32_e32 v252, v138, v96
	v_fmac_f32_e32 v252, v139, v97
	v_fmac_f32_e32 v252, v140, v98
	v_fmac_f32_e32 v252, v141, v99
	v_add_f32_dpp v250, v250, v250 quad_perm:[1,0,3,2] row_mask:0xf bank_mask:0xf bound_ctrl:1
	v_add_f32_dpp v251, v251, v251 quad_perm:[1,0,3,2] row_mask:0xf bank_mask:0xf bound_ctrl:1
	v_add_f32_dpp v252, v252, v252 quad_perm:[1,0,3,2] row_mask:0xf bank_mask:0xf bound_ctrl:1
	v_add_f32_dpp v250, v250, v250 quad_perm:[2,3,0,1] row_mask:0xf bank_mask:0xf bound_ctrl:1
	v_add_f32_dpp v251, v251, v251 quad_perm:[2,3,0,1] row_mask:0xf bank_mask:0xf bound_ctrl:1
	v_add_f32_dpp v252, v252, v252 quad_perm:[2,3,0,1] row_mask:0xf bank_mask:0xf bound_ctrl:1
	v_add_f32_dpp v250, v250, v250 row_ror:4 row_mask:0xf bank_mask:0xf bound_ctrl:1
	v_add_f32_dpp v251, v251, v251 row_ror:4 row_mask:0xf bank_mask:0xf bound_ctrl:1
	v_add_f32_dpp v252, v252, v252 row_ror:4 row_mask:0xf bank_mask:0xf bound_ctrl:1
	v_add_f32_dpp v250, v250, v250 row_ror:8 row_mask:0xf bank_mask:0xf bound_ctrl:1
	v_add_f32_dpp v251, v251, v251 row_ror:8 row_mask:0xf bank_mask:0xf bound_ctrl:1
	v_add_f32_dpp v252, v252, v252 row_ror:8 row_mask:0xf bank_mask:0xf bound_ctrl:1
	v_mov_b32_e32 v133, v250
	v_mov_b32_e32 v134, v251
	v_mov_b32_e32 v135, v252
	v_permlane32_swap_b32_e32 v250, v133
	v_permlane32_swap_b32_e32 v251, v134
	v_permlane32_swap_b32_e32 v252, v135
	s_waitcnt vmcnt(22)
	v_mul_f32_e32 v253, v142, v100
	v_fmac_f32_e32 v253, v143, v101
	v_fmac_f32_e32 v253, v144, v102
	v_fmac_f32_e32 v253, v145, v103
	s_waitcnt vmcnt(21)
	v_mul_f32_e32 v254, v146, v104
	v_fmac_f32_e32 v254, v147, v105
	v_fmac_f32_e32 v254, v148, v106
	v_fmac_f32_e32 v254, v149, v107
	s_waitcnt vmcnt(20)
	v_mul_f32_e32 v128, v150, v108
	v_fmac_f32_e32 v128, v151, v109
	v_fmac_f32_e32 v128, v152, v110
	v_fmac_f32_e32 v128, v153, v111
	v_add_f32_dpp v253, v253, v253 quad_perm:[1,0,3,2] row_mask:0xf bank_mask:0xf bound_ctrl:1
	v_add_f32_dpp v254, v254, v254 quad_perm:[1,0,3,2] row_mask:0xf bank_mask:0xf bound_ctrl:1
	v_add_f32_dpp v128, v128, v128 quad_perm:[1,0,3,2] row_mask:0xf bank_mask:0xf bound_ctrl:1
	v_add_f32_dpp v253, v253, v253 quad_perm:[2,3,0,1] row_mask:0xf bank_mask:0xf bound_ctrl:1
	v_add_f32_dpp v254, v254, v254 quad_perm:[2,3,0,1] row_mask:0xf bank_mask:0xf bound_ctrl:1
	v_add_f32_dpp v128, v128, v128 quad_perm:[2,3,0,1] row_mask:0xf bank_mask:0xf bound_ctrl:1
	v_add_f32_dpp v253, v253, v253 row_ror:4 row_mask:0xf bank_mask:0xf bound_ctrl:1
	v_add_f32_dpp v254, v254, v254 row_ror:4 row_mask:0xf bank_mask:0xf bound_ctrl:1
	v_add_f32_dpp v128, v128, v128 row_ror:4 row_mask:0xf bank_mask:0xf bound_ctrl:1
	v_add_f32_dpp v253, v253, v253 row_ror:8 row_mask:0xf bank_mask:0xf bound_ctrl:1
	v_add_f32_dpp v254, v254, v254 row_ror:8 row_mask:0xf bank_mask:0xf bound_ctrl:1
	v_add_f32_dpp v128, v128, v128 row_ror:8 row_mask:0xf bank_mask:0xf bound_ctrl:1
	v_mov_b32_e32 v133, v253
	v_mov_b32_e32 v134, v254
	v_mov_b32_e32 v135, v128
	v_permlane32_swap_b32_e32 v253, v133
	v_permlane32_swap_b32_e32 v254, v134
	v_permlane32_swap_b32_e32 v128, v135
	s_waitcnt vmcnt(19)
	v_mul_f32_e32 v129, v154, v112
	v_fmac_f32_e32 v129, v155, v113
	v_fmac_f32_e32 v129, v156, v114
	v_fmac_f32_e32 v129, v157, v115
	s_waitcnt vmcnt(18)
	v_mul_f32_e32 v130, v158, v116
	v_fmac_f32_e32 v130, v159, v117
	v_fmac_f32_e32 v130, v160, v118
	v_fmac_f32_e32 v130, v161, v119
	s_waitcnt vmcnt(17)
	v_mul_f32_e32 v131, v162, v120
	v_fmac_f32_e32 v131, v163, v121
	v_fmac_f32_e32 v131, v164, v122
	v_fmac_f32_e32 v131, v165, v123
	v_add_f32_dpp v129, v129, v129 quad_perm:[1,0,3,2] row_mask:0xf bank_mask:0xf bound_ctrl:1
	v_add_f32_dpp v130, v130, v130 quad_perm:[1,0,3,2] row_mask:0xf bank_mask:0xf bound_ctrl:1
	v_add_f32_dpp v131, v131, v131 quad_perm:[1,0,3,2] row_mask:0xf bank_mask:0xf bound_ctrl:1
	v_add_f32_dpp v129, v129, v129 quad_perm:[2,3,0,1] row_mask:0xf bank_mask:0xf bound_ctrl:1
	v_add_f32_dpp v130, v130, v130 quad_perm:[2,3,0,1] row_mask:0xf bank_mask:0xf bound_ctrl:1
	v_add_f32_dpp v131, v131, v131 quad_perm:[2,3,0,1] row_mask:0xf bank_mask:0xf bound_ctrl:1
	v_add_f32_dpp v129, v129, v129 row_ror:4 row_mask:0xf bank_mask:0xf bound_ctrl:1
	v_add_f32_dpp v130, v130, v130 row_ror:4 row_mask:0xf bank_mask:0xf bound_ctrl:1
	v_add_f32_dpp v131, v131, v131 row_ror:4 row_mask:0xf bank_mask:0xf bound_ctrl:1
	v_add_f32_dpp v129, v129, v129 row_ror:8 row_mask:0xf bank_mask:0xf bound_ctrl:1
	v_add_f32_dpp v130, v130, v130 row_ror:8 row_mask:0xf bank_mask:0xf bound_ctrl:1
	v_add_f32_dpp v131, v131, v131 row_ror:8 row_mask:0xf bank_mask:0xf bound_ctrl:1
	v_mov_b32_e32 v133, v129
	v_mov_b32_e32 v134, v130
	v_mov_b32_e32 v135, v131
	v_permlane32_swap_b32_e32 v129, v133
	v_permlane32_swap_b32_e32 v130, v134
	v_permlane32_swap_b32_e32 v131, v135
	s_waitcnt vmcnt(16)
	v_mul_f32_e32 v132, v166, v124
	v_fmac_f32_e32 v132, v167, v125
	v_fmac_f32_e32 v132, v168, v126
	v_fmac_f32_e32 v132, v169, v127
	s_nop 1
	v_add_f32_dpp v132, v132, v132 quad_perm:[1,0,3,2] row_mask:0xf bank_mask:0xf bound_ctrl:1
	s_nop 1
	v_add_f32_dpp v132, v132, v132 quad_perm:[2,3,0,1] row_mask:0xf bank_mask:0xf bound_ctrl:1
	s_nop 1
	v_add_f32_dpp v132, v132, v132 row_ror:4 row_mask:0xf bank_mask:0xf bound_ctrl:1
	s_nop 1
	v_add_f32_dpp v132, v132, v132 row_ror:8 row_mask:0xf bank_mask:0xf bound_ctrl:1
	s_nop 1
	v_mov_b32_e32 v133, v132
	s_nop 1
	v_permlane32_swap_b32_e32 v132, v133
	v_max3_f32 v228, v244, v252, v208
	v_sub_f32_e32 v227, v208, v228
	v_sub_f32_e32 v244, v244, v228
	v_sub_f32_e32 v252, v252, v228
	v_mul_f32_e32 v227, 0x3fb8aa3b, v227
	v_mul_f32_e32 v244, 0x3fb8aa3b, v244
	v_mul_f32_e32 v252, 0x3fb8aa3b, v252
	v_exp_f32_e32 v227, v227
	v_exp_f32_e32 v244, v244
	v_exp_f32_e32 v252, v252
	v_mov_b32_e32 v208, v228
	v_fma_f32 v219, v219, v227, v244
	v_add_f32_e32 v219, v219, v252
	v_mul_f32_e32 v172, v172, v227
	v_mul_f32_e32 v173, v173, v227
	v_mul_f32_e32 v174, v174, v227
	v_mul_f32_e32 v175, v175, v227
	v_fmac_f32_e32 v172, v244, v64
	v_fmac_f32_e32 v173, v244, v65
	v_fmac_f32_e32 v174, v244, v66
	v_fmac_f32_e32 v175, v244, v67
	v_fmac_f32_e32 v172, v252, v96
	v_fmac_f32_e32 v173, v252, v97
	v_fmac_f32_e32 v174, v252, v98
	v_fmac_f32_e32 v175, v252, v99
	v_max3_f32 v228, v245, v253, v209
	v_sub_f32_e32 v227, v209, v228
	v_sub_f32_e32 v245, v245, v228
	v_sub_f32_e32 v253, v253, v228
	v_mul_f32_e32 v227, 0x3fb8aa3b, v227
	v_mul_f32_e32 v245, 0x3fb8aa3b, v245
	v_mul_f32_e32 v253, 0x3fb8aa3b, v253
	v_exp_f32_e32 v227, v227
	v_exp_f32_e32 v245, v245
	v_exp_f32_e32 v253, v253
	v_mov_b32_e32 v209, v228
	v_fma_f32 v220, v220, v227, v245
	v_add_f32_e32 v220, v220, v253
	v_mul_f32_e32 v176, v176, v227
	v_mul_f32_e32 v177, v177, v227
	v_mul_f32_e32 v178, v178, v227
	v_mul_f32_e32 v179, v179, v227
	v_fmac_f32_e32 v176, v245, v68
	v_fmac_f32_e32 v177, v245, v69
	v_fmac_f32_e32 v178, v245, v70
	v_fmac_f32_e32 v179, v245, v71
	v_fmac_f32_e32 v176, v253, v100
	v_fmac_f32_e32 v177, v253, v101
	v_fmac_f32_e32 v178, v253, v102
	v_fmac_f32_e32 v179, v253, v103
	v_max3_f32 v228, v246, v254, v210
	v_sub_f32_e32 v227, v210, v228
	v_sub_f32_e32 v246, v246, v228
	v_sub_f32_e32 v254, v254, v228
	v_mul_f32_e32 v227, 0x3fb8aa3b, v227
	v_mul_f32_e32 v246, 0x3fb8aa3b, v246
	v_mul_f32_e32 v254, 0x3fb8aa3b, v254
	v_exp_f32_e32 v227, v227
	v_exp_f32_e32 v246, v246
	v_exp_f32_e32 v254, v254
	v_mov_b32_e32 v210, v228
	v_fma_f32 v221, v221, v227, v246
	v_add_f32_e32 v221, v221, v254
	v_mul_f32_e32 v180, v180, v227
	v_mul_f32_e32 v181, v181, v227
	v_mul_f32_e32 v182, v182, v227
	v_mul_f32_e32 v183, v183, v227
	v_fmac_f32_e32 v180, v246, v72
	v_fmac_f32_e32 v181, v246, v73
	v_fmac_f32_e32 v182, v246, v74
	v_fmac_f32_e32 v183, v246, v75
	v_fmac_f32_e32 v180, v254, v104
	v_fmac_f32_e32 v181, v254, v105
	v_fmac_f32_e32 v182, v254, v106
	v_fmac_f32_e32 v183, v254, v107
	v_max3_f32 v228, v247, v128, v212
	v_sub_f32_e32 v227, v212, v228
	v_sub_f32_e32 v247, v247, v228
	v_sub_f32_e32 v128, v128, v228
	v_mul_f32_e32 v227, 0x3fb8aa3b, v227
	v_mul_f32_e32 v247, 0x3fb8aa3b, v247
	v_mul_f32_e32 v128, 0x3fb8aa3b, v128
	v_exp_f32_e32 v227, v227
	v_exp_f32_e32 v247, v247
	v_exp_f32_e32 v128, v128
	v_mov_b32_e32 v212, v228
	v_fma_f32 v222, v222, v227, v247
	v_add_f32_e32 v222, v222, v128
	v_mul_f32_e32 v184, v184, v227
	v_mul_f32_e32 v185, v185, v227
	v_mul_f32_e32 v186, v186, v227
	v_mul_f32_e32 v187, v187, v227
	v_fmac_f32_e32 v184, v247, v76
	v_fmac_f32_e32 v185, v247, v77
	v_fmac_f32_e32 v186, v247, v78
	v_fmac_f32_e32 v187, v247, v79
	v_fmac_f32_e32 v184, v128, v108
	v_fmac_f32_e32 v185, v128, v109
	v_fmac_f32_e32 v186, v128, v110
	v_fmac_f32_e32 v187, v128, v111
	v_max3_f32 v228, v248, v129, v214
	v_sub_f32_e32 v227, v214, v228
	v_sub_f32_e32 v248, v248, v228
	v_sub_f32_e32 v129, v129, v228
	v_mul_f32_e32 v227, 0x3fb8aa3b, v227
	v_mul_f32_e32 v248, 0x3fb8aa3b, v248
	v_mul_f32_e32 v129, 0x3fb8aa3b, v129
	v_exp_f32_e32 v227, v227
	v_exp_f32_e32 v248, v248
	v_exp_f32_e32 v129, v129
	v_mov_b32_e32 v214, v228
	v_fma_f32 v223, v223, v227, v248
	v_add_f32_e32 v223, v223, v129
	v_mul_f32_e32 v188, v188, v227
	v_mul_f32_e32 v189, v189, v227
	v_mul_f32_e32 v190, v190, v227
	v_mul_f32_e32 v191, v191, v227
	v_fmac_f32_e32 v188, v248, v80
	v_fmac_f32_e32 v189, v248, v81
	v_fmac_f32_e32 v190, v248, v82
	v_fmac_f32_e32 v191, v248, v83
	v_fmac_f32_e32 v188, v129, v112
	v_fmac_f32_e32 v189, v129, v113
	v_fmac_f32_e32 v190, v129, v114
	v_fmac_f32_e32 v191, v129, v115
	v_max3_f32 v228, v249, v130, v216
	v_sub_f32_e32 v227, v216, v228
	v_sub_f32_e32 v249, v249, v228
	v_sub_f32_e32 v130, v130, v228
	v_mul_f32_e32 v227, 0x3fb8aa3b, v227
	v_mul_f32_e32 v249, 0x3fb8aa3b, v249
	v_mul_f32_e32 v130, 0x3fb8aa3b, v130
	v_exp_f32_e32 v227, v227
	v_exp_f32_e32 v249, v249
	v_exp_f32_e32 v130, v130
	v_mov_b32_e32 v216, v228
	v_fma_f32 v224, v224, v227, v249
	v_add_f32_e32 v224, v224, v130
	v_mul_f32_e32 v196, v196, v227
	v_mul_f32_e32 v197, v197, v227
	v_mul_f32_e32 v198, v198, v227
	v_mul_f32_e32 v199, v199, v227
	v_fmac_f32_e32 v196, v249, v84
	v_fmac_f32_e32 v197, v249, v85
	v_fmac_f32_e32 v198, v249, v86
	v_fmac_f32_e32 v199, v249, v87
	v_fmac_f32_e32 v196, v130, v116
	v_fmac_f32_e32 v197, v130, v117
	v_fmac_f32_e32 v198, v130, v118
	v_fmac_f32_e32 v199, v130, v119
	v_max3_f32 v228, v250, v131, v217
	v_sub_f32_e32 v227, v217, v228
	v_sub_f32_e32 v250, v250, v228
	v_sub_f32_e32 v131, v131, v228
	v_mul_f32_e32 v227, 0x3fb8aa3b, v227
	v_mul_f32_e32 v250, 0x3fb8aa3b, v250
	v_mul_f32_e32 v131, 0x3fb8aa3b, v131
	v_exp_f32_e32 v227, v227
	v_exp_f32_e32 v250, v250
	v_exp_f32_e32 v131, v131
	v_mov_b32_e32 v217, v228
	v_fma_f32 v225, v225, v227, v250
	v_add_f32_e32 v225, v225, v131
	v_mul_f32_e32 v200, v200, v227
	v_mul_f32_e32 v201, v201, v227
	v_mul_f32_e32 v202, v202, v227
	v_mul_f32_e32 v203, v203, v227
	v_fmac_f32_e32 v200, v250, v88
	v_fmac_f32_e32 v201, v250, v89
	v_fmac_f32_e32 v202, v250, v90
	v_fmac_f32_e32 v203, v250, v91
	v_fmac_f32_e32 v200, v131, v120
	v_fmac_f32_e32 v201, v131, v121
	v_fmac_f32_e32 v202, v131, v122
	v_fmac_f32_e32 v203, v131, v123
	v_max3_f32 v228, v251, v132, v218
	v_sub_f32_e32 v227, v218, v228
	v_sub_f32_e32 v251, v251, v228
	v_sub_f32_e32 v132, v132, v228
	v_mul_f32_e32 v227, 0x3fb8aa3b, v227
	v_mul_f32_e32 v251, 0x3fb8aa3b, v251
	v_mul_f32_e32 v132, 0x3fb8aa3b, v132
	v_exp_f32_e32 v227, v227
	v_exp_f32_e32 v251, v251
	v_exp_f32_e32 v132, v132
	v_mov_b32_e32 v218, v228
	v_fma_f32 v226, v226, v227, v251
	v_add_f32_e32 v226, v226, v132
	v_mul_f32_e32 v204, v204, v227
	v_mul_f32_e32 v205, v205, v227
	v_mul_f32_e32 v206, v206, v227
	v_mul_f32_e32 v207, v207, v227
	v_fmac_f32_e32 v204, v251, v92
	v_fmac_f32_e32 v205, v251, v93
	v_fmac_f32_e32 v206, v251, v94
	v_fmac_f32_e32 v207, v251, v95
	v_fmac_f32_e32 v204, v132, v124
	v_fmac_f32_e32 v205, v132, v125
	v_fmac_f32_e32 v206, v132, v126
	v_fmac_f32_e32 v207, v132, v127
	s_sub_u32 s62, s62, s64
	s_subb_u32 s63, s63, 0
	s_add_u32 s42, s62, 0x1000
	s_addc_u32 s43, s63, 0
	global_load_dwordx4 v[64:67], v136, s[62:63] nt
	global_load_dwordx4 v[68:71], v136, s[62:63] offset:1024 nt
	global_load_dwordx4 v[72:75], v136, s[62:63] offset:2048 nt
	global_load_dwordx4 v[76:79], v136, s[62:63] offset:3072 nt
	global_load_dwordx4 v[80:83], v136, s[42:43] nt
	global_load_dwordx4 v[84:87], v136, s[42:43] offset:1024 nt
	global_load_dwordx4 v[88:91], v136, s[42:43] offset:2048 nt
	global_load_dwordx4 v[92:95], v136, s[42:43] offset:3072 nt
	s_sub_u32 s62, s62, s64
	s_subb_u32 s63, s63, 0
	s_add_u32 s42, s62, 0x1000
	s_addc_u32 s43, s63, 0
	global_load_dwordx4 v[96:99], v136, s[62:63] nt
	global_load_dwordx4 v[100:103], v136, s[62:63] offset:1024 nt
	global_load_dwordx4 v[104:107], v136, s[62:63] offset:2048 nt
	global_load_dwordx4 v[108:111], v136, s[62:63] offset:3072 nt
	global_load_dwordx4 v[112:115], v136, s[42:43] nt
	global_load_dwordx4 v[116:119], v136, s[42:43] offset:1024 nt
	global_load_dwordx4 v[120:123], v136, s[42:43] offset:2048 nt
	global_load_dwordx4 v[124:127], v136, s[42:43] offset:3072 nt
	s_waitcnt vmcnt(31)
	v_mul_f32_e32 v244, v138, v0
	v_fmac_f32_e32 v244, v139, v1
	v_fmac_f32_e32 v244, v140, v2
	v_fmac_f32_e32 v244, v141, v3
	s_waitcnt vmcnt(30)
	v_mul_f32_e32 v245, v142, v4
	v_fmac_f32_e32 v245, v143, v5
	v_fmac_f32_e32 v245, v144, v6
	v_fmac_f32_e32 v245, v145, v7
	s_waitcnt vmcnt(29)
	v_mul_f32_e32 v246, v146, v8
	v_fmac_f32_e32 v246, v147, v9
	v_fmac_f32_e32 v246, v148, v10
	v_fmac_f32_e32 v246, v149, v11
	v_add_f32_dpp v244, v244, v244 quad_perm:[1,0,3,2] row_mask:0xf bank_mask:0xf bound_ctrl:1
	v_add_f32_dpp v245, v245, v245 quad_perm:[1,0,3,2] row_mask:0xf bank_mask:0xf bound_ctrl:1
	v_add_f32_dpp v246, v246, v246 quad_perm:[1,0,3,2] row_mask:0xf bank_mask:0xf bound_ctrl:1
	v_add_f32_dpp v244, v244, v244 quad_perm:[2,3,0,1] row_mask:0xf bank_mask:0xf bound_ctrl:1
	v_add_f32_dpp v245, v245, v245 quad_perm:[2,3,0,1] row_mask:0xf bank_mask:0xf bound_ctrl:1
	v_add_f32_dpp v246, v246, v246 quad_perm:[2,3,0,1] row_mask:0xf bank_mask:0xf bound_ctrl:1
	v_add_f32_dpp v244, v244, v244 row_ror:4 row_mask:0xf bank_mask:0xf bound_ctrl:1
	v_add_f32_dpp v245, v245, v245 row_ror:4 row_mask:0xf bank_mask:0xf bound_ctrl:1
	v_add_f32_dpp v246, v246, v246 row_ror:4 row_mask:0xf bank_mask:0xf bound_ctrl:1
	v_add_f32_dpp v244, v244, v244 row_ror:8 row_mask:0xf bank_mask:0xf bound_ctrl:1
	v_add_f32_dpp v245, v245, v245 row_ror:8 row_mask:0xf bank_mask:0xf bound_ctrl:1
	v_add_f32_dpp v246, v246, v246 row_ror:8 row_mask:0xf bank_mask:0xf bound_ctrl:1
	v_mov_b32_e32 v133, v244
	v_mov_b32_e32 v134, v245
	v_mov_b32_e32 v135, v246
	v_permlane32_swap_b32_e32 v244, v133
	v_permlane32_swap_b32_e32 v245, v134
	v_permlane32_swap_b32_e32 v246, v135
	s_waitcnt vmcnt(28)
	v_mul_f32_e32 v247, v150, v12
	v_fmac_f32_e32 v247, v151, v13
	v_fmac_f32_e32 v247, v152, v14
	v_fmac_f32_e32 v247, v153, v15
	s_waitcnt vmcnt(27)
	v_mul_f32_e32 v248, v154, v16
	v_fmac_f32_e32 v248, v155, v17
	v_fmac_f32_e32 v248, v156, v18
	v_fmac_f32_e32 v248, v157, v19
	s_waitcnt vmcnt(26)
	v_mul_f32_e32 v249, v158, v20
	v_fmac_f32_e32 v249, v159, v21
	v_fmac_f32_e32 v249, v160, v22
	v_fmac_f32_e32 v249, v161, v23
	v_add_f32_dpp v247, v247, v247 quad_perm:[1,0,3,2] row_mask:0xf bank_mask:0xf bound_ctrl:1
	v_add_f32_dpp v248, v248, v248 quad_perm:[1,0,3,2] row_mask:0xf bank_mask:0xf bound_ctrl:1
	v_add_f32_dpp v249, v249, v249 quad_perm:[1,0,3,2] row_mask:0xf bank_mask:0xf bound_ctrl:1
	v_add_f32_dpp v247, v247, v247 quad_perm:[2,3,0,1] row_mask:0xf bank_mask:0xf bound_ctrl:1
	v_add_f32_dpp v248, v248, v248 quad_perm:[2,3,0,1] row_mask:0xf bank_mask:0xf bound_ctrl:1
	v_add_f32_dpp v249, v249, v249 quad_perm:[2,3,0,1] row_mask:0xf bank_mask:0xf bound_ctrl:1
	v_add_f32_dpp v247, v247, v247 row_ror:4 row_mask:0xf bank_mask:0xf bound_ctrl:1
	v_add_f32_dpp v248, v248, v248 row_ror:4 row_mask:0xf bank_mask:0xf bound_ctrl:1
	v_add_f32_dpp v249, v249, v249 row_ror:4 row_mask:0xf bank_mask:0xf bound_ctrl:1
	v_add_f32_dpp v247, v247, v247 row_ror:8 row_mask:0xf bank_mask:0xf bound_ctrl:1
	v_add_f32_dpp v248, v248, v248 row_ror:8 row_mask:0xf bank_mask:0xf bound_ctrl:1
	v_add_f32_dpp v249, v249, v249 row_ror:8 row_mask:0xf bank_mask:0xf bound_ctrl:1
	v_mov_b32_e32 v133, v247
	v_mov_b32_e32 v134, v248
	v_mov_b32_e32 v135, v249
	v_permlane32_swap_b32_e32 v247, v133
	v_permlane32_swap_b32_e32 v248, v134
	v_permlane32_swap_b32_e32 v249, v135
	s_waitcnt vmcnt(25)
	v_mul_f32_e32 v250, v162, v24
	v_fmac_f32_e32 v250, v163, v25
	v_fmac_f32_e32 v250, v164, v26
	v_fmac_f32_e32 v250, v165, v27
	s_waitcnt vmcnt(24)
	v_mul_f32_e32 v251, v166, v28
	v_fmac_f32_e32 v251, v167, v29
	v_fmac_f32_e32 v251, v168, v30
	v_fmac_f32_e32 v251, v169, v31
	s_waitcnt vmcnt(23)
	v_mul_f32_e32 v252, v138, v32
	v_fmac_f32_e32 v252, v139, v33
	v_fmac_f32_e32 v252, v140, v34
	v_fmac_f32_e32 v252, v141, v35
	v_add_f32_dpp v250, v250, v250 quad_perm:[1,0,3,2] row_mask:0xf bank_mask:0xf bound_ctrl:1
	v_add_f32_dpp v251, v251, v251 quad_perm:[1,0,3,2] row_mask:0xf bank_mask:0xf bound_ctrl:1
	v_add_f32_dpp v252, v252, v252 quad_perm:[1,0,3,2] row_mask:0xf bank_mask:0xf bound_ctrl:1
	v_add_f32_dpp v250, v250, v250 quad_perm:[2,3,0,1] row_mask:0xf bank_mask:0xf bound_ctrl:1
	v_add_f32_dpp v251, v251, v251 quad_perm:[2,3,0,1] row_mask:0xf bank_mask:0xf bound_ctrl:1
	v_add_f32_dpp v252, v252, v252 quad_perm:[2,3,0,1] row_mask:0xf bank_mask:0xf bound_ctrl:1
	v_add_f32_dpp v250, v250, v250 row_ror:4 row_mask:0xf bank_mask:0xf bound_ctrl:1
	v_add_f32_dpp v251, v251, v251 row_ror:4 row_mask:0xf bank_mask:0xf bound_ctrl:1
	v_add_f32_dpp v252, v252, v252 row_ror:4 row_mask:0xf bank_mask:0xf bound_ctrl:1
	v_add_f32_dpp v250, v250, v250 row_ror:8 row_mask:0xf bank_mask:0xf bound_ctrl:1
	v_add_f32_dpp v251, v251, v251 row_ror:8 row_mask:0xf bank_mask:0xf bound_ctrl:1
	v_add_f32_dpp v252, v252, v252 row_ror:8 row_mask:0xf bank_mask:0xf bound_ctrl:1
	v_mov_b32_e32 v133, v250
	v_mov_b32_e32 v134, v251
	v_mov_b32_e32 v135, v252
	v_permlane32_swap_b32_e32 v250, v133
	v_permlane32_swap_b32_e32 v251, v134
	v_permlane32_swap_b32_e32 v252, v135
	s_waitcnt vmcnt(22)
	v_mul_f32_e32 v253, v142, v36
	v_fmac_f32_e32 v253, v143, v37
	v_fmac_f32_e32 v253, v144, v38
	v_fmac_f32_e32 v253, v145, v39
	s_waitcnt vmcnt(21)
	v_mul_f32_e32 v254, v146, v40
	v_fmac_f32_e32 v254, v147, v41
	v_fmac_f32_e32 v254, v148, v42
	v_fmac_f32_e32 v254, v149, v43
	s_waitcnt vmcnt(20)
	v_mul_f32_e32 v128, v150, v44
	v_fmac_f32_e32 v128, v151, v45
	v_fmac_f32_e32 v128, v152, v46
	v_fmac_f32_e32 v128, v153, v47
	v_add_f32_dpp v253, v253, v253 quad_perm:[1,0,3,2] row_mask:0xf bank_mask:0xf bound_ctrl:1
	v_add_f32_dpp v254, v254, v254 quad_perm:[1,0,3,2] row_mask:0xf bank_mask:0xf bound_ctrl:1
	v_add_f32_dpp v128, v128, v128 quad_perm:[1,0,3,2] row_mask:0xf bank_mask:0xf bound_ctrl:1
	v_add_f32_dpp v253, v253, v253 quad_perm:[2,3,0,1] row_mask:0xf bank_mask:0xf bound_ctrl:1
	v_add_f32_dpp v254, v254, v254 quad_perm:[2,3,0,1] row_mask:0xf bank_mask:0xf bound_ctrl:1
	v_add_f32_dpp v128, v128, v128 quad_perm:[2,3,0,1] row_mask:0xf bank_mask:0xf bound_ctrl:1
	v_add_f32_dpp v253, v253, v253 row_ror:4 row_mask:0xf bank_mask:0xf bound_ctrl:1
	v_add_f32_dpp v254, v254, v254 row_ror:4 row_mask:0xf bank_mask:0xf bound_ctrl:1
	v_add_f32_dpp v128, v128, v128 row_ror:4 row_mask:0xf bank_mask:0xf bound_ctrl:1
	v_add_f32_dpp v253, v253, v253 row_ror:8 row_mask:0xf bank_mask:0xf bound_ctrl:1
	v_add_f32_dpp v254, v254, v254 row_ror:8 row_mask:0xf bank_mask:0xf bound_ctrl:1
	v_add_f32_dpp v128, v128, v128 row_ror:8 row_mask:0xf bank_mask:0xf bound_ctrl:1
	v_mov_b32_e32 v133, v253
	v_mov_b32_e32 v134, v254
	v_mov_b32_e32 v135, v128
	v_permlane32_swap_b32_e32 v253, v133
	v_permlane32_swap_b32_e32 v254, v134
	v_permlane32_swap_b32_e32 v128, v135
	s_waitcnt vmcnt(19)
	v_mul_f32_e32 v129, v154, v48
	v_fmac_f32_e32 v129, v155, v49
	v_fmac_f32_e32 v129, v156, v50
	v_fmac_f32_e32 v129, v157, v51
	s_waitcnt vmcnt(18)
	v_mul_f32_e32 v130, v158, v52
	v_fmac_f32_e32 v130, v159, v53
	v_fmac_f32_e32 v130, v160, v54
	v_fmac_f32_e32 v130, v161, v55
	s_waitcnt vmcnt(17)
	v_mul_f32_e32 v131, v162, v56
	v_fmac_f32_e32 v131, v163, v57
	v_fmac_f32_e32 v131, v164, v58
	v_fmac_f32_e32 v131, v165, v59
	v_add_f32_dpp v129, v129, v129 quad_perm:[1,0,3,2] row_mask:0xf bank_mask:0xf bound_ctrl:1
	v_add_f32_dpp v130, v130, v130 quad_perm:[1,0,3,2] row_mask:0xf bank_mask:0xf bound_ctrl:1
	v_add_f32_dpp v131, v131, v131 quad_perm:[1,0,3,2] row_mask:0xf bank_mask:0xf bound_ctrl:1
	v_add_f32_dpp v129, v129, v129 quad_perm:[2,3,0,1] row_mask:0xf bank_mask:0xf bound_ctrl:1
	v_add_f32_dpp v130, v130, v130 quad_perm:[2,3,0,1] row_mask:0xf bank_mask:0xf bound_ctrl:1
	v_add_f32_dpp v131, v131, v131 quad_perm:[2,3,0,1] row_mask:0xf bank_mask:0xf bound_ctrl:1
	v_add_f32_dpp v129, v129, v129 row_ror:4 row_mask:0xf bank_mask:0xf bound_ctrl:1
	v_add_f32_dpp v130, v130, v130 row_ror:4 row_mask:0xf bank_mask:0xf bound_ctrl:1
	v_add_f32_dpp v131, v131, v131 row_ror:4 row_mask:0xf bank_mask:0xf bound_ctrl:1
	v_add_f32_dpp v129, v129, v129 row_ror:8 row_mask:0xf bank_mask:0xf bound_ctrl:1
	v_add_f32_dpp v130, v130, v130 row_ror:8 row_mask:0xf bank_mask:0xf bound_ctrl:1
	v_add_f32_dpp v131, v131, v131 row_ror:8 row_mask:0xf bank_mask:0xf bound_ctrl:1
	v_mov_b32_e32 v133, v129
	v_mov_b32_e32 v134, v130
	v_mov_b32_e32 v135, v131
	v_permlane32_swap_b32_e32 v129, v133
	v_permlane32_swap_b32_e32 v130, v134
	v_permlane32_swap_b32_e32 v131, v135
	s_waitcnt vmcnt(16)
	v_mul_f32_e32 v132, v166, v60
	v_fmac_f32_e32 v132, v167, v61
	v_fmac_f32_e32 v132, v168, v62
	v_fmac_f32_e32 v132, v169, v63
	s_nop 1
	v_add_f32_dpp v132, v132, v132 quad_perm:[1,0,3,2] row_mask:0xf bank_mask:0xf bound_ctrl:1
	s_nop 1
	v_add_f32_dpp v132, v132, v132 quad_perm:[2,3,0,1] row_mask:0xf bank_mask:0xf bound_ctrl:1
	s_nop 1
	v_add_f32_dpp v132, v132, v132 row_ror:4 row_mask:0xf bank_mask:0xf bound_ctrl:1
	s_nop 1
	v_add_f32_dpp v132, v132, v132 row_ror:8 row_mask:0xf bank_mask:0xf bound_ctrl:1
	s_nop 1
	v_mov_b32_e32 v133, v132
	s_nop 1
	v_permlane32_swap_b32_e32 v132, v133
	v_max3_f32 v228, v244, v252, v208
	v_sub_f32_e32 v227, v208, v228
	v_sub_f32_e32 v244, v244, v228
	v_sub_f32_e32 v252, v252, v228
	v_mul_f32_e32 v227, 0x3fb8aa3b, v227
	v_mul_f32_e32 v244, 0x3fb8aa3b, v244
	v_mul_f32_e32 v252, 0x3fb8aa3b, v252
	v_exp_f32_e32 v227, v227
	v_exp_f32_e32 v244, v244
	v_exp_f32_e32 v252, v252
	v_mov_b32_e32 v208, v228
	v_fma_f32 v219, v219, v227, v244
	v_add_f32_e32 v219, v219, v252
	v_mul_f32_e32 v172, v172, v227
	v_mul_f32_e32 v173, v173, v227
	v_mul_f32_e32 v174, v174, v227
	v_mul_f32_e32 v175, v175, v227
	v_fmac_f32_e32 v172, v244, v0
	v_fmac_f32_e32 v173, v244, v1
	v_fmac_f32_e32 v174, v244, v2
	v_fmac_f32_e32 v175, v244, v3
	v_fmac_f32_e32 v172, v252, v32
	v_fmac_f32_e32 v173, v252, v33
	v_fmac_f32_e32 v174, v252, v34
	v_fmac_f32_e32 v175, v252, v35
	v_max3_f32 v228, v245, v253, v209
	v_sub_f32_e32 v227, v209, v228
	v_sub_f32_e32 v245, v245, v228
	v_sub_f32_e32 v253, v253, v228
	v_mul_f32_e32 v227, 0x3fb8aa3b, v227
	v_mul_f32_e32 v245, 0x3fb8aa3b, v245
	v_mul_f32_e32 v253, 0x3fb8aa3b, v253
	v_exp_f32_e32 v227, v227
	v_exp_f32_e32 v245, v245
	v_exp_f32_e32 v253, v253
	v_mov_b32_e32 v209, v228
	v_fma_f32 v220, v220, v227, v245
	v_add_f32_e32 v220, v220, v253
	v_mul_f32_e32 v176, v176, v227
	v_mul_f32_e32 v177, v177, v227
	v_mul_f32_e32 v178, v178, v227
	v_mul_f32_e32 v179, v179, v227
	v_fmac_f32_e32 v176, v245, v4
	v_fmac_f32_e32 v177, v245, v5
	v_fmac_f32_e32 v178, v245, v6
	v_fmac_f32_e32 v179, v245, v7
	v_fmac_f32_e32 v176, v253, v36
	v_fmac_f32_e32 v177, v253, v37
	v_fmac_f32_e32 v178, v253, v38
	v_fmac_f32_e32 v179, v253, v39
	v_max3_f32 v228, v246, v254, v210
	v_sub_f32_e32 v227, v210, v228
	v_sub_f32_e32 v246, v246, v228
	v_sub_f32_e32 v254, v254, v228
	v_mul_f32_e32 v227, 0x3fb8aa3b, v227
	v_mul_f32_e32 v246, 0x3fb8aa3b, v246
	v_mul_f32_e32 v254, 0x3fb8aa3b, v254
	v_exp_f32_e32 v227, v227
	v_exp_f32_e32 v246, v246
	v_exp_f32_e32 v254, v254
	v_mov_b32_e32 v210, v228
	v_fma_f32 v221, v221, v227, v246
	v_add_f32_e32 v221, v221, v254
	v_mul_f32_e32 v180, v180, v227
	v_mul_f32_e32 v181, v181, v227
	v_mul_f32_e32 v182, v182, v227
	v_mul_f32_e32 v183, v183, v227
	v_fmac_f32_e32 v180, v246, v8
	v_fmac_f32_e32 v181, v246, v9
	v_fmac_f32_e32 v182, v246, v10
	v_fmac_f32_e32 v183, v246, v11
	v_fmac_f32_e32 v180, v254, v40
	v_fmac_f32_e32 v181, v254, v41
	v_fmac_f32_e32 v182, v254, v42
	v_fmac_f32_e32 v183, v254, v43
	v_max3_f32 v228, v247, v128, v212
	v_sub_f32_e32 v227, v212, v228
	v_sub_f32_e32 v247, v247, v228
	v_sub_f32_e32 v128, v128, v228
	v_mul_f32_e32 v227, 0x3fb8aa3b, v227
	v_mul_f32_e32 v247, 0x3fb8aa3b, v247
	v_mul_f32_e32 v128, 0x3fb8aa3b, v128
	v_exp_f32_e32 v227, v227
	v_exp_f32_e32 v247, v247
	v_exp_f32_e32 v128, v128
	v_mov_b32_e32 v212, v228
	v_fma_f32 v222, v222, v227, v247
	v_add_f32_e32 v222, v222, v128
	v_mul_f32_e32 v184, v184, v227
	v_mul_f32_e32 v185, v185, v227
	v_mul_f32_e32 v186, v186, v227
	v_mul_f32_e32 v187, v187, v227
	v_fmac_f32_e32 v184, v247, v12
	v_fmac_f32_e32 v185, v247, v13
	v_fmac_f32_e32 v186, v247, v14
	v_fmac_f32_e32 v187, v247, v15
	v_fmac_f32_e32 v184, v128, v44
	v_fmac_f32_e32 v185, v128, v45
	v_fmac_f32_e32 v186, v128, v46
	v_fmac_f32_e32 v187, v128, v47
	v_max3_f32 v228, v248, v129, v214
	v_sub_f32_e32 v227, v214, v228
	v_sub_f32_e32 v248, v248, v228
	v_sub_f32_e32 v129, v129, v228
	v_mul_f32_e32 v227, 0x3fb8aa3b, v227
	v_mul_f32_e32 v248, 0x3fb8aa3b, v248
	v_mul_f32_e32 v129, 0x3fb8aa3b, v129
	v_exp_f32_e32 v227, v227
	v_exp_f32_e32 v248, v248
	v_exp_f32_e32 v129, v129
	v_mov_b32_e32 v214, v228
	v_fma_f32 v223, v223, v227, v248
	v_add_f32_e32 v223, v223, v129
	v_mul_f32_e32 v188, v188, v227
	v_mul_f32_e32 v189, v189, v227
	v_mul_f32_e32 v190, v190, v227
	v_mul_f32_e32 v191, v191, v227
	v_fmac_f32_e32 v188, v248, v16
	v_fmac_f32_e32 v189, v248, v17
	v_fmac_f32_e32 v190, v248, v18
	v_fmac_f32_e32 v191, v248, v19
	v_fmac_f32_e32 v188, v129, v48
	v_fmac_f32_e32 v189, v129, v49
	v_fmac_f32_e32 v190, v129, v50
	v_fmac_f32_e32 v191, v129, v51
	v_max3_f32 v228, v249, v130, v216
	v_sub_f32_e32 v227, v216, v228
	v_sub_f32_e32 v249, v249, v228
	v_sub_f32_e32 v130, v130, v228
	v_mul_f32_e32 v227, 0x3fb8aa3b, v227
	v_mul_f32_e32 v249, 0x3fb8aa3b, v249
	v_mul_f32_e32 v130, 0x3fb8aa3b, v130
	v_exp_f32_e32 v227, v227
	v_exp_f32_e32 v249, v249
	v_exp_f32_e32 v130, v130
	v_mov_b32_e32 v216, v228
	v_fma_f32 v224, v224, v227, v249
	v_add_f32_e32 v224, v224, v130
	v_mul_f32_e32 v196, v196, v227
	v_mul_f32_e32 v197, v197, v227
	v_mul_f32_e32 v198, v198, v227
	v_mul_f32_e32 v199, v199, v227
	v_fmac_f32_e32 v196, v249, v20
	v_fmac_f32_e32 v197, v249, v21
	v_fmac_f32_e32 v198, v249, v22
	v_fmac_f32_e32 v199, v249, v23
	v_fmac_f32_e32 v196, v130, v52
	v_fmac_f32_e32 v197, v130, v53
	v_fmac_f32_e32 v198, v130, v54
	v_fmac_f32_e32 v199, v130, v55
	v_max3_f32 v228, v250, v131, v217
	v_sub_f32_e32 v227, v217, v228
	v_sub_f32_e32 v250, v250, v228
	v_sub_f32_e32 v131, v131, v228
	v_mul_f32_e32 v227, 0x3fb8aa3b, v227
	v_mul_f32_e32 v250, 0x3fb8aa3b, v250
	v_mul_f32_e32 v131, 0x3fb8aa3b, v131
	v_exp_f32_e32 v227, v227
	v_exp_f32_e32 v250, v250
	v_exp_f32_e32 v131, v131
	v_mov_b32_e32 v217, v228
	v_fma_f32 v225, v225, v227, v250
	v_add_f32_e32 v225, v225, v131
	v_mul_f32_e32 v200, v200, v227
	v_mul_f32_e32 v201, v201, v227
	v_mul_f32_e32 v202, v202, v227
	v_mul_f32_e32 v203, v203, v227
	v_fmac_f32_e32 v200, v250, v24
	v_fmac_f32_e32 v201, v250, v25
	v_fmac_f32_e32 v202, v250, v26
	v_fmac_f32_e32 v203, v250, v27
	v_fmac_f32_e32 v200, v131, v56
	v_fmac_f32_e32 v201, v131, v57
	v_fmac_f32_e32 v202, v131, v58
	v_fmac_f32_e32 v203, v131, v59
	v_max3_f32 v228, v251, v132, v218
	v_sub_f32_e32 v227, v218, v228
	v_sub_f32_e32 v251, v251, v228
	v_sub_f32_e32 v132, v132, v228
	v_mul_f32_e32 v227, 0x3fb8aa3b, v227
	v_mul_f32_e32 v251, 0x3fb8aa3b, v251
	v_mul_f32_e32 v132, 0x3fb8aa3b, v132
	v_exp_f32_e32 v227, v227
	v_exp_f32_e32 v251, v251
	v_exp_f32_e32 v132, v132
	v_mov_b32_e32 v218, v228
	v_fma_f32 v226, v226, v227, v251
	v_add_f32_e32 v226, v226, v132
	v_mul_f32_e32 v204, v204, v227
	v_mul_f32_e32 v205, v205, v227
	v_mul_f32_e32 v206, v206, v227
	v_mul_f32_e32 v207, v207, v227
	v_fmac_f32_e32 v204, v251, v28
	v_fmac_f32_e32 v205, v251, v29
	v_fmac_f32_e32 v206, v251, v30
	v_fmac_f32_e32 v207, v251, v31
	v_fmac_f32_e32 v204, v132, v60
	v_fmac_f32_e32 v205, v132, v61
	v_fmac_f32_e32 v206, v132, v62
	v_fmac_f32_e32 v207, v132, v63
	s_sub_u32 s62, s62, s64
	s_subb_u32 s63, s63, 0
	s_add_u32 s42, s62, 0x1000
	s_addc_u32 s43, s63, 0
	global_load_dwordx4 v[0:3], v136, s[62:63] nt
	global_load_dwordx4 v[4:7], v136, s[62:63] offset:1024 nt
	global_load_dwordx4 v[8:11], v136, s[62:63] offset:2048 nt
	global_load_dwordx4 v[12:15], v136, s[62:63] offset:3072 nt
	global_load_dwordx4 v[16:19], v136, s[42:43] nt
	global_load_dwordx4 v[20:23], v136, s[42:43] offset:1024 nt
	global_load_dwordx4 v[24:27], v136, s[42:43] offset:2048 nt
	global_load_dwordx4 v[28:31], v136, s[42:43] offset:3072 nt
	s_sub_u32 s62, s62, s64
	s_subb_u32 s63, s63, 0
	s_add_u32 s42, s62, 0x1000
	s_addc_u32 s43, s63, 0
	global_load_dwordx4 v[32:35], v136, s[62:63] nt
	global_load_dwordx4 v[36:39], v136, s[62:63] offset:1024 nt
	global_load_dwordx4 v[40:43], v136, s[62:63] offset:2048 nt
	global_load_dwordx4 v[44:47], v136, s[62:63] offset:3072 nt
	global_load_dwordx4 v[48:51], v136, s[42:43] nt
	global_load_dwordx4 v[52:55], v136, s[42:43] offset:1024 nt
	global_load_dwordx4 v[56:59], v136, s[42:43] offset:2048 nt
	global_load_dwordx4 v[60:63], v136, s[42:43] offset:3072 nt
	s_waitcnt vmcnt(31)
	v_mul_f32_e32 v244, v138, v64
	v_fmac_f32_e32 v244, v139, v65
	v_fmac_f32_e32 v244, v140, v66
	v_fmac_f32_e32 v244, v141, v67
	s_waitcnt vmcnt(30)
	v_mul_f32_e32 v245, v142, v68
	v_fmac_f32_e32 v245, v143, v69
	v_fmac_f32_e32 v245, v144, v70
	v_fmac_f32_e32 v245, v145, v71
	s_waitcnt vmcnt(29)
	v_mul_f32_e32 v246, v146, v72
	v_fmac_f32_e32 v246, v147, v73
	v_fmac_f32_e32 v246, v148, v74
	v_fmac_f32_e32 v246, v149, v75
	v_add_f32_dpp v244, v244, v244 quad_perm:[1,0,3,2] row_mask:0xf bank_mask:0xf bound_ctrl:1
	v_add_f32_dpp v245, v245, v245 quad_perm:[1,0,3,2] row_mask:0xf bank_mask:0xf bound_ctrl:1
	v_add_f32_dpp v246, v246, v246 quad_perm:[1,0,3,2] row_mask:0xf bank_mask:0xf bound_ctrl:1
	v_add_f32_dpp v244, v244, v244 quad_perm:[2,3,0,1] row_mask:0xf bank_mask:0xf bound_ctrl:1
	v_add_f32_dpp v245, v245, v245 quad_perm:[2,3,0,1] row_mask:0xf bank_mask:0xf bound_ctrl:1
	v_add_f32_dpp v246, v246, v246 quad_perm:[2,3,0,1] row_mask:0xf bank_mask:0xf bound_ctrl:1
	v_add_f32_dpp v244, v244, v244 row_ror:4 row_mask:0xf bank_mask:0xf bound_ctrl:1
	v_add_f32_dpp v245, v245, v245 row_ror:4 row_mask:0xf bank_mask:0xf bound_ctrl:1
	v_add_f32_dpp v246, v246, v246 row_ror:4 row_mask:0xf bank_mask:0xf bound_ctrl:1
	v_add_f32_dpp v244, v244, v244 row_ror:8 row_mask:0xf bank_mask:0xf bound_ctrl:1
	v_add_f32_dpp v245, v245, v245 row_ror:8 row_mask:0xf bank_mask:0xf bound_ctrl:1
	v_add_f32_dpp v246, v246, v246 row_ror:8 row_mask:0xf bank_mask:0xf bound_ctrl:1
	v_mov_b32_e32 v133, v244
	v_mov_b32_e32 v134, v245
	v_mov_b32_e32 v135, v246
	v_permlane32_swap_b32_e32 v244, v133
	v_permlane32_swap_b32_e32 v245, v134
	v_permlane32_swap_b32_e32 v246, v135
	s_waitcnt vmcnt(28)
	v_mul_f32_e32 v247, v150, v76
	v_fmac_f32_e32 v247, v151, v77
	v_fmac_f32_e32 v247, v152, v78
	v_fmac_f32_e32 v247, v153, v79
	s_waitcnt vmcnt(27)
	v_mul_f32_e32 v248, v154, v80
	v_fmac_f32_e32 v248, v155, v81
	v_fmac_f32_e32 v248, v156, v82
	v_fmac_f32_e32 v248, v157, v83
	s_waitcnt vmcnt(26)
	v_mul_f32_e32 v249, v158, v84
	v_fmac_f32_e32 v249, v159, v85
	v_fmac_f32_e32 v249, v160, v86
	v_fmac_f32_e32 v249, v161, v87
	v_add_f32_dpp v247, v247, v247 quad_perm:[1,0,3,2] row_mask:0xf bank_mask:0xf bound_ctrl:1
	v_add_f32_dpp v248, v248, v248 quad_perm:[1,0,3,2] row_mask:0xf bank_mask:0xf bound_ctrl:1
	v_add_f32_dpp v249, v249, v249 quad_perm:[1,0,3,2] row_mask:0xf bank_mask:0xf bound_ctrl:1
	v_add_f32_dpp v247, v247, v247 quad_perm:[2,3,0,1] row_mask:0xf bank_mask:0xf bound_ctrl:1
	v_add_f32_dpp v248, v248, v248 quad_perm:[2,3,0,1] row_mask:0xf bank_mask:0xf bound_ctrl:1
	v_add_f32_dpp v249, v249, v249 quad_perm:[2,3,0,1] row_mask:0xf bank_mask:0xf bound_ctrl:1
	v_add_f32_dpp v247, v247, v247 row_ror:4 row_mask:0xf bank_mask:0xf bound_ctrl:1
	v_add_f32_dpp v248, v248, v248 row_ror:4 row_mask:0xf bank_mask:0xf bound_ctrl:1
	v_add_f32_dpp v249, v249, v249 row_ror:4 row_mask:0xf bank_mask:0xf bound_ctrl:1
	v_add_f32_dpp v247, v247, v247 row_ror:8 row_mask:0xf bank_mask:0xf bound_ctrl:1
	v_add_f32_dpp v248, v248, v248 row_ror:8 row_mask:0xf bank_mask:0xf bound_ctrl:1
	v_add_f32_dpp v249, v249, v249 row_ror:8 row_mask:0xf bank_mask:0xf bound_ctrl:1
	v_mov_b32_e32 v133, v247
	v_mov_b32_e32 v134, v248
	v_mov_b32_e32 v135, v249
	v_permlane32_swap_b32_e32 v247, v133
	v_permlane32_swap_b32_e32 v248, v134
	v_permlane32_swap_b32_e32 v249, v135
	s_waitcnt vmcnt(25)
	v_mul_f32_e32 v250, v162, v88
	v_fmac_f32_e32 v250, v163, v89
	v_fmac_f32_e32 v250, v164, v90
	v_fmac_f32_e32 v250, v165, v91
	s_waitcnt vmcnt(24)
	v_mul_f32_e32 v251, v166, v92
	v_fmac_f32_e32 v251, v167, v93
	v_fmac_f32_e32 v251, v168, v94
	v_fmac_f32_e32 v251, v169, v95
	s_waitcnt vmcnt(23)
	v_mul_f32_e32 v252, v138, v96
	v_fmac_f32_e32 v252, v139, v97
	v_fmac_f32_e32 v252, v140, v98
	v_fmac_f32_e32 v252, v141, v99
	v_add_f32_dpp v250, v250, v250 quad_perm:[1,0,3,2] row_mask:0xf bank_mask:0xf bound_ctrl:1
	v_add_f32_dpp v251, v251, v251 quad_perm:[1,0,3,2] row_mask:0xf bank_mask:0xf bound_ctrl:1
	v_add_f32_dpp v252, v252, v252 quad_perm:[1,0,3,2] row_mask:0xf bank_mask:0xf bound_ctrl:1
	v_add_f32_dpp v250, v250, v250 quad_perm:[2,3,0,1] row_mask:0xf bank_mask:0xf bound_ctrl:1
	v_add_f32_dpp v251, v251, v251 quad_perm:[2,3,0,1] row_mask:0xf bank_mask:0xf bound_ctrl:1
	v_add_f32_dpp v252, v252, v252 quad_perm:[2,3,0,1] row_mask:0xf bank_mask:0xf bound_ctrl:1
	v_add_f32_dpp v250, v250, v250 row_ror:4 row_mask:0xf bank_mask:0xf bound_ctrl:1
	v_add_f32_dpp v251, v251, v251 row_ror:4 row_mask:0xf bank_mask:0xf bound_ctrl:1
	v_add_f32_dpp v252, v252, v252 row_ror:4 row_mask:0xf bank_mask:0xf bound_ctrl:1
	v_add_f32_dpp v250, v250, v250 row_ror:8 row_mask:0xf bank_mask:0xf bound_ctrl:1
	v_add_f32_dpp v251, v251, v251 row_ror:8 row_mask:0xf bank_mask:0xf bound_ctrl:1
	v_add_f32_dpp v252, v252, v252 row_ror:8 row_mask:0xf bank_mask:0xf bound_ctrl:1
	v_mov_b32_e32 v133, v250
	v_mov_b32_e32 v134, v251
	v_mov_b32_e32 v135, v252
	v_permlane32_swap_b32_e32 v250, v133
	v_permlane32_swap_b32_e32 v251, v134
	v_permlane32_swap_b32_e32 v252, v135
	s_waitcnt vmcnt(22)
	v_mul_f32_e32 v253, v142, v100
	v_fmac_f32_e32 v253, v143, v101
	v_fmac_f32_e32 v253, v144, v102
	v_fmac_f32_e32 v253, v145, v103
	s_waitcnt vmcnt(21)
	v_mul_f32_e32 v254, v146, v104
	v_fmac_f32_e32 v254, v147, v105
	v_fmac_f32_e32 v254, v148, v106
	v_fmac_f32_e32 v254, v149, v107
	s_waitcnt vmcnt(20)
	v_mul_f32_e32 v128, v150, v108
	v_fmac_f32_e32 v128, v151, v109
	v_fmac_f32_e32 v128, v152, v110
	v_fmac_f32_e32 v128, v153, v111
	v_add_f32_dpp v253, v253, v253 quad_perm:[1,0,3,2] row_mask:0xf bank_mask:0xf bound_ctrl:1
	v_add_f32_dpp v254, v254, v254 quad_perm:[1,0,3,2] row_mask:0xf bank_mask:0xf bound_ctrl:1
	v_add_f32_dpp v128, v128, v128 quad_perm:[1,0,3,2] row_mask:0xf bank_mask:0xf bound_ctrl:1
	v_add_f32_dpp v253, v253, v253 quad_perm:[2,3,0,1] row_mask:0xf bank_mask:0xf bound_ctrl:1
	v_add_f32_dpp v254, v254, v254 quad_perm:[2,3,0,1] row_mask:0xf bank_mask:0xf bound_ctrl:1
	v_add_f32_dpp v128, v128, v128 quad_perm:[2,3,0,1] row_mask:0xf bank_mask:0xf bound_ctrl:1
	v_add_f32_dpp v253, v253, v253 row_ror:4 row_mask:0xf bank_mask:0xf bound_ctrl:1
	v_add_f32_dpp v254, v254, v254 row_ror:4 row_mask:0xf bank_mask:0xf bound_ctrl:1
	v_add_f32_dpp v128, v128, v128 row_ror:4 row_mask:0xf bank_mask:0xf bound_ctrl:1
	v_add_f32_dpp v253, v253, v253 row_ror:8 row_mask:0xf bank_mask:0xf bound_ctrl:1
	v_add_f32_dpp v254, v254, v254 row_ror:8 row_mask:0xf bank_mask:0xf bound_ctrl:1
	v_add_f32_dpp v128, v128, v128 row_ror:8 row_mask:0xf bank_mask:0xf bound_ctrl:1
	v_mov_b32_e32 v133, v253
	v_mov_b32_e32 v134, v254
	v_mov_b32_e32 v135, v128
	v_permlane32_swap_b32_e32 v253, v133
	v_permlane32_swap_b32_e32 v254, v134
	v_permlane32_swap_b32_e32 v128, v135
	s_waitcnt vmcnt(19)
	v_mul_f32_e32 v129, v154, v112
	v_fmac_f32_e32 v129, v155, v113
	v_fmac_f32_e32 v129, v156, v114
	v_fmac_f32_e32 v129, v157, v115
	s_waitcnt vmcnt(18)
	v_mul_f32_e32 v130, v158, v116
	v_fmac_f32_e32 v130, v159, v117
	v_fmac_f32_e32 v130, v160, v118
	v_fmac_f32_e32 v130, v161, v119
	s_waitcnt vmcnt(17)
	v_mul_f32_e32 v131, v162, v120
	v_fmac_f32_e32 v131, v163, v121
	v_fmac_f32_e32 v131, v164, v122
	v_fmac_f32_e32 v131, v165, v123
	v_add_f32_dpp v129, v129, v129 quad_perm:[1,0,3,2] row_mask:0xf bank_mask:0xf bound_ctrl:1
	v_add_f32_dpp v130, v130, v130 quad_perm:[1,0,3,2] row_mask:0xf bank_mask:0xf bound_ctrl:1
	v_add_f32_dpp v131, v131, v131 quad_perm:[1,0,3,2] row_mask:0xf bank_mask:0xf bound_ctrl:1
	v_add_f32_dpp v129, v129, v129 quad_perm:[2,3,0,1] row_mask:0xf bank_mask:0xf bound_ctrl:1
	v_add_f32_dpp v130, v130, v130 quad_perm:[2,3,0,1] row_mask:0xf bank_mask:0xf bound_ctrl:1
	v_add_f32_dpp v131, v131, v131 quad_perm:[2,3,0,1] row_mask:0xf bank_mask:0xf bound_ctrl:1
	v_add_f32_dpp v129, v129, v129 row_ror:4 row_mask:0xf bank_mask:0xf bound_ctrl:1
	v_add_f32_dpp v130, v130, v130 row_ror:4 row_mask:0xf bank_mask:0xf bound_ctrl:1
	v_add_f32_dpp v131, v131, v131 row_ror:4 row_mask:0xf bank_mask:0xf bound_ctrl:1
	v_add_f32_dpp v129, v129, v129 row_ror:8 row_mask:0xf bank_mask:0xf bound_ctrl:1
	v_add_f32_dpp v130, v130, v130 row_ror:8 row_mask:0xf bank_mask:0xf bound_ctrl:1
	v_add_f32_dpp v131, v131, v131 row_ror:8 row_mask:0xf bank_mask:0xf bound_ctrl:1
	v_mov_b32_e32 v133, v129
	v_mov_b32_e32 v134, v130
	v_mov_b32_e32 v135, v131
	v_permlane32_swap_b32_e32 v129, v133
	v_permlane32_swap_b32_e32 v130, v134
	v_permlane32_swap_b32_e32 v131, v135
	s_waitcnt vmcnt(16)
	v_mul_f32_e32 v132, v166, v124
	v_fmac_f32_e32 v132, v167, v125
	v_fmac_f32_e32 v132, v168, v126
	v_fmac_f32_e32 v132, v169, v127
	s_nop 1
	v_add_f32_dpp v132, v132, v132 quad_perm:[1,0,3,2] row_mask:0xf bank_mask:0xf bound_ctrl:1
	s_nop 1
	v_add_f32_dpp v132, v132, v132 quad_perm:[2,3,0,1] row_mask:0xf bank_mask:0xf bound_ctrl:1
	s_nop 1
	v_add_f32_dpp v132, v132, v132 row_ror:4 row_mask:0xf bank_mask:0xf bound_ctrl:1
	s_nop 1
	v_add_f32_dpp v132, v132, v132 row_ror:8 row_mask:0xf bank_mask:0xf bound_ctrl:1
	s_nop 1
	v_mov_b32_e32 v133, v132
	s_nop 1
	v_permlane32_swap_b32_e32 v132, v133
	v_max3_f32 v228, v244, v252, v208
	v_sub_f32_e32 v227, v208, v228
	v_sub_f32_e32 v244, v244, v228
	v_sub_f32_e32 v252, v252, v228
	v_mul_f32_e32 v227, 0x3fb8aa3b, v227
	v_mul_f32_e32 v244, 0x3fb8aa3b, v244
	v_mul_f32_e32 v252, 0x3fb8aa3b, v252
	v_exp_f32_e32 v227, v227
	v_exp_f32_e32 v244, v244
	v_exp_f32_e32 v252, v252
	v_mov_b32_e32 v208, v228
	v_fma_f32 v219, v219, v227, v244
	v_add_f32_e32 v219, v219, v252
	v_mul_f32_e32 v172, v172, v227
	v_mul_f32_e32 v173, v173, v227
	v_mul_f32_e32 v174, v174, v227
	v_mul_f32_e32 v175, v175, v227
	v_fmac_f32_e32 v172, v244, v64
	v_fmac_f32_e32 v173, v244, v65
	v_fmac_f32_e32 v174, v244, v66
	v_fmac_f32_e32 v175, v244, v67
	v_fmac_f32_e32 v172, v252, v96
	v_fmac_f32_e32 v173, v252, v97
	v_fmac_f32_e32 v174, v252, v98
	v_fmac_f32_e32 v175, v252, v99
	v_max3_f32 v228, v245, v253, v209
	v_sub_f32_e32 v227, v209, v228
	v_sub_f32_e32 v245, v245, v228
	v_sub_f32_e32 v253, v253, v228
	v_mul_f32_e32 v227, 0x3fb8aa3b, v227
	v_mul_f32_e32 v245, 0x3fb8aa3b, v245
	v_mul_f32_e32 v253, 0x3fb8aa3b, v253
	v_exp_f32_e32 v227, v227
	v_exp_f32_e32 v245, v245
	v_exp_f32_e32 v253, v253
	v_mov_b32_e32 v209, v228
	v_fma_f32 v220, v220, v227, v245
	v_add_f32_e32 v220, v220, v253
	v_mul_f32_e32 v176, v176, v227
	v_mul_f32_e32 v177, v177, v227
	v_mul_f32_e32 v178, v178, v227
	v_mul_f32_e32 v179, v179, v227
	v_fmac_f32_e32 v176, v245, v68
	v_fmac_f32_e32 v177, v245, v69
	v_fmac_f32_e32 v178, v245, v70
	v_fmac_f32_e32 v179, v245, v71
	v_fmac_f32_e32 v176, v253, v100
	v_fmac_f32_e32 v177, v253, v101
	v_fmac_f32_e32 v178, v253, v102
	v_fmac_f32_e32 v179, v253, v103
	v_max3_f32 v228, v246, v254, v210
	v_sub_f32_e32 v227, v210, v228
	v_sub_f32_e32 v246, v246, v228
	v_sub_f32_e32 v254, v254, v228
	v_mul_f32_e32 v227, 0x3fb8aa3b, v227
	v_mul_f32_e32 v246, 0x3fb8aa3b, v246
	v_mul_f32_e32 v254, 0x3fb8aa3b, v254
	v_exp_f32_e32 v227, v227
	v_exp_f32_e32 v246, v246
	v_exp_f32_e32 v254, v254
	v_mov_b32_e32 v210, v228
	v_fma_f32 v221, v221, v227, v246
	v_add_f32_e32 v221, v221, v254
	v_mul_f32_e32 v180, v180, v227
	v_mul_f32_e32 v181, v181, v227
	v_mul_f32_e32 v182, v182, v227
	v_mul_f32_e32 v183, v183, v227
	v_fmac_f32_e32 v180, v246, v72
	v_fmac_f32_e32 v181, v246, v73
	v_fmac_f32_e32 v182, v246, v74
	v_fmac_f32_e32 v183, v246, v75
	v_fmac_f32_e32 v180, v254, v104
	v_fmac_f32_e32 v181, v254, v105
	v_fmac_f32_e32 v182, v254, v106
	v_fmac_f32_e32 v183, v254, v107
	v_max3_f32 v228, v247, v128, v212
	v_sub_f32_e32 v227, v212, v228
	v_sub_f32_e32 v247, v247, v228
	v_sub_f32_e32 v128, v128, v228
	v_mul_f32_e32 v227, 0x3fb8aa3b, v227
	v_mul_f32_e32 v247, 0x3fb8aa3b, v247
	v_mul_f32_e32 v128, 0x3fb8aa3b, v128
	v_exp_f32_e32 v227, v227
	v_exp_f32_e32 v247, v247
	v_exp_f32_e32 v128, v128
	v_mov_b32_e32 v212, v228
	v_fma_f32 v222, v222, v227, v247
	v_add_f32_e32 v222, v222, v128
	v_mul_f32_e32 v184, v184, v227
	v_mul_f32_e32 v185, v185, v227
	v_mul_f32_e32 v186, v186, v227
	v_mul_f32_e32 v187, v187, v227
	v_fmac_f32_e32 v184, v247, v76
	v_fmac_f32_e32 v185, v247, v77
	v_fmac_f32_e32 v186, v247, v78
	v_fmac_f32_e32 v187, v247, v79
	v_fmac_f32_e32 v184, v128, v108
	v_fmac_f32_e32 v185, v128, v109
	v_fmac_f32_e32 v186, v128, v110
	v_fmac_f32_e32 v187, v128, v111
	v_max3_f32 v228, v248, v129, v214
	v_sub_f32_e32 v227, v214, v228
	v_sub_f32_e32 v248, v248, v228
	v_sub_f32_e32 v129, v129, v228
	v_mul_f32_e32 v227, 0x3fb8aa3b, v227
	v_mul_f32_e32 v248, 0x3fb8aa3b, v248
	v_mul_f32_e32 v129, 0x3fb8aa3b, v129
	v_exp_f32_e32 v227, v227
	v_exp_f32_e32 v248, v248
	v_exp_f32_e32 v129, v129
	v_mov_b32_e32 v214, v228
	v_fma_f32 v223, v223, v227, v248
	v_add_f32_e32 v223, v223, v129
	v_mul_f32_e32 v188, v188, v227
	v_mul_f32_e32 v189, v189, v227
	v_mul_f32_e32 v190, v190, v227
	v_mul_f32_e32 v191, v191, v227
	v_fmac_f32_e32 v188, v248, v80
	v_fmac_f32_e32 v189, v248, v81
	v_fmac_f32_e32 v190, v248, v82
	v_fmac_f32_e32 v191, v248, v83
	v_fmac_f32_e32 v188, v129, v112
	v_fmac_f32_e32 v189, v129, v113
	v_fmac_f32_e32 v190, v129, v114
	v_fmac_f32_e32 v191, v129, v115
	v_max3_f32 v228, v249, v130, v216
	v_sub_f32_e32 v227, v216, v228
	v_sub_f32_e32 v249, v249, v228
	v_sub_f32_e32 v130, v130, v228
	v_mul_f32_e32 v227, 0x3fb8aa3b, v227
	v_mul_f32_e32 v249, 0x3fb8aa3b, v249
	v_mul_f32_e32 v130, 0x3fb8aa3b, v130
	v_exp_f32_e32 v227, v227
	v_exp_f32_e32 v249, v249
	v_exp_f32_e32 v130, v130
	v_mov_b32_e32 v216, v228
	v_fma_f32 v224, v224, v227, v249
	v_add_f32_e32 v224, v224, v130
	v_mul_f32_e32 v196, v196, v227
	v_mul_f32_e32 v197, v197, v227
	v_mul_f32_e32 v198, v198, v227
	v_mul_f32_e32 v199, v199, v227
	v_fmac_f32_e32 v196, v249, v84
	v_fmac_f32_e32 v197, v249, v85
	v_fmac_f32_e32 v198, v249, v86
	v_fmac_f32_e32 v199, v249, v87
	v_fmac_f32_e32 v196, v130, v116
	v_fmac_f32_e32 v197, v130, v117
	v_fmac_f32_e32 v198, v130, v118
	v_fmac_f32_e32 v199, v130, v119
	v_max3_f32 v228, v250, v131, v217
	v_sub_f32_e32 v227, v217, v228
	v_sub_f32_e32 v250, v250, v228
	v_sub_f32_e32 v131, v131, v228
	v_mul_f32_e32 v227, 0x3fb8aa3b, v227
	v_mul_f32_e32 v250, 0x3fb8aa3b, v250
	v_mul_f32_e32 v131, 0x3fb8aa3b, v131
	v_exp_f32_e32 v227, v227
	v_exp_f32_e32 v250, v250
	v_exp_f32_e32 v131, v131
	v_mov_b32_e32 v217, v228
	v_fma_f32 v225, v225, v227, v250
	v_add_f32_e32 v225, v225, v131
	v_mul_f32_e32 v200, v200, v227
	v_mul_f32_e32 v201, v201, v227
	v_mul_f32_e32 v202, v202, v227
	v_mul_f32_e32 v203, v203, v227
	v_fmac_f32_e32 v200, v250, v88
	v_fmac_f32_e32 v201, v250, v89
	v_fmac_f32_e32 v202, v250, v90
	v_fmac_f32_e32 v203, v250, v91
	v_fmac_f32_e32 v200, v131, v120
	v_fmac_f32_e32 v201, v131, v121
	v_fmac_f32_e32 v202, v131, v122
	v_fmac_f32_e32 v203, v131, v123
	v_max3_f32 v228, v251, v132, v218
	v_sub_f32_e32 v227, v218, v228
	v_sub_f32_e32 v251, v251, v228
	v_sub_f32_e32 v132, v132, v228
	v_mul_f32_e32 v227, 0x3fb8aa3b, v227
	v_mul_f32_e32 v251, 0x3fb8aa3b, v251
	v_mul_f32_e32 v132, 0x3fb8aa3b, v132
	v_exp_f32_e32 v227, v227
	v_exp_f32_e32 v251, v251
	v_exp_f32_e32 v132, v132
	v_mov_b32_e32 v218, v228
	v_fma_f32 v226, v226, v227, v251
	v_add_f32_e32 v226, v226, v132
	v_mul_f32_e32 v204, v204, v227
	v_mul_f32_e32 v205, v205, v227
	v_mul_f32_e32 v206, v206, v227
	v_mul_f32_e32 v207, v207, v227
	v_fmac_f32_e32 v204, v251, v92
	v_fmac_f32_e32 v205, v251, v93
	v_fmac_f32_e32 v206, v251, v94
	v_fmac_f32_e32 v207, v251, v95
	v_fmac_f32_e32 v204, v132, v124
	v_fmac_f32_e32 v205, v132, v125
	v_fmac_f32_e32 v206, v132, v126
	v_fmac_f32_e32 v207, v132, v127
	s_sub_u32 s62, s62, s64
	s_subb_u32 s63, s63, 0
	s_add_u32 s42, s62, 0x1000
	s_addc_u32 s43, s63, 0
	global_load_dwordx4 v[64:67], v136, s[62:63] nt
	global_load_dwordx4 v[68:71], v136, s[62:63] offset:1024 nt
	global_load_dwordx4 v[72:75], v136, s[62:63] offset:2048 nt
	global_load_dwordx4 v[76:79], v136, s[62:63] offset:3072 nt
	global_load_dwordx4 v[80:83], v136, s[42:43] nt
	global_load_dwordx4 v[84:87], v136, s[42:43] offset:1024 nt
	global_load_dwordx4 v[88:91], v136, s[42:43] offset:2048 nt
	global_load_dwordx4 v[92:95], v136, s[42:43] offset:3072 nt
	s_sub_u32 s62, s62, s64
	s_subb_u32 s63, s63, 0
	s_add_u32 s42, s62, 0x1000
	s_addc_u32 s43, s63, 0
	global_load_dwordx4 v[96:99], v136, s[62:63] nt
	global_load_dwordx4 v[100:103], v136, s[62:63] offset:1024 nt
	global_load_dwordx4 v[104:107], v136, s[62:63] offset:2048 nt
	global_load_dwordx4 v[108:111], v136, s[62:63] offset:3072 nt
	global_load_dwordx4 v[112:115], v136, s[42:43] nt
	global_load_dwordx4 v[116:119], v136, s[42:43] offset:1024 nt
	global_load_dwordx4 v[120:123], v136, s[42:43] offset:2048 nt
	global_load_dwordx4 v[124:127], v136, s[42:43] offset:3072 nt
	s_waitcnt vmcnt(31)
	v_mul_f32_e32 v244, v138, v0
	v_fmac_f32_e32 v244, v139, v1
	v_fmac_f32_e32 v244, v140, v2
	v_fmac_f32_e32 v244, v141, v3
	s_waitcnt vmcnt(30)
	v_mul_f32_e32 v245, v142, v4
	v_fmac_f32_e32 v245, v143, v5
	v_fmac_f32_e32 v245, v144, v6
	v_fmac_f32_e32 v245, v145, v7
	s_waitcnt vmcnt(29)
	v_mul_f32_e32 v246, v146, v8
	v_fmac_f32_e32 v246, v147, v9
	v_fmac_f32_e32 v246, v148, v10
	v_fmac_f32_e32 v246, v149, v11
	v_add_f32_dpp v244, v244, v244 quad_perm:[1,0,3,2] row_mask:0xf bank_mask:0xf bound_ctrl:1
	v_add_f32_dpp v245, v245, v245 quad_perm:[1,0,3,2] row_mask:0xf bank_mask:0xf bound_ctrl:1
	v_add_f32_dpp v246, v246, v246 quad_perm:[1,0,3,2] row_mask:0xf bank_mask:0xf bound_ctrl:1
	v_add_f32_dpp v244, v244, v244 quad_perm:[2,3,0,1] row_mask:0xf bank_mask:0xf bound_ctrl:1
	v_add_f32_dpp v245, v245, v245 quad_perm:[2,3,0,1] row_mask:0xf bank_mask:0xf bound_ctrl:1
	v_add_f32_dpp v246, v246, v246 quad_perm:[2,3,0,1] row_mask:0xf bank_mask:0xf bound_ctrl:1
	v_add_f32_dpp v244, v244, v244 row_ror:4 row_mask:0xf bank_mask:0xf bound_ctrl:1
	v_add_f32_dpp v245, v245, v245 row_ror:4 row_mask:0xf bank_mask:0xf bound_ctrl:1
	v_add_f32_dpp v246, v246, v246 row_ror:4 row_mask:0xf bank_mask:0xf bound_ctrl:1
	v_add_f32_dpp v244, v244, v244 row_ror:8 row_mask:0xf bank_mask:0xf bound_ctrl:1
	v_add_f32_dpp v245, v245, v245 row_ror:8 row_mask:0xf bank_mask:0xf bound_ctrl:1
	v_add_f32_dpp v246, v246, v246 row_ror:8 row_mask:0xf bank_mask:0xf bound_ctrl:1
	v_mov_b32_e32 v133, v244
	v_mov_b32_e32 v134, v245
	v_mov_b32_e32 v135, v246
	v_permlane32_swap_b32_e32 v244, v133
	v_permlane32_swap_b32_e32 v245, v134
	v_permlane32_swap_b32_e32 v246, v135
	s_waitcnt vmcnt(28)
	v_mul_f32_e32 v247, v150, v12
	v_fmac_f32_e32 v247, v151, v13
	v_fmac_f32_e32 v247, v152, v14
	v_fmac_f32_e32 v247, v153, v15
	s_waitcnt vmcnt(27)
	v_mul_f32_e32 v248, v154, v16
	v_fmac_f32_e32 v248, v155, v17
	v_fmac_f32_e32 v248, v156, v18
	v_fmac_f32_e32 v248, v157, v19
	s_waitcnt vmcnt(26)
	v_mul_f32_e32 v249, v158, v20
	v_fmac_f32_e32 v249, v159, v21
	v_fmac_f32_e32 v249, v160, v22
	v_fmac_f32_e32 v249, v161, v23
	v_add_f32_dpp v247, v247, v247 quad_perm:[1,0,3,2] row_mask:0xf bank_mask:0xf bound_ctrl:1
	v_add_f32_dpp v248, v248, v248 quad_perm:[1,0,3,2] row_mask:0xf bank_mask:0xf bound_ctrl:1
	v_add_f32_dpp v249, v249, v249 quad_perm:[1,0,3,2] row_mask:0xf bank_mask:0xf bound_ctrl:1
	v_add_f32_dpp v247, v247, v247 quad_perm:[2,3,0,1] row_mask:0xf bank_mask:0xf bound_ctrl:1
	v_add_f32_dpp v248, v248, v248 quad_perm:[2,3,0,1] row_mask:0xf bank_mask:0xf bound_ctrl:1
	v_add_f32_dpp v249, v249, v249 quad_perm:[2,3,0,1] row_mask:0xf bank_mask:0xf bound_ctrl:1
	v_add_f32_dpp v247, v247, v247 row_ror:4 row_mask:0xf bank_mask:0xf bound_ctrl:1
	v_add_f32_dpp v248, v248, v248 row_ror:4 row_mask:0xf bank_mask:0xf bound_ctrl:1
	v_add_f32_dpp v249, v249, v249 row_ror:4 row_mask:0xf bank_mask:0xf bound_ctrl:1
	v_add_f32_dpp v247, v247, v247 row_ror:8 row_mask:0xf bank_mask:0xf bound_ctrl:1
	v_add_f32_dpp v248, v248, v248 row_ror:8 row_mask:0xf bank_mask:0xf bound_ctrl:1
	v_add_f32_dpp v249, v249, v249 row_ror:8 row_mask:0xf bank_mask:0xf bound_ctrl:1
	v_mov_b32_e32 v133, v247
	v_mov_b32_e32 v134, v248
	v_mov_b32_e32 v135, v249
	v_permlane32_swap_b32_e32 v247, v133
	v_permlane32_swap_b32_e32 v248, v134
	v_permlane32_swap_b32_e32 v249, v135
	s_waitcnt vmcnt(25)
	v_mul_f32_e32 v250, v162, v24
	v_fmac_f32_e32 v250, v163, v25
	v_fmac_f32_e32 v250, v164, v26
	v_fmac_f32_e32 v250, v165, v27
	s_waitcnt vmcnt(24)
	v_mul_f32_e32 v251, v166, v28
	v_fmac_f32_e32 v251, v167, v29
	v_fmac_f32_e32 v251, v168, v30
	v_fmac_f32_e32 v251, v169, v31
	s_waitcnt vmcnt(23)
	v_mul_f32_e32 v252, v138, v32
	v_fmac_f32_e32 v252, v139, v33
	v_fmac_f32_e32 v252, v140, v34
	v_fmac_f32_e32 v252, v141, v35
	v_add_f32_dpp v250, v250, v250 quad_perm:[1,0,3,2] row_mask:0xf bank_mask:0xf bound_ctrl:1
	v_add_f32_dpp v251, v251, v251 quad_perm:[1,0,3,2] row_mask:0xf bank_mask:0xf bound_ctrl:1
	v_add_f32_dpp v252, v252, v252 quad_perm:[1,0,3,2] row_mask:0xf bank_mask:0xf bound_ctrl:1
	v_add_f32_dpp v250, v250, v250 quad_perm:[2,3,0,1] row_mask:0xf bank_mask:0xf bound_ctrl:1
	v_add_f32_dpp v251, v251, v251 quad_perm:[2,3,0,1] row_mask:0xf bank_mask:0xf bound_ctrl:1
	v_add_f32_dpp v252, v252, v252 quad_perm:[2,3,0,1] row_mask:0xf bank_mask:0xf bound_ctrl:1
	v_add_f32_dpp v250, v250, v250 row_ror:4 row_mask:0xf bank_mask:0xf bound_ctrl:1
	v_add_f32_dpp v251, v251, v251 row_ror:4 row_mask:0xf bank_mask:0xf bound_ctrl:1
	v_add_f32_dpp v252, v252, v252 row_ror:4 row_mask:0xf bank_mask:0xf bound_ctrl:1
	v_add_f32_dpp v250, v250, v250 row_ror:8 row_mask:0xf bank_mask:0xf bound_ctrl:1
	v_add_f32_dpp v251, v251, v251 row_ror:8 row_mask:0xf bank_mask:0xf bound_ctrl:1
	v_add_f32_dpp v252, v252, v252 row_ror:8 row_mask:0xf bank_mask:0xf bound_ctrl:1
	v_mov_b32_e32 v133, v250
	v_mov_b32_e32 v134, v251
	v_mov_b32_e32 v135, v252
	v_permlane32_swap_b32_e32 v250, v133
	v_permlane32_swap_b32_e32 v251, v134
	v_permlane32_swap_b32_e32 v252, v135
	s_waitcnt vmcnt(22)
	v_mul_f32_e32 v253, v142, v36
	v_fmac_f32_e32 v253, v143, v37
	v_fmac_f32_e32 v253, v144, v38
	v_fmac_f32_e32 v253, v145, v39
	s_waitcnt vmcnt(21)
	v_mul_f32_e32 v254, v146, v40
	v_fmac_f32_e32 v254, v147, v41
	v_fmac_f32_e32 v254, v148, v42
	v_fmac_f32_e32 v254, v149, v43
	s_waitcnt vmcnt(20)
	v_mul_f32_e32 v128, v150, v44
	v_fmac_f32_e32 v128, v151, v45
	v_fmac_f32_e32 v128, v152, v46
	v_fmac_f32_e32 v128, v153, v47
	v_add_f32_dpp v253, v253, v253 quad_perm:[1,0,3,2] row_mask:0xf bank_mask:0xf bound_ctrl:1
	v_add_f32_dpp v254, v254, v254 quad_perm:[1,0,3,2] row_mask:0xf bank_mask:0xf bound_ctrl:1
	v_add_f32_dpp v128, v128, v128 quad_perm:[1,0,3,2] row_mask:0xf bank_mask:0xf bound_ctrl:1
	v_add_f32_dpp v253, v253, v253 quad_perm:[2,3,0,1] row_mask:0xf bank_mask:0xf bound_ctrl:1
	v_add_f32_dpp v254, v254, v254 quad_perm:[2,3,0,1] row_mask:0xf bank_mask:0xf bound_ctrl:1
	v_add_f32_dpp v128, v128, v128 quad_perm:[2,3,0,1] row_mask:0xf bank_mask:0xf bound_ctrl:1
	v_add_f32_dpp v253, v253, v253 row_ror:4 row_mask:0xf bank_mask:0xf bound_ctrl:1
	v_add_f32_dpp v254, v254, v254 row_ror:4 row_mask:0xf bank_mask:0xf bound_ctrl:1
	v_add_f32_dpp v128, v128, v128 row_ror:4 row_mask:0xf bank_mask:0xf bound_ctrl:1
	v_add_f32_dpp v253, v253, v253 row_ror:8 row_mask:0xf bank_mask:0xf bound_ctrl:1
	v_add_f32_dpp v254, v254, v254 row_ror:8 row_mask:0xf bank_mask:0xf bound_ctrl:1
	v_add_f32_dpp v128, v128, v128 row_ror:8 row_mask:0xf bank_mask:0xf bound_ctrl:1
	v_mov_b32_e32 v133, v253
	v_mov_b32_e32 v134, v254
	v_mov_b32_e32 v135, v128
	v_permlane32_swap_b32_e32 v253, v133
	v_permlane32_swap_b32_e32 v254, v134
	v_permlane32_swap_b32_e32 v128, v135
	s_waitcnt vmcnt(19)
	v_mul_f32_e32 v129, v154, v48
	v_fmac_f32_e32 v129, v155, v49
	v_fmac_f32_e32 v129, v156, v50
	v_fmac_f32_e32 v129, v157, v51
	s_waitcnt vmcnt(18)
	v_mul_f32_e32 v130, v158, v52
	v_fmac_f32_e32 v130, v159, v53
	v_fmac_f32_e32 v130, v160, v54
	v_fmac_f32_e32 v130, v161, v55
	s_waitcnt vmcnt(17)
	v_mul_f32_e32 v131, v162, v56
	v_fmac_f32_e32 v131, v163, v57
	v_fmac_f32_e32 v131, v164, v58
	v_fmac_f32_e32 v131, v165, v59
	v_add_f32_dpp v129, v129, v129 quad_perm:[1,0,3,2] row_mask:0xf bank_mask:0xf bound_ctrl:1
	v_add_f32_dpp v130, v130, v130 quad_perm:[1,0,3,2] row_mask:0xf bank_mask:0xf bound_ctrl:1
	v_add_f32_dpp v131, v131, v131 quad_perm:[1,0,3,2] row_mask:0xf bank_mask:0xf bound_ctrl:1
	v_add_f32_dpp v129, v129, v129 quad_perm:[2,3,0,1] row_mask:0xf bank_mask:0xf bound_ctrl:1
	v_add_f32_dpp v130, v130, v130 quad_perm:[2,3,0,1] row_mask:0xf bank_mask:0xf bound_ctrl:1
	v_add_f32_dpp v131, v131, v131 quad_perm:[2,3,0,1] row_mask:0xf bank_mask:0xf bound_ctrl:1
	v_add_f32_dpp v129, v129, v129 row_ror:4 row_mask:0xf bank_mask:0xf bound_ctrl:1
	v_add_f32_dpp v130, v130, v130 row_ror:4 row_mask:0xf bank_mask:0xf bound_ctrl:1
	v_add_f32_dpp v131, v131, v131 row_ror:4 row_mask:0xf bank_mask:0xf bound_ctrl:1
	v_add_f32_dpp v129, v129, v129 row_ror:8 row_mask:0xf bank_mask:0xf bound_ctrl:1
	v_add_f32_dpp v130, v130, v130 row_ror:8 row_mask:0xf bank_mask:0xf bound_ctrl:1
	v_add_f32_dpp v131, v131, v131 row_ror:8 row_mask:0xf bank_mask:0xf bound_ctrl:1
	v_mov_b32_e32 v133, v129
	v_mov_b32_e32 v134, v130
	v_mov_b32_e32 v135, v131
	v_permlane32_swap_b32_e32 v129, v133
	v_permlane32_swap_b32_e32 v130, v134
	v_permlane32_swap_b32_e32 v131, v135
	s_waitcnt vmcnt(16)
	v_mul_f32_e32 v132, v166, v60
	v_fmac_f32_e32 v132, v167, v61
	v_fmac_f32_e32 v132, v168, v62
	v_fmac_f32_e32 v132, v169, v63
	s_nop 1
	v_add_f32_dpp v132, v132, v132 quad_perm:[1,0,3,2] row_mask:0xf bank_mask:0xf bound_ctrl:1
	s_nop 1
	v_add_f32_dpp v132, v132, v132 quad_perm:[2,3,0,1] row_mask:0xf bank_mask:0xf bound_ctrl:1
	s_nop 1
	v_add_f32_dpp v132, v132, v132 row_ror:4 row_mask:0xf bank_mask:0xf bound_ctrl:1
	s_nop 1
	v_add_f32_dpp v132, v132, v132 row_ror:8 row_mask:0xf bank_mask:0xf bound_ctrl:1
	s_nop 1
	v_mov_b32_e32 v133, v132
	s_nop 1
	v_permlane32_swap_b32_e32 v132, v133
	v_max3_f32 v228, v244, v252, v208
	v_sub_f32_e32 v227, v208, v228
	v_sub_f32_e32 v244, v244, v228
	v_sub_f32_e32 v252, v252, v228
	v_mul_f32_e32 v227, 0x3fb8aa3b, v227
	v_mul_f32_e32 v244, 0x3fb8aa3b, v244
	v_mul_f32_e32 v252, 0x3fb8aa3b, v252
	v_exp_f32_e32 v227, v227
	v_exp_f32_e32 v244, v244
	v_exp_f32_e32 v252, v252
	v_mov_b32_e32 v208, v228
	v_fma_f32 v219, v219, v227, v244
	v_add_f32_e32 v219, v219, v252
	v_mul_f32_e32 v172, v172, v227
	v_mul_f32_e32 v173, v173, v227
	v_mul_f32_e32 v174, v174, v227
	v_mul_f32_e32 v175, v175, v227
	v_fmac_f32_e32 v172, v244, v0
	v_fmac_f32_e32 v173, v244, v1
	v_fmac_f32_e32 v174, v244, v2
	v_fmac_f32_e32 v175, v244, v3
	v_fmac_f32_e32 v172, v252, v32
	v_fmac_f32_e32 v173, v252, v33
	v_fmac_f32_e32 v174, v252, v34
	v_fmac_f32_e32 v175, v252, v35
	v_max3_f32 v228, v245, v253, v209
	v_sub_f32_e32 v227, v209, v228
	v_sub_f32_e32 v245, v245, v228
	v_sub_f32_e32 v253, v253, v228
	v_mul_f32_e32 v227, 0x3fb8aa3b, v227
	v_mul_f32_e32 v245, 0x3fb8aa3b, v245
	v_mul_f32_e32 v253, 0x3fb8aa3b, v253
	v_exp_f32_e32 v227, v227
	v_exp_f32_e32 v245, v245
	v_exp_f32_e32 v253, v253
	v_mov_b32_e32 v209, v228
	v_fma_f32 v220, v220, v227, v245
	v_add_f32_e32 v220, v220, v253
	v_mul_f32_e32 v176, v176, v227
	v_mul_f32_e32 v177, v177, v227
	v_mul_f32_e32 v178, v178, v227
	v_mul_f32_e32 v179, v179, v227
	v_fmac_f32_e32 v176, v245, v4
	v_fmac_f32_e32 v177, v245, v5
	v_fmac_f32_e32 v178, v245, v6
	v_fmac_f32_e32 v179, v245, v7
	v_fmac_f32_e32 v176, v253, v36
	v_fmac_f32_e32 v177, v253, v37
	v_fmac_f32_e32 v178, v253, v38
	v_fmac_f32_e32 v179, v253, v39
	v_max3_f32 v228, v246, v254, v210
	v_sub_f32_e32 v227, v210, v228
	v_sub_f32_e32 v246, v246, v228
	v_sub_f32_e32 v254, v254, v228
	v_mul_f32_e32 v227, 0x3fb8aa3b, v227
	v_mul_f32_e32 v246, 0x3fb8aa3b, v246
	v_mul_f32_e32 v254, 0x3fb8aa3b, v254
	v_exp_f32_e32 v227, v227
	v_exp_f32_e32 v246, v246
	v_exp_f32_e32 v254, v254
	v_mov_b32_e32 v210, v228
	v_fma_f32 v221, v221, v227, v246
	v_add_f32_e32 v221, v221, v254
	v_mul_f32_e32 v180, v180, v227
	v_mul_f32_e32 v181, v181, v227
	v_mul_f32_e32 v182, v182, v227
	v_mul_f32_e32 v183, v183, v227
	v_fmac_f32_e32 v180, v246, v8
	v_fmac_f32_e32 v181, v246, v9
	v_fmac_f32_e32 v182, v246, v10
	v_fmac_f32_e32 v183, v246, v11
	v_fmac_f32_e32 v180, v254, v40
	v_fmac_f32_e32 v181, v254, v41
	v_fmac_f32_e32 v182, v254, v42
	v_fmac_f32_e32 v183, v254, v43
	v_max3_f32 v228, v247, v128, v212
	v_sub_f32_e32 v227, v212, v228
	v_sub_f32_e32 v247, v247, v228
	v_sub_f32_e32 v128, v128, v228
	v_mul_f32_e32 v227, 0x3fb8aa3b, v227
	v_mul_f32_e32 v247, 0x3fb8aa3b, v247
	v_mul_f32_e32 v128, 0x3fb8aa3b, v128
	v_exp_f32_e32 v227, v227
	v_exp_f32_e32 v247, v247
	v_exp_f32_e32 v128, v128
	v_mov_b32_e32 v212, v228
	v_fma_f32 v222, v222, v227, v247
	v_add_f32_e32 v222, v222, v128
	v_mul_f32_e32 v184, v184, v227
	v_mul_f32_e32 v185, v185, v227
	v_mul_f32_e32 v186, v186, v227
	v_mul_f32_e32 v187, v187, v227
	v_fmac_f32_e32 v184, v247, v12
	v_fmac_f32_e32 v185, v247, v13
	v_fmac_f32_e32 v186, v247, v14
	v_fmac_f32_e32 v187, v247, v15
	v_fmac_f32_e32 v184, v128, v44
	v_fmac_f32_e32 v185, v128, v45
	v_fmac_f32_e32 v186, v128, v46
	v_fmac_f32_e32 v187, v128, v47
	v_max3_f32 v228, v248, v129, v214
	v_sub_f32_e32 v227, v214, v228
	v_sub_f32_e32 v248, v248, v228
	v_sub_f32_e32 v129, v129, v228
	v_mul_f32_e32 v227, 0x3fb8aa3b, v227
	v_mul_f32_e32 v248, 0x3fb8aa3b, v248
	v_mul_f32_e32 v129, 0x3fb8aa3b, v129
	v_exp_f32_e32 v227, v227
	v_exp_f32_e32 v248, v248
	v_exp_f32_e32 v129, v129
	v_mov_b32_e32 v214, v228
	v_fma_f32 v223, v223, v227, v248
	v_add_f32_e32 v223, v223, v129
	v_mul_f32_e32 v188, v188, v227
	v_mul_f32_e32 v189, v189, v227
	v_mul_f32_e32 v190, v190, v227
	v_mul_f32_e32 v191, v191, v227
	v_fmac_f32_e32 v188, v248, v16
	v_fmac_f32_e32 v189, v248, v17
	v_fmac_f32_e32 v190, v248, v18
	v_fmac_f32_e32 v191, v248, v19
	v_fmac_f32_e32 v188, v129, v48
	v_fmac_f32_e32 v189, v129, v49
	v_fmac_f32_e32 v190, v129, v50
	v_fmac_f32_e32 v191, v129, v51
	v_max3_f32 v228, v249, v130, v216
	v_sub_f32_e32 v227, v216, v228
	v_sub_f32_e32 v249, v249, v228
	v_sub_f32_e32 v130, v130, v228
	v_mul_f32_e32 v227, 0x3fb8aa3b, v227
	v_mul_f32_e32 v249, 0x3fb8aa3b, v249
	v_mul_f32_e32 v130, 0x3fb8aa3b, v130
	v_exp_f32_e32 v227, v227
	v_exp_f32_e32 v249, v249
	v_exp_f32_e32 v130, v130
	v_mov_b32_e32 v216, v228
	v_fma_f32 v224, v224, v227, v249
	v_add_f32_e32 v224, v224, v130
	v_mul_f32_e32 v196, v196, v227
	v_mul_f32_e32 v197, v197, v227
	v_mul_f32_e32 v198, v198, v227
	v_mul_f32_e32 v199, v199, v227
	v_fmac_f32_e32 v196, v249, v20
	v_fmac_f32_e32 v197, v249, v21
	v_fmac_f32_e32 v198, v249, v22
	v_fmac_f32_e32 v199, v249, v23
	v_fmac_f32_e32 v196, v130, v52
	v_fmac_f32_e32 v197, v130, v53
	v_fmac_f32_e32 v198, v130, v54
	v_fmac_f32_e32 v199, v130, v55
	v_max3_f32 v228, v250, v131, v217
	v_sub_f32_e32 v227, v217, v228
	v_sub_f32_e32 v250, v250, v228
	v_sub_f32_e32 v131, v131, v228
	v_mul_f32_e32 v227, 0x3fb8aa3b, v227
	v_mul_f32_e32 v250, 0x3fb8aa3b, v250
	v_mul_f32_e32 v131, 0x3fb8aa3b, v131
	v_exp_f32_e32 v227, v227
	v_exp_f32_e32 v250, v250
	v_exp_f32_e32 v131, v131
	v_mov_b32_e32 v217, v228
	v_fma_f32 v225, v225, v227, v250
	v_add_f32_e32 v225, v225, v131
	v_mul_f32_e32 v200, v200, v227
	v_mul_f32_e32 v201, v201, v227
	v_mul_f32_e32 v202, v202, v227
	v_mul_f32_e32 v203, v203, v227
	v_fmac_f32_e32 v200, v250, v24
	v_fmac_f32_e32 v201, v250, v25
	v_fmac_f32_e32 v202, v250, v26
	v_fmac_f32_e32 v203, v250, v27
	v_fmac_f32_e32 v200, v131, v56
	v_fmac_f32_e32 v201, v131, v57
	v_fmac_f32_e32 v202, v131, v58
	v_fmac_f32_e32 v203, v131, v59
	v_max3_f32 v228, v251, v132, v218
	v_sub_f32_e32 v227, v218, v228
	v_sub_f32_e32 v251, v251, v228
	v_sub_f32_e32 v132, v132, v228
	v_mul_f32_e32 v227, 0x3fb8aa3b, v227
	v_mul_f32_e32 v251, 0x3fb8aa3b, v251
	v_mul_f32_e32 v132, 0x3fb8aa3b, v132
	v_exp_f32_e32 v227, v227
	v_exp_f32_e32 v251, v251
	v_exp_f32_e32 v132, v132
	v_mov_b32_e32 v218, v228
	v_fma_f32 v226, v226, v227, v251
	v_add_f32_e32 v226, v226, v132
	v_mul_f32_e32 v204, v204, v227
	v_mul_f32_e32 v205, v205, v227
	v_mul_f32_e32 v206, v206, v227
	v_mul_f32_e32 v207, v207, v227
	v_fmac_f32_e32 v204, v251, v28
	v_fmac_f32_e32 v205, v251, v29
	v_fmac_f32_e32 v206, v251, v30
	v_fmac_f32_e32 v207, v251, v31
	v_fmac_f32_e32 v204, v132, v60
	v_fmac_f32_e32 v205, v132, v61
	v_fmac_f32_e32 v206, v132, v62
	v_fmac_f32_e32 v207, v132, v63
	s_waitcnt vmcnt(15)
	v_mul_f32_e32 v244, v138, v64
	v_fmac_f32_e32 v244, v139, v65
	v_fmac_f32_e32 v244, v140, v66
	v_fmac_f32_e32 v244, v141, v67
	s_waitcnt vmcnt(14)
	v_mul_f32_e32 v245, v142, v68
	v_fmac_f32_e32 v245, v143, v69
	v_fmac_f32_e32 v245, v144, v70
	v_fmac_f32_e32 v245, v145, v71
	s_waitcnt vmcnt(13)
	v_mul_f32_e32 v246, v146, v72
	v_fmac_f32_e32 v246, v147, v73
	v_fmac_f32_e32 v246, v148, v74
	v_fmac_f32_e32 v246, v149, v75
	v_add_f32_dpp v244, v244, v244 quad_perm:[1,0,3,2] row_mask:0xf bank_mask:0xf bound_ctrl:1
	v_add_f32_dpp v245, v245, v245 quad_perm:[1,0,3,2] row_mask:0xf bank_mask:0xf bound_ctrl:1
	v_add_f32_dpp v246, v246, v246 quad_perm:[1,0,3,2] row_mask:0xf bank_mask:0xf bound_ctrl:1
	v_add_f32_dpp v244, v244, v244 quad_perm:[2,3,0,1] row_mask:0xf bank_mask:0xf bound_ctrl:1
	v_add_f32_dpp v245, v245, v245 quad_perm:[2,3,0,1] row_mask:0xf bank_mask:0xf bound_ctrl:1
	v_add_f32_dpp v246, v246, v246 quad_perm:[2,3,0,1] row_mask:0xf bank_mask:0xf bound_ctrl:1
	v_add_f32_dpp v244, v244, v244 row_ror:4 row_mask:0xf bank_mask:0xf bound_ctrl:1
	v_add_f32_dpp v245, v245, v245 row_ror:4 row_mask:0xf bank_mask:0xf bound_ctrl:1
	v_add_f32_dpp v246, v246, v246 row_ror:4 row_mask:0xf bank_mask:0xf bound_ctrl:1
	v_add_f32_dpp v244, v244, v244 row_ror:8 row_mask:0xf bank_mask:0xf bound_ctrl:1
	v_add_f32_dpp v245, v245, v245 row_ror:8 row_mask:0xf bank_mask:0xf bound_ctrl:1
	v_add_f32_dpp v246, v246, v246 row_ror:8 row_mask:0xf bank_mask:0xf bound_ctrl:1
	v_mov_b32_e32 v133, v244
	v_mov_b32_e32 v134, v245
	v_mov_b32_e32 v135, v246
	v_permlane32_swap_b32_e32 v244, v133
	v_permlane32_swap_b32_e32 v245, v134
	v_permlane32_swap_b32_e32 v246, v135
	s_waitcnt vmcnt(12)
	v_mul_f32_e32 v247, v150, v76
	v_fmac_f32_e32 v247, v151, v77
	v_fmac_f32_e32 v247, v152, v78
	v_fmac_f32_e32 v247, v153, v79
	s_waitcnt vmcnt(11)
	v_mul_f32_e32 v248, v154, v80
	v_fmac_f32_e32 v248, v155, v81
	v_fmac_f32_e32 v248, v156, v82
	v_fmac_f32_e32 v248, v157, v83
	s_waitcnt vmcnt(10)
	v_mul_f32_e32 v249, v158, v84
	v_fmac_f32_e32 v249, v159, v85
	v_fmac_f32_e32 v249, v160, v86
	v_fmac_f32_e32 v249, v161, v87
	v_add_f32_dpp v247, v247, v247 quad_perm:[1,0,3,2] row_mask:0xf bank_mask:0xf bound_ctrl:1
	v_add_f32_dpp v248, v248, v248 quad_perm:[1,0,3,2] row_mask:0xf bank_mask:0xf bound_ctrl:1
	v_add_f32_dpp v249, v249, v249 quad_perm:[1,0,3,2] row_mask:0xf bank_mask:0xf bound_ctrl:1
	v_add_f32_dpp v247, v247, v247 quad_perm:[2,3,0,1] row_mask:0xf bank_mask:0xf bound_ctrl:1
	v_add_f32_dpp v248, v248, v248 quad_perm:[2,3,0,1] row_mask:0xf bank_mask:0xf bound_ctrl:1
	v_add_f32_dpp v249, v249, v249 quad_perm:[2,3,0,1] row_mask:0xf bank_mask:0xf bound_ctrl:1
	v_add_f32_dpp v247, v247, v247 row_ror:4 row_mask:0xf bank_mask:0xf bound_ctrl:1
	v_add_f32_dpp v248, v248, v248 row_ror:4 row_mask:0xf bank_mask:0xf bound_ctrl:1
	v_add_f32_dpp v249, v249, v249 row_ror:4 row_mask:0xf bank_mask:0xf bound_ctrl:1
	v_add_f32_dpp v247, v247, v247 row_ror:8 row_mask:0xf bank_mask:0xf bound_ctrl:1
	v_add_f32_dpp v248, v248, v248 row_ror:8 row_mask:0xf bank_mask:0xf bound_ctrl:1
	v_add_f32_dpp v249, v249, v249 row_ror:8 row_mask:0xf bank_mask:0xf bound_ctrl:1
	v_mov_b32_e32 v133, v247
	v_mov_b32_e32 v134, v248
	v_mov_b32_e32 v135, v249
	v_permlane32_swap_b32_e32 v247, v133
	v_permlane32_swap_b32_e32 v248, v134
	v_permlane32_swap_b32_e32 v249, v135
	s_waitcnt vmcnt(9)
	v_mul_f32_e32 v250, v162, v88
	v_fmac_f32_e32 v250, v163, v89
	v_fmac_f32_e32 v250, v164, v90
	v_fmac_f32_e32 v250, v165, v91
	s_waitcnt vmcnt(8)
	v_mul_f32_e32 v251, v166, v92
	v_fmac_f32_e32 v251, v167, v93
	v_fmac_f32_e32 v251, v168, v94
	v_fmac_f32_e32 v251, v169, v95
	s_waitcnt vmcnt(7)
	v_mul_f32_e32 v252, v138, v96
	v_fmac_f32_e32 v252, v139, v97
	v_fmac_f32_e32 v252, v140, v98
	v_fmac_f32_e32 v252, v141, v99
	v_add_f32_dpp v250, v250, v250 quad_perm:[1,0,3,2] row_mask:0xf bank_mask:0xf bound_ctrl:1
	v_add_f32_dpp v251, v251, v251 quad_perm:[1,0,3,2] row_mask:0xf bank_mask:0xf bound_ctrl:1
	v_add_f32_dpp v252, v252, v252 quad_perm:[1,0,3,2] row_mask:0xf bank_mask:0xf bound_ctrl:1
	v_add_f32_dpp v250, v250, v250 quad_perm:[2,3,0,1] row_mask:0xf bank_mask:0xf bound_ctrl:1
	v_add_f32_dpp v251, v251, v251 quad_perm:[2,3,0,1] row_mask:0xf bank_mask:0xf bound_ctrl:1
	v_add_f32_dpp v252, v252, v252 quad_perm:[2,3,0,1] row_mask:0xf bank_mask:0xf bound_ctrl:1
	v_add_f32_dpp v250, v250, v250 row_ror:4 row_mask:0xf bank_mask:0xf bound_ctrl:1
	v_add_f32_dpp v251, v251, v251 row_ror:4 row_mask:0xf bank_mask:0xf bound_ctrl:1
	v_add_f32_dpp v252, v252, v252 row_ror:4 row_mask:0xf bank_mask:0xf bound_ctrl:1
	v_add_f32_dpp v250, v250, v250 row_ror:8 row_mask:0xf bank_mask:0xf bound_ctrl:1
	v_add_f32_dpp v251, v251, v251 row_ror:8 row_mask:0xf bank_mask:0xf bound_ctrl:1
	v_add_f32_dpp v252, v252, v252 row_ror:8 row_mask:0xf bank_mask:0xf bound_ctrl:1
	v_mov_b32_e32 v133, v250
	v_mov_b32_e32 v134, v251
	v_mov_b32_e32 v135, v252
	v_permlane32_swap_b32_e32 v250, v133
	v_permlane32_swap_b32_e32 v251, v134
	v_permlane32_swap_b32_e32 v252, v135
	s_waitcnt vmcnt(6)
	v_mul_f32_e32 v253, v142, v100
	v_fmac_f32_e32 v253, v143, v101
	v_fmac_f32_e32 v253, v144, v102
	v_fmac_f32_e32 v253, v145, v103
	s_waitcnt vmcnt(5)
	v_mul_f32_e32 v254, v146, v104
	v_fmac_f32_e32 v254, v147, v105
	v_fmac_f32_e32 v254, v148, v106
	v_fmac_f32_e32 v254, v149, v107
	s_waitcnt vmcnt(4)
	v_mul_f32_e32 v128, v150, v108
	v_fmac_f32_e32 v128, v151, v109
	v_fmac_f32_e32 v128, v152, v110
	v_fmac_f32_e32 v128, v153, v111
	v_add_f32_dpp v253, v253, v253 quad_perm:[1,0,3,2] row_mask:0xf bank_mask:0xf bound_ctrl:1
	v_add_f32_dpp v254, v254, v254 quad_perm:[1,0,3,2] row_mask:0xf bank_mask:0xf bound_ctrl:1
	v_add_f32_dpp v128, v128, v128 quad_perm:[1,0,3,2] row_mask:0xf bank_mask:0xf bound_ctrl:1
	v_add_f32_dpp v253, v253, v253 quad_perm:[2,3,0,1] row_mask:0xf bank_mask:0xf bound_ctrl:1
	v_add_f32_dpp v254, v254, v254 quad_perm:[2,3,0,1] row_mask:0xf bank_mask:0xf bound_ctrl:1
	v_add_f32_dpp v128, v128, v128 quad_perm:[2,3,0,1] row_mask:0xf bank_mask:0xf bound_ctrl:1
	v_add_f32_dpp v253, v253, v253 row_ror:4 row_mask:0xf bank_mask:0xf bound_ctrl:1
	v_add_f32_dpp v254, v254, v254 row_ror:4 row_mask:0xf bank_mask:0xf bound_ctrl:1
	v_add_f32_dpp v128, v128, v128 row_ror:4 row_mask:0xf bank_mask:0xf bound_ctrl:1
	v_add_f32_dpp v253, v253, v253 row_ror:8 row_mask:0xf bank_mask:0xf bound_ctrl:1
	v_add_f32_dpp v254, v254, v254 row_ror:8 row_mask:0xf bank_mask:0xf bound_ctrl:1
	v_add_f32_dpp v128, v128, v128 row_ror:8 row_mask:0xf bank_mask:0xf bound_ctrl:1
	v_mov_b32_e32 v133, v253
	v_mov_b32_e32 v134, v254
	v_mov_b32_e32 v135, v128
	v_permlane32_swap_b32_e32 v253, v133
	v_permlane32_swap_b32_e32 v254, v134
	v_permlane32_swap_b32_e32 v128, v135
	s_waitcnt vmcnt(3)
	v_mul_f32_e32 v129, v154, v112
	v_fmac_f32_e32 v129, v155, v113
	v_fmac_f32_e32 v129, v156, v114
	v_fmac_f32_e32 v129, v157, v115
	s_waitcnt vmcnt(2)
	v_mul_f32_e32 v130, v158, v116
	v_fmac_f32_e32 v130, v159, v117
	v_fmac_f32_e32 v130, v160, v118
	v_fmac_f32_e32 v130, v161, v119
	s_waitcnt vmcnt(1)
	v_mul_f32_e32 v131, v162, v120
	v_fmac_f32_e32 v131, v163, v121
	v_fmac_f32_e32 v131, v164, v122
	v_fmac_f32_e32 v131, v165, v123
	v_add_f32_dpp v129, v129, v129 quad_perm:[1,0,3,2] row_mask:0xf bank_mask:0xf bound_ctrl:1
	v_add_f32_dpp v130, v130, v130 quad_perm:[1,0,3,2] row_mask:0xf bank_mask:0xf bound_ctrl:1
	v_add_f32_dpp v131, v131, v131 quad_perm:[1,0,3,2] row_mask:0xf bank_mask:0xf bound_ctrl:1
	v_add_f32_dpp v129, v129, v129 quad_perm:[2,3,0,1] row_mask:0xf bank_mask:0xf bound_ctrl:1
	v_add_f32_dpp v130, v130, v130 quad_perm:[2,3,0,1] row_mask:0xf bank_mask:0xf bound_ctrl:1
	v_add_f32_dpp v131, v131, v131 quad_perm:[2,3,0,1] row_mask:0xf bank_mask:0xf bound_ctrl:1
	v_add_f32_dpp v129, v129, v129 row_ror:4 row_mask:0xf bank_mask:0xf bound_ctrl:1
	v_add_f32_dpp v130, v130, v130 row_ror:4 row_mask:0xf bank_mask:0xf bound_ctrl:1
	v_add_f32_dpp v131, v131, v131 row_ror:4 row_mask:0xf bank_mask:0xf bound_ctrl:1
	v_add_f32_dpp v129, v129, v129 row_ror:8 row_mask:0xf bank_mask:0xf bound_ctrl:1
	v_add_f32_dpp v130, v130, v130 row_ror:8 row_mask:0xf bank_mask:0xf bound_ctrl:1
	v_add_f32_dpp v131, v131, v131 row_ror:8 row_mask:0xf bank_mask:0xf bound_ctrl:1
	v_mov_b32_e32 v133, v129
	v_mov_b32_e32 v134, v130
	v_mov_b32_e32 v135, v131
	v_permlane32_swap_b32_e32 v129, v133
	v_permlane32_swap_b32_e32 v130, v134
	v_permlane32_swap_b32_e32 v131, v135
	s_waitcnt vmcnt(0)
	v_mul_f32_e32 v132, v166, v124
	v_fmac_f32_e32 v132, v167, v125
	v_fmac_f32_e32 v132, v168, v126
	v_fmac_f32_e32 v132, v169, v127
	s_nop 1
	v_add_f32_dpp v132, v132, v132 quad_perm:[1,0,3,2] row_mask:0xf bank_mask:0xf bound_ctrl:1
	s_nop 1
	v_add_f32_dpp v132, v132, v132 quad_perm:[2,3,0,1] row_mask:0xf bank_mask:0xf bound_ctrl:1
	s_nop 1
	v_add_f32_dpp v132, v132, v132 row_ror:4 row_mask:0xf bank_mask:0xf bound_ctrl:1
	s_nop 1
	v_add_f32_dpp v132, v132, v132 row_ror:8 row_mask:0xf bank_mask:0xf bound_ctrl:1
	s_nop 1
	v_mov_b32_e32 v133, v132
	s_nop 1
	v_permlane32_swap_b32_e32 v132, v133
	v_max3_f32 v228, v244, v252, v208
	v_sub_f32_e32 v227, v208, v228
	v_sub_f32_e32 v244, v244, v228
	v_sub_f32_e32 v252, v252, v228
	v_mul_f32_e32 v227, 0x3fb8aa3b, v227
	v_mul_f32_e32 v244, 0x3fb8aa3b, v244
	v_mul_f32_e32 v252, 0x3fb8aa3b, v252
	v_exp_f32_e32 v227, v227
	v_exp_f32_e32 v244, v244
	v_exp_f32_e32 v252, v252
	v_mov_b32_e32 v208, v228
	v_fma_f32 v219, v219, v227, v244
	v_add_f32_e32 v219, v219, v252
	v_mul_f32_e32 v172, v172, v227
	v_mul_f32_e32 v173, v173, v227
	v_mul_f32_e32 v174, v174, v227
	v_mul_f32_e32 v175, v175, v227
	v_fmac_f32_e32 v172, v244, v64
	v_fmac_f32_e32 v173, v244, v65
	v_fmac_f32_e32 v174, v244, v66
	v_fmac_f32_e32 v175, v244, v67
	v_fmac_f32_e32 v172, v252, v96
	v_fmac_f32_e32 v173, v252, v97
	v_fmac_f32_e32 v174, v252, v98
	v_fmac_f32_e32 v175, v252, v99
	v_max3_f32 v228, v245, v253, v209
	v_sub_f32_e32 v227, v209, v228
	v_sub_f32_e32 v245, v245, v228
	v_sub_f32_e32 v253, v253, v228
	v_mul_f32_e32 v227, 0x3fb8aa3b, v227
	v_mul_f32_e32 v245, 0x3fb8aa3b, v245
	v_mul_f32_e32 v253, 0x3fb8aa3b, v253
	v_exp_f32_e32 v227, v227
	v_exp_f32_e32 v245, v245
	v_exp_f32_e32 v253, v253
	v_mov_b32_e32 v209, v228
	v_fma_f32 v220, v220, v227, v245
	v_add_f32_e32 v220, v220, v253
	v_mul_f32_e32 v176, v176, v227
	v_mul_f32_e32 v177, v177, v227
	v_mul_f32_e32 v178, v178, v227
	v_mul_f32_e32 v179, v179, v227
	v_fmac_f32_e32 v176, v245, v68
	v_fmac_f32_e32 v177, v245, v69
	v_fmac_f32_e32 v178, v245, v70
	v_fmac_f32_e32 v179, v245, v71
	v_fmac_f32_e32 v176, v253, v100
	v_fmac_f32_e32 v177, v253, v101
	v_fmac_f32_e32 v178, v253, v102
	v_fmac_f32_e32 v179, v253, v103
	v_max3_f32 v228, v246, v254, v210
	v_sub_f32_e32 v227, v210, v228
	v_sub_f32_e32 v246, v246, v228
	v_sub_f32_e32 v254, v254, v228
	v_mul_f32_e32 v227, 0x3fb8aa3b, v227
	v_mul_f32_e32 v246, 0x3fb8aa3b, v246
	v_mul_f32_e32 v254, 0x3fb8aa3b, v254
	v_exp_f32_e32 v227, v227
	v_exp_f32_e32 v246, v246
	v_exp_f32_e32 v254, v254
	v_mov_b32_e32 v210, v228
	v_fma_f32 v221, v221, v227, v246
	v_add_f32_e32 v221, v221, v254
	v_mul_f32_e32 v180, v180, v227
	v_mul_f32_e32 v181, v181, v227
	v_mul_f32_e32 v182, v182, v227
	v_mul_f32_e32 v183, v183, v227
	v_fmac_f32_e32 v180, v246, v72
	v_fmac_f32_e32 v181, v246, v73
	v_fmac_f32_e32 v182, v246, v74
	v_fmac_f32_e32 v183, v246, v75
	v_fmac_f32_e32 v180, v254, v104
	v_fmac_f32_e32 v181, v254, v105
	v_fmac_f32_e32 v182, v254, v106
	v_fmac_f32_e32 v183, v254, v107
	v_max3_f32 v228, v247, v128, v212
	v_sub_f32_e32 v227, v212, v228
	v_sub_f32_e32 v247, v247, v228
	v_sub_f32_e32 v128, v128, v228
	v_mul_f32_e32 v227, 0x3fb8aa3b, v227
	v_mul_f32_e32 v247, 0x3fb8aa3b, v247
	v_mul_f32_e32 v128, 0x3fb8aa3b, v128
	v_exp_f32_e32 v227, v227
	v_exp_f32_e32 v247, v247
	v_exp_f32_e32 v128, v128
	v_mov_b32_e32 v212, v228
	v_fma_f32 v222, v222, v227, v247
	v_add_f32_e32 v222, v222, v128
	v_mul_f32_e32 v184, v184, v227
	v_mul_f32_e32 v185, v185, v227
	v_mul_f32_e32 v186, v186, v227
	v_mul_f32_e32 v187, v187, v227
	v_fmac_f32_e32 v184, v247, v76
	v_fmac_f32_e32 v185, v247, v77
	v_fmac_f32_e32 v186, v247, v78
	v_fmac_f32_e32 v187, v247, v79
	v_fmac_f32_e32 v184, v128, v108
	v_fmac_f32_e32 v185, v128, v109
	v_fmac_f32_e32 v186, v128, v110
	v_fmac_f32_e32 v187, v128, v111
	v_max3_f32 v228, v248, v129, v214
	v_sub_f32_e32 v227, v214, v228
	v_sub_f32_e32 v248, v248, v228
	v_sub_f32_e32 v129, v129, v228
	v_mul_f32_e32 v227, 0x3fb8aa3b, v227
	v_mul_f32_e32 v248, 0x3fb8aa3b, v248
	v_mul_f32_e32 v129, 0x3fb8aa3b, v129
	v_exp_f32_e32 v227, v227
	v_exp_f32_e32 v248, v248
	v_exp_f32_e32 v129, v129
	v_mov_b32_e32 v214, v228
	v_fma_f32 v223, v223, v227, v248
	v_add_f32_e32 v223, v223, v129
	v_mul_f32_e32 v188, v188, v227
	v_mul_f32_e32 v189, v189, v227
	v_mul_f32_e32 v190, v190, v227
	v_mul_f32_e32 v191, v191, v227
	v_fmac_f32_e32 v188, v248, v80
	v_fmac_f32_e32 v189, v248, v81
	v_fmac_f32_e32 v190, v248, v82
	v_fmac_f32_e32 v191, v248, v83
	v_fmac_f32_e32 v188, v129, v112
	v_fmac_f32_e32 v189, v129, v113
	v_fmac_f32_e32 v190, v129, v114
	v_fmac_f32_e32 v191, v129, v115
	v_max3_f32 v228, v249, v130, v216
	v_sub_f32_e32 v227, v216, v228
	v_sub_f32_e32 v249, v249, v228
	v_sub_f32_e32 v130, v130, v228
	v_mul_f32_e32 v227, 0x3fb8aa3b, v227
	v_mul_f32_e32 v249, 0x3fb8aa3b, v249
	v_mul_f32_e32 v130, 0x3fb8aa3b, v130
	v_exp_f32_e32 v227, v227
	v_exp_f32_e32 v249, v249
	v_exp_f32_e32 v130, v130
	v_mov_b32_e32 v216, v228
	v_fma_f32 v224, v224, v227, v249
	v_add_f32_e32 v224, v224, v130
	v_mul_f32_e32 v196, v196, v227
	v_mul_f32_e32 v197, v197, v227
	v_mul_f32_e32 v198, v198, v227
	v_mul_f32_e32 v199, v199, v227
	v_fmac_f32_e32 v196, v249, v84
	v_fmac_f32_e32 v197, v249, v85
	v_fmac_f32_e32 v198, v249, v86
	v_fmac_f32_e32 v199, v249, v87
	v_fmac_f32_e32 v196, v130, v116
	v_fmac_f32_e32 v197, v130, v117
	v_fmac_f32_e32 v198, v130, v118
	v_fmac_f32_e32 v199, v130, v119
	v_max3_f32 v228, v250, v131, v217
	v_sub_f32_e32 v227, v217, v228
	v_sub_f32_e32 v250, v250, v228
	v_sub_f32_e32 v131, v131, v228
	v_mul_f32_e32 v227, 0x3fb8aa3b, v227
	v_mul_f32_e32 v250, 0x3fb8aa3b, v250
	v_mul_f32_e32 v131, 0x3fb8aa3b, v131
	v_exp_f32_e32 v227, v227
	v_exp_f32_e32 v250, v250
	v_exp_f32_e32 v131, v131
	v_mov_b32_e32 v217, v228
	v_fma_f32 v225, v225, v227, v250
	v_add_f32_e32 v225, v225, v131
	v_mul_f32_e32 v200, v200, v227
	v_mul_f32_e32 v201, v201, v227
	v_mul_f32_e32 v202, v202, v227
	v_mul_f32_e32 v203, v203, v227
	v_fmac_f32_e32 v200, v250, v88
	v_fmac_f32_e32 v201, v250, v89
	v_fmac_f32_e32 v202, v250, v90
	v_fmac_f32_e32 v203, v250, v91
	v_fmac_f32_e32 v200, v131, v120
	v_fmac_f32_e32 v201, v131, v121
	v_fmac_f32_e32 v202, v131, v122
	v_fmac_f32_e32 v203, v131, v123
	v_max3_f32 v228, v251, v132, v218
	v_sub_f32_e32 v227, v218, v228
	v_sub_f32_e32 v251, v251, v228
	v_sub_f32_e32 v132, v132, v228
	v_mul_f32_e32 v227, 0x3fb8aa3b, v227
	v_mul_f32_e32 v251, 0x3fb8aa3b, v251
	v_mul_f32_e32 v132, 0x3fb8aa3b, v132
	v_exp_f32_e32 v227, v227
	v_exp_f32_e32 v251, v251
	v_exp_f32_e32 v132, v132
	v_mov_b32_e32 v218, v228
	v_fma_f32 v226, v226, v227, v251
	v_add_f32_e32 v226, v226, v132
	v_mul_f32_e32 v204, v204, v227
	v_mul_f32_e32 v205, v205, v227
	v_mul_f32_e32 v206, v206, v227
	v_mul_f32_e32 v207, v207, v227
	v_fmac_f32_e32 v204, v251, v92
	v_fmac_f32_e32 v205, v251, v93
	v_fmac_f32_e32 v206, v251, v94
	v_fmac_f32_e32 v207, v251, v95
	v_fmac_f32_e32 v204, v132, v124
	v_fmac_f32_e32 v205, v132, v125
	v_fmac_f32_e32 v206, v132, v126
	v_fmac_f32_e32 v207, v132, v127
	s_cmp_lg_u32 s4, 0
	s_cbranch_scc1 .Lst4_noextra
	s_waitcnt vmcnt(0)
	s_sub_u32 s62, s62, s64
	s_subb_u32 s63, s63, 0
	s_add_u32 s42, s62, 0x1000
	s_addc_u32 s43, s63, 0
	global_load_dwordx4 v[0:3], v136, s[62:63] nt
	global_load_dwordx4 v[4:7], v136, s[62:63] offset:1024 nt
	global_load_dwordx4 v[8:11], v136, s[62:63] offset:2048 nt
	global_load_dwordx4 v[12:15], v136, s[62:63] offset:3072 nt
	global_load_dwordx4 v[16:19], v136, s[42:43] nt
	global_load_dwordx4 v[20:23], v136, s[42:43] offset:1024 nt
	global_load_dwordx4 v[24:27], v136, s[42:43] offset:2048 nt
	global_load_dwordx4 v[28:31], v136, s[42:43] offset:3072 nt
	s_waitcnt vmcnt(7)
	v_mul_f32_e32 v244, v138, v0
	v_fmac_f32_e32 v244, v139, v1
	v_fmac_f32_e32 v244, v140, v2
	v_fmac_f32_e32 v244, v141, v3
	s_waitcnt vmcnt(6)
	v_mul_f32_e32 v245, v142, v4
	v_fmac_f32_e32 v245, v143, v5
	v_fmac_f32_e32 v245, v144, v6
	v_fmac_f32_e32 v245, v145, v7
	s_waitcnt vmcnt(5)
	v_mul_f32_e32 v246, v146, v8
	v_fmac_f32_e32 v246, v147, v9
	v_fmac_f32_e32 v246, v148, v10
	v_fmac_f32_e32 v246, v149, v11
	v_add_f32_dpp v244, v244, v244 quad_perm:[1,0,3,2] row_mask:0xf bank_mask:0xf bound_ctrl:1
	v_add_f32_dpp v245, v245, v245 quad_perm:[1,0,3,2] row_mask:0xf bank_mask:0xf bound_ctrl:1
	v_add_f32_dpp v246, v246, v246 quad_perm:[1,0,3,2] row_mask:0xf bank_mask:0xf bound_ctrl:1
	v_add_f32_dpp v244, v244, v244 quad_perm:[2,3,0,1] row_mask:0xf bank_mask:0xf bound_ctrl:1
	v_add_f32_dpp v245, v245, v245 quad_perm:[2,3,0,1] row_mask:0xf bank_mask:0xf bound_ctrl:1
	v_add_f32_dpp v246, v246, v246 quad_perm:[2,3,0,1] row_mask:0xf bank_mask:0xf bound_ctrl:1
	v_add_f32_dpp v244, v244, v244 row_ror:4 row_mask:0xf bank_mask:0xf bound_ctrl:1
	v_add_f32_dpp v245, v245, v245 row_ror:4 row_mask:0xf bank_mask:0xf bound_ctrl:1
	v_add_f32_dpp v246, v246, v246 row_ror:4 row_mask:0xf bank_mask:0xf bound_ctrl:1
	v_add_f32_dpp v244, v244, v244 row_ror:8 row_mask:0xf bank_mask:0xf bound_ctrl:1
	v_add_f32_dpp v245, v245, v245 row_ror:8 row_mask:0xf bank_mask:0xf bound_ctrl:1
	v_add_f32_dpp v246, v246, v246 row_ror:8 row_mask:0xf bank_mask:0xf bound_ctrl:1
	v_mov_b32_e32 v133, v244
	v_mov_b32_e32 v134, v245
	v_mov_b32_e32 v135, v246
	v_permlane32_swap_b32_e32 v244, v133
	v_permlane32_swap_b32_e32 v245, v134
	v_permlane32_swap_b32_e32 v246, v135
	s_waitcnt vmcnt(4)
	v_mul_f32_e32 v247, v150, v12
	v_fmac_f32_e32 v247, v151, v13
	v_fmac_f32_e32 v247, v152, v14
	v_fmac_f32_e32 v247, v153, v15
	s_waitcnt vmcnt(3)
	v_mul_f32_e32 v248, v154, v16
	v_fmac_f32_e32 v248, v155, v17
	v_fmac_f32_e32 v248, v156, v18
	v_fmac_f32_e32 v248, v157, v19
	s_waitcnt vmcnt(2)
	v_mul_f32_e32 v249, v158, v20
	v_fmac_f32_e32 v249, v159, v21
	v_fmac_f32_e32 v249, v160, v22
	v_fmac_f32_e32 v249, v161, v23
	v_add_f32_dpp v247, v247, v247 quad_perm:[1,0,3,2] row_mask:0xf bank_mask:0xf bound_ctrl:1
	v_add_f32_dpp v248, v248, v248 quad_perm:[1,0,3,2] row_mask:0xf bank_mask:0xf bound_ctrl:1
	v_add_f32_dpp v249, v249, v249 quad_perm:[1,0,3,2] row_mask:0xf bank_mask:0xf bound_ctrl:1
	v_add_f32_dpp v247, v247, v247 quad_perm:[2,3,0,1] row_mask:0xf bank_mask:0xf bound_ctrl:1
	v_add_f32_dpp v248, v248, v248 quad_perm:[2,3,0,1] row_mask:0xf bank_mask:0xf bound_ctrl:1
	v_add_f32_dpp v249, v249, v249 quad_perm:[2,3,0,1] row_mask:0xf bank_mask:0xf bound_ctrl:1
	v_add_f32_dpp v247, v247, v247 row_ror:4 row_mask:0xf bank_mask:0xf bound_ctrl:1
	v_add_f32_dpp v248, v248, v248 row_ror:4 row_mask:0xf bank_mask:0xf bound_ctrl:1
	v_add_f32_dpp v249, v249, v249 row_ror:4 row_mask:0xf bank_mask:0xf bound_ctrl:1
	v_add_f32_dpp v247, v247, v247 row_ror:8 row_mask:0xf bank_mask:0xf bound_ctrl:1
	v_add_f32_dpp v248, v248, v248 row_ror:8 row_mask:0xf bank_mask:0xf bound_ctrl:1
	v_add_f32_dpp v249, v249, v249 row_ror:8 row_mask:0xf bank_mask:0xf bound_ctrl:1
	v_mov_b32_e32 v133, v247
	v_mov_b32_e32 v134, v248
	v_mov_b32_e32 v135, v249
	v_permlane32_swap_b32_e32 v247, v133
	v_permlane32_swap_b32_e32 v248, v134
	v_permlane32_swap_b32_e32 v249, v135
	s_waitcnt vmcnt(1)
	v_mul_f32_e32 v250, v162, v24
	v_fmac_f32_e32 v250, v163, v25
	v_fmac_f32_e32 v250, v164, v26
	v_fmac_f32_e32 v250, v165, v27
	s_waitcnt vmcnt(0)
	v_mul_f32_e32 v251, v166, v28
	v_fmac_f32_e32 v251, v167, v29
	v_fmac_f32_e32 v251, v168, v30
	v_fmac_f32_e32 v251, v169, v31
	s_nop 1
	v_add_f32_dpp v250, v250, v250 quad_perm:[1,0,3,2] row_mask:0xf bank_mask:0xf bound_ctrl:1
	v_add_f32_dpp v251, v251, v251 quad_perm:[1,0,3,2] row_mask:0xf bank_mask:0xf bound_ctrl:1
	s_nop 1
	v_add_f32_dpp v250, v250, v250 quad_perm:[2,3,0,1] row_mask:0xf bank_mask:0xf bound_ctrl:1
	v_add_f32_dpp v251, v251, v251 quad_perm:[2,3,0,1] row_mask:0xf bank_mask:0xf bound_ctrl:1
	s_nop 1
	v_add_f32_dpp v250, v250, v250 row_ror:4 row_mask:0xf bank_mask:0xf bound_ctrl:1
	v_add_f32_dpp v251, v251, v251 row_ror:4 row_mask:0xf bank_mask:0xf bound_ctrl:1
	s_nop 1
	v_add_f32_dpp v250, v250, v250 row_ror:8 row_mask:0xf bank_mask:0xf bound_ctrl:1
	v_add_f32_dpp v251, v251, v251 row_ror:8 row_mask:0xf bank_mask:0xf bound_ctrl:1
	s_nop 1
	v_mov_b32_e32 v133, v250
	v_mov_b32_e32 v134, v251
	s_nop 1
	v_permlane32_swap_b32_e32 v250, v133
	v_permlane32_swap_b32_e32 v251, v134
	v_max_f32_e32 v228, v244, v208
	v_sub_f32_e32 v227, v208, v228
	v_sub_f32_e32 v244, v244, v228
	v_mul_f32_e32 v227, 0x3fb8aa3b, v227
	v_mul_f32_e32 v244, 0x3fb8aa3b, v244
	v_exp_f32_e32 v227, v227
	v_exp_f32_e32 v244, v244
	v_mov_b32_e32 v208, v228
	v_fma_f32 v219, v219, v227, v244
	v_mul_f32_e32 v172, v172, v227
	v_mul_f32_e32 v173, v173, v227
	v_mul_f32_e32 v174, v174, v227
	v_mul_f32_e32 v175, v175, v227
	v_fmac_f32_e32 v172, v244, v0
	v_fmac_f32_e32 v173, v244, v1
	v_fmac_f32_e32 v174, v244, v2
	v_fmac_f32_e32 v175, v244, v3
	v_max_f32_e32 v228, v245, v209
	v_sub_f32_e32 v227, v209, v228
	v_sub_f32_e32 v245, v245, v228
	v_mul_f32_e32 v227, 0x3fb8aa3b, v227
	v_mul_f32_e32 v245, 0x3fb8aa3b, v245
	v_exp_f32_e32 v227, v227
	v_exp_f32_e32 v245, v245
	v_mov_b32_e32 v209, v228
	v_fma_f32 v220, v220, v227, v245
	v_mul_f32_e32 v176, v176, v227
	v_mul_f32_e32 v177, v177, v227
	v_mul_f32_e32 v178, v178, v227
	v_mul_f32_e32 v179, v179, v227
	v_fmac_f32_e32 v176, v245, v4
	v_fmac_f32_e32 v177, v245, v5
	v_fmac_f32_e32 v178, v245, v6
	v_fmac_f32_e32 v179, v245, v7
	v_max_f32_e32 v228, v246, v210
	v_sub_f32_e32 v227, v210, v228
	v_sub_f32_e32 v246, v246, v228
	v_mul_f32_e32 v227, 0x3fb8aa3b, v227
	v_mul_f32_e32 v246, 0x3fb8aa3b, v246
	v_exp_f32_e32 v227, v227
	v_exp_f32_e32 v246, v246
	v_mov_b32_e32 v210, v228
	v_fma_f32 v221, v221, v227, v246
	v_mul_f32_e32 v180, v180, v227
	v_mul_f32_e32 v181, v181, v227
	v_mul_f32_e32 v182, v182, v227
	v_mul_f32_e32 v183, v183, v227
	v_fmac_f32_e32 v180, v246, v8
	v_fmac_f32_e32 v181, v246, v9
	v_fmac_f32_e32 v182, v246, v10
	v_fmac_f32_e32 v183, v246, v11
	v_max_f32_e32 v228, v247, v212
	v_sub_f32_e32 v227, v212, v228
	v_sub_f32_e32 v247, v247, v228
	v_mul_f32_e32 v227, 0x3fb8aa3b, v227
	v_mul_f32_e32 v247, 0x3fb8aa3b, v247
	v_exp_f32_e32 v227, v227
	v_exp_f32_e32 v247, v247
	v_mov_b32_e32 v212, v228
	v_fma_f32 v222, v222, v227, v247
	v_mul_f32_e32 v184, v184, v227
	v_mul_f32_e32 v185, v185, v227
	v_mul_f32_e32 v186, v186, v227
	v_mul_f32_e32 v187, v187, v227
	v_fmac_f32_e32 v184, v247, v12
	v_fmac_f32_e32 v185, v247, v13
	v_fmac_f32_e32 v186, v247, v14
	v_fmac_f32_e32 v187, v247, v15
	v_max_f32_e32 v228, v248, v214
	v_sub_f32_e32 v227, v214, v228
	v_sub_f32_e32 v248, v248, v228
	v_mul_f32_e32 v227, 0x3fb8aa3b, v227
	v_mul_f32_e32 v248, 0x3fb8aa3b, v248
	v_exp_f32_e32 v227, v227
	v_exp_f32_e32 v248, v248
	v_mov_b32_e32 v214, v228
	v_fma_f32 v223, v223, v227, v248
	v_mul_f32_e32 v188, v188, v227
	v_mul_f32_e32 v189, v189, v227
	v_mul_f32_e32 v190, v190, v227
	v_mul_f32_e32 v191, v191, v227
	v_fmac_f32_e32 v188, v248, v16
	v_fmac_f32_e32 v189, v248, v17
	v_fmac_f32_e32 v190, v248, v18
	v_fmac_f32_e32 v191, v248, v19
	v_max_f32_e32 v228, v249, v216
	v_sub_f32_e32 v227, v216, v228
	v_sub_f32_e32 v249, v249, v228
	v_mul_f32_e32 v227, 0x3fb8aa3b, v227
	v_mul_f32_e32 v249, 0x3fb8aa3b, v249
	v_exp_f32_e32 v227, v227
	v_exp_f32_e32 v249, v249
	v_mov_b32_e32 v216, v228
	v_fma_f32 v224, v224, v227, v249
	v_mul_f32_e32 v196, v196, v227
	v_mul_f32_e32 v197, v197, v227
	v_mul_f32_e32 v198, v198, v227
	v_mul_f32_e32 v199, v199, v227
	v_fmac_f32_e32 v196, v249, v20
	v_fmac_f32_e32 v197, v249, v21
	v_fmac_f32_e32 v198, v249, v22
	v_fmac_f32_e32 v199, v249, v23
	v_max_f32_e32 v228, v250, v217
	v_sub_f32_e32 v227, v217, v228
	v_sub_f32_e32 v250, v250, v228
	v_mul_f32_e32 v227, 0x3fb8aa3b, v227
	v_mul_f32_e32 v250, 0x3fb8aa3b, v250
	v_exp_f32_e32 v227, v227
	v_exp_f32_e32 v250, v250
	v_mov_b32_e32 v217, v228
	v_fma_f32 v225, v225, v227, v250
	v_mul_f32_e32 v200, v200, v227
	v_mul_f32_e32 v201, v201, v227
	v_mul_f32_e32 v202, v202, v227
	v_mul_f32_e32 v203, v203, v227
	v_fmac_f32_e32 v200, v250, v24
	v_fmac_f32_e32 v201, v250, v25
	v_fmac_f32_e32 v202, v250, v26
	v_fmac_f32_e32 v203, v250, v27
	v_max_f32_e32 v228, v251, v218
	v_sub_f32_e32 v227, v218, v228
	v_sub_f32_e32 v251, v251, v228
	v_mul_f32_e32 v227, 0x3fb8aa3b, v227
	v_mul_f32_e32 v251, 0x3fb8aa3b, v251
	v_exp_f32_e32 v227, v227
	v_exp_f32_e32 v251, v251
	v_mov_b32_e32 v218, v228
	v_fma_f32 v226, v226, v227, v251
	v_mul_f32_e32 v204, v204, v227
	v_mul_f32_e32 v205, v205, v227
	v_mul_f32_e32 v206, v206, v227
	v_mul_f32_e32 v207, v207, v227
	v_fmac_f32_e32 v204, v251, v28
	v_fmac_f32_e32 v205, v251, v29
	v_fmac_f32_e32 v206, v251, v30
	v_fmac_f32_e32 v207, v251, v31
.Lst4_noextra:
	s_waitcnt vmcnt(0) lgkmcnt(0)
	s_barrier
	v_subrev_u32_e32 v229, 0x200, v136
	s_lshl_b32 s28, s4, 9
	v_add_u32_e32 v229, s28, v229
	v_add_u32_e32 v229, 16, v229
	v_lshrrev_b32_e32 v230, 5, v136
	v_and_b32_e32 v230, 8, v230
	s_lshl_b32 s28, s4, 4
	v_add_u32_e32 v230, s28, v230
	v_add_u32_e32 v230, 0x8010, v230
	s_mov_b64 s[40:41], exec
	s_mov_b32 exec_lo, 0
	s_mov_b32 exec_hi, -1
	ds_write_b128 v229, v[172:175] offset:0
	ds_write_b128 v229, v[176:179] offset:4096
	ds_write_b128 v229, v[180:183] offset:8192
	ds_write_b128 v229, v[184:187] offset:12288
	ds_write_b128 v229, v[188:191] offset:16384
	ds_write_b128 v229, v[196:199] offset:20480
	ds_write_b128 v229, v[200:203] offset:24576
	ds_write_b128 v229, v[204:207] offset:28672
	s_mov_b32 exec_hi, 0x10001
	v_mov_b32_e32 v228, v208
	v_mov_b32_e32 v229, v219
	ds_write_b64 v230, v[228:229] offset:0
	v_mov_b32_e32 v228, v209
	v_mov_b32_e32 v229, v220
	ds_write_b64 v230, v[228:229] offset:128
	v_mov_b32_e32 v228, v210
	v_mov_b32_e32 v229, v221
	ds_write_b64 v230, v[228:229] offset:256
	v_mov_b32_e32 v228, v212
	v_mov_b32_e32 v229, v222
	ds_write_b64 v230, v[228:229] offset:384
	v_mov_b32_e32 v228, v214
	v_mov_b32_e32 v229, v223
	ds_write_b64 v230, v[228:229] offset:512
	v_mov_b32_e32 v228, v216
	v_mov_b32_e32 v229, v224
	ds_write_b64 v230, v[228:229] offset:640
	v_mov_b32_e32 v228, v217
	v_mov_b32_e32 v229, v225
	ds_write_b64 v230, v[228:229] offset:768
	v_mov_b32_e32 v228, v218
	v_mov_b32_e32 v229, v226
	ds_write_b64 v230, v[228:229] offset:896
	s_mov_b64 exec, s[40:41]
	s_waitcnt lgkmcnt(0)
	s_barrier
	s_mov_b32 exec_lo, 0
	s_mov_b32 exec_hi, -1
	v_subrev_u32_e32 v229, 0x200, v136
	s_lshl_b32 s28, s4, 12
	v_add_u32_e32 v229, s28, v229
	v_add_u32_e32 v229, 16, v229
	v_lshrrev_b32_e32 v230, 5, v136
	v_and_b32_e32 v230, 8, v230
	s_lshl_b32 s28, s4, 7
	v_add_u32_e32 v230, s28, v230
	v_add_u32_e32 v230, 0x8010, v230
	ds_read_b64 v[0:1], v230 offset:0
	ds_read_b64 v[2:3], v230 offset:16
	ds_read_b64 v[4:5], v230 offset:32
	ds_read_b64 v[6:7], v230 offset:48
	ds_read_b64 v[8:9], v230 offset:64
	ds_read_b64 v[10:11], v230 offset:80
	ds_read_b64 v[12:13], v230 offset:96
	ds_read_b64 v[14:15], v230 offset:112
	ds_read_b128 v[16:19], v229 offset:0
	ds_read_b128 v[20:23], v229 offset:512
	ds_read_b128 v[24:27], v229 offset:1024
	ds_read_b128 v[28:31], v229 offset:1536
	ds_read_b128 v[32:35], v229 offset:2048
	ds_read_b128 v[36:39], v229 offset:2560
	ds_read_b128 v[40:43], v229 offset:3072
	ds_read_b128 v[44:47], v229 offset:3584
	s_waitcnt lgkmcnt(0)
	v_max3_f32 v228, v0, v2, v4
	v_max3_f32 v228, v228, v6, v8
	v_max3_f32 v228, v228, v10, v12
	v_max_f32_e32 v228, v228, v14
	v_sub_f32_e32 v0, v0, v228
	v_sub_f32_e32 v2, v2, v228
	v_sub_f32_e32 v4, v4, v228
	v_sub_f32_e32 v6, v6, v228
	v_sub_f32_e32 v8, v8, v228
	v_sub_f32_e32 v10, v10, v228
	v_sub_f32_e32 v12, v12, v228
	v_sub_f32_e32 v14, v14, v228
	v_mul_f32_e32 v0, 0x3fb8aa3b, v0
	v_mul_f32_e32 v2, 0x3fb8aa3b, v2
	v_mul_f32_e32 v4, 0x3fb8aa3b, v4
	v_mul_f32_e32 v6, 0x3fb8aa3b, v6
	v_mul_f32_e32 v8, 0x3fb8aa3b, v8
	v_mul_f32_e32 v10, 0x3fb8aa3b, v10
	v_mul_f32_e32 v12, 0x3fb8aa3b, v12
	v_mul_f32_e32 v14, 0x3fb8aa3b, v14
	v_exp_f32_e32 v0, v0
	v_exp_f32_e32 v2, v2
	v_exp_f32_e32 v4, v4
	v_exp_f32_e32 v6, v6
	v_exp_f32_e32 v8, v8
	v_exp_f32_e32 v10, v10
	v_exp_f32_e32 v12, v12
	v_exp_f32_e32 v14, v14
	s_nop 0
	v_mul_f32_e32 v231, v1, v0
	v_fmac_f32_e32 v231, v3, v2
	v_fmac_f32_e32 v231, v5, v4
	v_fmac_f32_e32 v231, v7, v6
	v_fmac_f32_e32 v231, v9, v8
	v_fmac_f32_e32 v231, v11, v10
	v_fmac_f32_e32 v231, v13, v12
	v_fmac_f32_e32 v231, v15, v14
	v_mul_f32_e32 v48, v16, v0
	v_mul_f32_e32 v49, v17, v0
	v_mul_f32_e32 v50, v18, v0
	v_mul_f32_e32 v51, v19, v0
	v_fmac_f32_e32 v48, v20, v2
	v_fmac_f32_e32 v49, v21, v2
	v_fmac_f32_e32 v50, v22, v2
	v_fmac_f32_e32 v51, v23, v2
	v_fmac_f32_e32 v48, v24, v4
	v_fmac_f32_e32 v49, v25, v4
	v_fmac_f32_e32 v50, v26, v4
	v_fmac_f32_e32 v51, v27, v4
	v_fmac_f32_e32 v48, v28, v6
	v_fmac_f32_e32 v49, v29, v6
	v_fmac_f32_e32 v50, v30, v6
	v_fmac_f32_e32 v51, v31, v6
	v_fmac_f32_e32 v48, v32, v8
	v_fmac_f32_e32 v49, v33, v8
	v_fmac_f32_e32 v50, v34, v8
	v_fmac_f32_e32 v51, v35, v8
	v_fmac_f32_e32 v48, v36, v10
	v_fmac_f32_e32 v49, v37, v10
	v_fmac_f32_e32 v50, v38, v10
	v_fmac_f32_e32 v51, v39, v10
	v_fmac_f32_e32 v48, v40, v12
	v_fmac_f32_e32 v49, v41, v12
	v_fmac_f32_e32 v50, v42, v12
	v_fmac_f32_e32 v51, v43, v12
	v_fmac_f32_e32 v48, v44, v14
	v_fmac_f32_e32 v49, v45, v14
	v_fmac_f32_e32 v50, v46, v14
	v_fmac_f32_e32 v51, v47, v14
	v_rcp_f32_e32 v227, v231
	s_nop 0
	v_fma_f32 v52, -v231, v227, 2.0
	v_mul_f32_e32 v227, v227, v52
	v_mul_f32_e32 v48, v48, v227
	v_mul_f32_e32 v49, v49, v227
	v_mul_f32_e32 v50, v50, v227
	v_mul_f32_e32 v51, v51, v227
	v_cvt_pk_bf16_f32 v54, v48, v49
	v_cvt_pk_bf16_f32 v55, v50, v51
	v_subrev_u32_e32 v229, 0x200, v136
	v_lshrrev_b32_e32 v229, 1, v229
	v_log_f32_e32 v227, v231
	v_lshrrev_b32_e32 v230, 5, v229
	v_mul_f32_e32 v227, 0x3f317218, v227
	v_add_f32_e32 v227, v227, v228
	global_store_dwordx2 v229, v[54:55], s[14:15]
	s_mov_b32 exec_hi, 0x10001
	s_nop 0
	global_store_dword v230, v227, s[22:23]
	s_mov_b64 exec, s[40:41]
.Lst4_done:
	s_mov_b64 s[0:1], 0
	s_branch .LBB0_768
.LBB0_767:
	s_or_b64 exec, exec, s[4:5]
	s_mov_b64 s[0:1], 0

	.amdhsa_kernel _Z10fwd_kernel6Params
		.amdhsa_group_segment_fixed_size 16
		.amdhsa_private_segment_fixed_size 0
		.amdhsa_kernarg_size 448
		.amdhsa_user_sgpr_count 2
		.amdhsa_user_sgpr_dispatch_ptr 0
		.amdhsa_user_sgpr_queue_ptr 0
		.amdhsa_user_sgpr_kernarg_segment_ptr 1
		.amdhsa_user_sgpr_dispatch_id 0
		.amdhsa_user_sgpr_kernarg_preload_length 0
		.amdhsa_user_sgpr_kernarg_preload_offset 0
		.amdhsa_user_sgpr_private_segment_size 0
		.amdhsa_uses_dynamic_stack 0
		.amdhsa_enable_private_segment 0
		.amdhsa_system_sgpr_workgroup_id_x 1
		.amdhsa_system_sgpr_workgroup_id_y 0
		.amdhsa_system_sgpr_workgroup_id_z 0
		.amdhsa_system_sgpr_workgroup_info 0
		.amdhsa_system_vgpr_workitem_id 2
		.amdhsa_next_free_vgpr 256
		.amdhsa_next_free_sgpr 102
		.amdhsa_accum_offset 256
		.amdhsa_reserve_vcc 1
		.amdhsa_float_round_mode_32 0
		.amdhsa_float_round_mode_16_64 0
		.amdhsa_float_denorm_mode_32 3
		.amdhsa_float_denorm_mode_16_64 3
		.amdhsa_dx10_clamp 1
		.amdhsa_ieee_mode 1
		.amdhsa_fp16_overflow 0
		.amdhsa_tg_split 0
		.amdhsa_exception_fp_ieee_invalid_op 0
		.amdhsa_exception_fp_denorm_src 0
		.amdhsa_exception_fp_ieee_div_zero 0
		.amdhsa_exception_fp_ieee_overflow 0
		.amdhsa_exception_fp_ieee_underflow 0
		.amdhsa_exception_fp_ieee_inexact 0
		.amdhsa_exception_int_div_zero 0
	.end_amdhsa_kernel

amdhsa.kernels:
  - .agpr_count:     0
    .args:
      - .offset:         0
        .size:           192
        .value_kind:     by_value
      - .offset:         192
        .size:           4
        .value_kind:     hidden_block_count_x
      - .offset:         196
        .size:           4
        .value_kind:     hidden_block_count_y
      - .offset:         200
        .size:           4
        .value_kind:     hidden_block_count_z
      - .offset:         204
        .size:           2
        .value_kind:     hidden_group_size_x
      - .offset:         206
        .size:           2
        .value_kind:     hidden_group_size_y
      - .offset:         208
        .size:           2
        .value_kind:     hidden_group_size_z
      - .offset:         210
        .size:           2
        .value_kind:     hidden_remainder_x
      - .offset:         212
        .size:           2
        .value_kind:     hidden_remainder_y
      - .offset:         214
        .size:           2
        .value_kind:     hidden_remainder_z
      - .offset:         232
        .size:           8
        .value_kind:     hidden_global_offset_x
      - .offset:         240
        .size:           8
        .value_kind:     hidden_global_offset_y
      - .offset:         248
        .size:           8
        .value_kind:     hidden_global_offset_z
      - .offset:         256
        .size:           2
        .value_kind:     hidden_grid_dims
      - .offset:         280
        .size:           8
        .value_kind:     hidden_multigrid_sync_arg
      - .offset:         312
        .size:           4
        .value_kind:     hidden_dynamic_lds_size
    .group_segment_fixed_size: 16
    .kernarg_segment_align: 8
    .kernarg_segment_size: 448
    .language:       OpenCL C
    .language_version:
      - 2
      - 0
    .max_flat_workgroup_size: 512
    .name:           _Z10fwd_kernel6Params
    .private_segment_fixed_size: 0
    .sgpr_count:     108
    .sgpr_spill_count: 81
    .symbol:         _Z10fwd_kernel6Params.kd
    .uniform_work_group_size: 1
    .uses_dynamic_stack: false
    .vgpr_count:     256
    .vgpr_spill_count: 0
    .wavefront_size: 64
